# GEMM K-loops: priority raised before the pre-MFMA barrier, redundant lgkmcnt(0) dropped, post-MFMA barrier signalled before lowering priority
# speedup vs baseline: 1.0082x; 1.0082x over previous
.LBB0_122:
	ds_read_b128 v[152:155], v148
	ds_read_b128 v[156:159], v148 offset:1024
	ds_read_b128 v[160:163], v148 offset:2048
	ds_read_b128 v[164:167], v148 offset:3072
	ds_read_b128 v[168:171], v149
	ds_read_b128 v[172:175], v149 offset:1024
	ds_read_b128 v[176:179], v149 offset:2048
	ds_read_b128 v[180:183], v149 offset:3072
	s_add_u32 s44, s36, 0xfff80080
	s_addc_u32 s45, s37, -1
	s_cmp_eq_u32 s54, 28
	s_cselect_b32 s53, s25, s45
	s_cselect_b32 s52, s48, s44
	s_cselect_b32 s45, s23, s51
	s_cselect_b32 s44, s49, s50
	v_lshl_add_u64 v[216:217], s[36:37], 0, v[140:141]
	s_add_i32 m0, s18, 0xc000
	ds_read_b128 v[184:187], v150
	ds_read_b128 v[188:191], v150 offset:1024
	ds_read_b128 v[192:195], v150 offset:2048
	ds_read_b128 v[196:199], v150 offset:3072
	ds_read_b128 v[200:203], v150 offset:4096
	ds_read_b128 v[204:207], v150 offset:5120
	ds_read_b128 v[208:211], v150 offset:6144
	ds_read_b128 v[212:215], v150 offset:7168
	global_load_lds_dwordx4 v[216:217], off
	v_lshl_add_u64 v[216:217], s[36:37], 0, v[138:139]
	s_add_i32 m0, s18, 0xe000
	s_nop 0
	global_load_lds_dwordx4 v[216:217], off
	s_waitcnt vmcnt(8)
	s_waitcnt lgkmcnt(0)
	s_setprio 1
	s_barrier
	v_mfma_f32_16x16x32_bf16 v[126:129], v[152:155], v[184:187], v[126:129]
	v_mfma_f32_16x16x32_bf16 v[122:125], v[160:163], v[184:187], v[122:125]
	v_mfma_f32_16x16x32_bf16 v[110:113], v[152:155], v[192:195], v[110:113]
	v_mfma_f32_16x16x32_bf16 v[106:109], v[160:163], v[192:195], v[106:109]
	v_mfma_f32_16x16x32_bf16 v[94:97], v[152:155], v[200:203], v[94:97]
	v_mfma_f32_16x16x32_bf16 v[90:93], v[160:163], v[200:203], v[90:93]
	v_mfma_f32_16x16x32_bf16 v[78:81], v[152:155], v[208:211], v[78:81]
	v_mfma_f32_16x16x32_bf16 v[74:77], v[160:163], v[208:211], v[74:77]
	v_mfma_f32_16x16x32_bf16 v[126:129], v[156:159], v[188:191], v[126:129]
	v_mfma_f32_16x16x32_bf16 v[122:125], v[164:167], v[188:191], v[122:125]
	v_mfma_f32_16x16x32_bf16 v[110:113], v[156:159], v[196:199], v[110:113]
	v_mfma_f32_16x16x32_bf16 v[106:109], v[164:167], v[196:199], v[106:109]
	v_mfma_f32_16x16x32_bf16 v[94:97], v[156:159], v[204:207], v[94:97]
	v_mfma_f32_16x16x32_bf16 v[90:93], v[164:167], v[204:207], v[90:93]
	v_mfma_f32_16x16x32_bf16 v[78:81], v[156:159], v[212:215], v[78:81]
	v_mfma_f32_16x16x32_bf16 v[74:77], v[164:167], v[212:215], v[74:77]
	s_setprio 0
	s_setprio 1
	v_mfma_f32_16x16x32_bf16 v[118:121], v[168:171], v[184:187], v[118:121]
	v_mfma_f32_16x16x32_bf16 v[114:117], v[176:179], v[184:187], v[114:117]
	v_mfma_f32_16x16x32_bf16 v[102:105], v[168:171], v[192:195], v[102:105]
	v_mfma_f32_16x16x32_bf16 v[98:101], v[176:179], v[192:195], v[98:101]
	v_mfma_f32_16x16x32_bf16 v[86:89], v[168:171], v[200:203], v[86:89]
	v_mfma_f32_16x16x32_bf16 v[82:85], v[176:179], v[200:203], v[82:85]
	v_mfma_f32_16x16x32_bf16 v[70:73], v[168:171], v[208:211], v[70:73]
	v_mfma_f32_16x16x32_bf16 v[66:69], v[176:179], v[208:211], v[66:69]
	v_mfma_f32_16x16x32_bf16 v[118:121], v[172:175], v[188:191], v[118:121]
	v_mfma_f32_16x16x32_bf16 v[114:117], v[180:183], v[188:191], v[114:117]
	v_mfma_f32_16x16x32_bf16 v[102:105], v[172:175], v[196:199], v[102:105]
	v_mfma_f32_16x16x32_bf16 v[98:101], v[180:183], v[196:199], v[98:101]
	v_mfma_f32_16x16x32_bf16 v[86:89], v[172:175], v[204:207], v[86:89]
	v_mfma_f32_16x16x32_bf16 v[82:85], v[180:183], v[204:207], v[82:85]
	v_mfma_f32_16x16x32_bf16 v[70:73], v[172:175], v[212:215], v[70:73]
	v_mfma_f32_16x16x32_bf16 v[66:69], v[180:183], v[212:215], v[66:69]
	s_barrier
	s_setprio 0
	s_add_i32 s55, s42, s13
	v_lshl_add_u64 v[216:217], s[44:45], 0, v[134:135]
	s_mov_b32 m0, s55
	ds_read_b128 v[184:187], v150 offset:16384
	ds_read_b128 v[188:191], v150 offset:17408
	ds_read_b128 v[192:195], v150 offset:18432
	ds_read_b128 v[196:199], v150 offset:19456
	ds_read_b128 v[200:203], v150 offset:20480
	ds_read_b128 v[204:207], v150 offset:21504
	ds_read_b128 v[208:211], v150 offset:22528
	ds_read_b128 v[212:215], v150 offset:23552
	global_load_lds_dwordx4 v[216:217], off
	s_add_i32 m0, s55, 0x2000
	s_add_u32 s68, s44, 0x80000
	v_lshl_add_u64 v[218:219], s[44:45], 0, v[130:131]
	s_addc_u32 s69, s45, 0
	s_add_i32 s55, s43, s13
	global_load_lds_dwordx4 v[218:219], off
	v_lshl_add_u64 v[220:221], s[68:69], 0, v[134:135]
	s_mov_b32 m0, s55
	v_lshl_add_u64 v[222:223], s[52:53], 0, v[132:133]
	global_load_lds_dwordx4 v[220:221], off
	v_lshl_add_u64 v[220:221], s[68:69], 0, v[130:131]
	s_add_i32 m0, s55, 0x2000
	s_nop 0
	global_load_lds_dwordx4 v[220:221], off
	v_lshl_add_u64 v[220:221], s[52:53], 0, v[136:137]
	s_mov_b32 m0, s18
	s_nop 0
	global_load_lds_dwordx4 v[220:221], off
	s_mov_b32 m0, s19
	s_nop 0
	global_load_lds_dwordx4 v[222:223], off
	s_waitcnt vmcnt(8)
	s_waitcnt lgkmcnt(0)
	s_setprio 1
	s_barrier
	v_mfma_f32_16x16x32_bf16 v[62:65], v[152:155], v[184:187], v[62:65]
	v_mfma_f32_16x16x32_bf16 v[58:61], v[160:163], v[184:187], v[58:61]
	v_mfma_f32_16x16x32_bf16 v[46:49], v[152:155], v[192:195], v[46:49]
	v_mfma_f32_16x16x32_bf16 v[42:45], v[160:163], v[192:195], v[42:45]
	v_mfma_f32_16x16x32_bf16 v[30:33], v[152:155], v[200:203], v[30:33]
	v_mfma_f32_16x16x32_bf16 v[26:29], v[160:163], v[200:203], v[26:29]
	v_mfma_f32_16x16x32_bf16 v[14:17], v[152:155], v[208:211], v[14:17]
	v_mfma_f32_16x16x32_bf16 v[10:13], v[160:163], v[208:211], v[10:13]
	v_mfma_f32_16x16x32_bf16 v[62:65], v[156:159], v[188:191], v[62:65]
	v_mfma_f32_16x16x32_bf16 v[58:61], v[164:167], v[188:191], v[58:61]
	v_mfma_f32_16x16x32_bf16 v[46:49], v[156:159], v[196:199], v[46:49]
	v_mfma_f32_16x16x32_bf16 v[42:45], v[164:167], v[196:199], v[42:45]
	v_mfma_f32_16x16x32_bf16 v[30:33], v[156:159], v[204:207], v[30:33]
	v_mfma_f32_16x16x32_bf16 v[26:29], v[164:167], v[204:207], v[26:29]
	v_mfma_f32_16x16x32_bf16 v[14:17], v[156:159], v[212:215], v[14:17]
	v_mfma_f32_16x16x32_bf16 v[10:13], v[164:167], v[212:215], v[10:13]
	s_setprio 0
	s_setprio 1
	v_mfma_f32_16x16x32_bf16 v[54:57], v[168:171], v[184:187], v[54:57]
	v_mfma_f32_16x16x32_bf16 v[50:53], v[176:179], v[184:187], v[50:53]
	v_mfma_f32_16x16x32_bf16 v[38:41], v[168:171], v[192:195], v[38:41]
	v_mfma_f32_16x16x32_bf16 v[34:37], v[176:179], v[192:195], v[34:37]
	v_mfma_f32_16x16x32_bf16 v[22:25], v[168:171], v[200:203], v[22:25]
	v_mfma_f32_16x16x32_bf16 v[18:21], v[176:179], v[200:203], v[18:21]
	v_mfma_f32_16x16x32_bf16 v[6:9], v[168:171], v[208:211], v[6:9]
	v_mfma_f32_16x16x32_bf16 v[2:5], v[176:179], v[208:211], v[2:5]
	v_mfma_f32_16x16x32_bf16 v[54:57], v[172:175], v[188:191], v[54:57]
	v_mfma_f32_16x16x32_bf16 v[50:53], v[180:183], v[188:191], v[50:53]
	v_mfma_f32_16x16x32_bf16 v[38:41], v[172:175], v[196:199], v[38:41]
	v_mfma_f32_16x16x32_bf16 v[34:37], v[180:183], v[196:199], v[34:37]
	v_mfma_f32_16x16x32_bf16 v[22:25], v[172:175], v[204:207], v[22:25]
	v_mfma_f32_16x16x32_bf16 v[18:21], v[180:183], v[204:207], v[18:21]
	v_mfma_f32_16x16x32_bf16 v[6:9], v[172:175], v[212:215], v[6:9]
	v_mfma_f32_16x16x32_bf16 v[2:5], v[180:183], v[212:215], v[2:5]
	s_barrier
	s_setprio 0
	s_add_i32 s55, 0, 0x18000
	v_add_u32_e32 v151, s55, v147
	s_add_i32 s68, 0, 0x1c000
	ds_read_b128 v[152:155], v151
	ds_read_b128 v[156:159], v151 offset:1024
	ds_read_b128 v[160:163], v151 offset:2048
	ds_read_b128 v[164:167], v151 offset:3072
	v_add_u32_e32 v151, s68, v147
	ds_read_b128 v[168:171], v151
	ds_read_b128 v[172:175], v151 offset:1024
	ds_read_b128 v[176:179], v151 offset:2048
	ds_read_b128 v[180:183], v151 offset:3072
	s_add_u32 s52, s52, 0x80000
	s_addc_u32 s53, s53, 0
	s_mov_b32 m0, s31
	v_lshl_add_u64 v[224:225], s[52:53], 0, v[136:137]
	ds_read_b128 v[184:187], v150 offset:32768
	ds_read_b128 v[188:191], v150 offset:33792
	ds_read_b128 v[192:195], v150 offset:34816
	ds_read_b128 v[196:199], v150 offset:35840
	ds_read_b128 v[200:203], v150 offset:36864
	ds_read_b128 v[204:207], v150 offset:37888
	ds_read_b128 v[208:211], v150 offset:38912
	ds_read_b128 v[212:215], v150 offset:39936
	global_load_lds_dwordx4 v[224:225], off
	v_lshl_add_u64 v[224:225], s[52:53], 0, v[132:133]
	s_mov_b32 m0, s33
	s_nop 0
	global_load_lds_dwordx4 v[224:225], off
	s_waitcnt vmcnt(8)
	s_waitcnt lgkmcnt(0)
	s_setprio 1
	s_barrier
	v_mfma_f32_16x16x32_bf16 v[126:129], v[152:155], v[184:187], v[126:129]
	v_mfma_f32_16x16x32_bf16 v[122:125], v[160:163], v[184:187], v[122:125]
	v_mfma_f32_16x16x32_bf16 v[110:113], v[152:155], v[192:195], v[110:113]
	v_mfma_f32_16x16x32_bf16 v[106:109], v[160:163], v[192:195], v[106:109]
	v_mfma_f32_16x16x32_bf16 v[94:97], v[152:155], v[200:203], v[94:97]
	v_mfma_f32_16x16x32_bf16 v[90:93], v[160:163], v[200:203], v[90:93]
	v_mfma_f32_16x16x32_bf16 v[78:81], v[152:155], v[208:211], v[78:81]
	v_mfma_f32_16x16x32_bf16 v[74:77], v[160:163], v[208:211], v[74:77]
	v_mfma_f32_16x16x32_bf16 v[126:129], v[156:159], v[188:191], v[126:129]
	v_mfma_f32_16x16x32_bf16 v[122:125], v[164:167], v[188:191], v[122:125]
	v_mfma_f32_16x16x32_bf16 v[110:113], v[156:159], v[196:199], v[110:113]
	v_mfma_f32_16x16x32_bf16 v[106:109], v[164:167], v[196:199], v[106:109]
	v_mfma_f32_16x16x32_bf16 v[94:97], v[156:159], v[204:207], v[94:97]
	v_mfma_f32_16x16x32_bf16 v[90:93], v[164:167], v[204:207], v[90:93]
	v_mfma_f32_16x16x32_bf16 v[78:81], v[156:159], v[212:215], v[78:81]
	v_mfma_f32_16x16x32_bf16 v[74:77], v[164:167], v[212:215], v[74:77]
	s_setprio 0
	s_setprio 1
	v_mfma_f32_16x16x32_bf16 v[118:121], v[168:171], v[184:187], v[118:121]
	v_mfma_f32_16x16x32_bf16 v[114:117], v[176:179], v[184:187], v[114:117]
	v_mfma_f32_16x16x32_bf16 v[102:105], v[168:171], v[192:195], v[102:105]
	v_mfma_f32_16x16x32_bf16 v[98:101], v[176:179], v[192:195], v[98:101]
	v_mfma_f32_16x16x32_bf16 v[86:89], v[168:171], v[200:203], v[86:89]
	v_mfma_f32_16x16x32_bf16 v[82:85], v[176:179], v[200:203], v[82:85]
	v_mfma_f32_16x16x32_bf16 v[70:73], v[168:171], v[208:211], v[70:73]
	v_mfma_f32_16x16x32_bf16 v[66:69], v[176:179], v[208:211], v[66:69]
	v_mfma_f32_16x16x32_bf16 v[118:121], v[172:175], v[188:191], v[118:121]
	v_mfma_f32_16x16x32_bf16 v[114:117], v[180:183], v[188:191], v[114:117]
	v_mfma_f32_16x16x32_bf16 v[102:105], v[172:175], v[196:199], v[102:105]
	v_mfma_f32_16x16x32_bf16 v[98:101], v[180:183], v[196:199], v[98:101]
	v_mfma_f32_16x16x32_bf16 v[86:89], v[172:175], v[204:207], v[86:89]
	v_mfma_f32_16x16x32_bf16 v[82:85], v[180:183], v[204:207], v[82:85]
	v_mfma_f32_16x16x32_bf16 v[70:73], v[172:175], v[212:215], v[70:73]
	v_mfma_f32_16x16x32_bf16 v[66:69], v[180:183], v[212:215], v[66:69]
	s_barrier
	s_setprio 0
	s_add_i32 s52, s55, s13
	v_lshl_add_u64 v[216:217], v[216:217], 0, s[16:17]
	s_mov_b32 m0, s52
	ds_read_b128 v[184:187], v150 offset:49152
	ds_read_b128 v[188:191], v150 offset:50176
	ds_read_b128 v[192:195], v150 offset:51200
	ds_read_b128 v[196:199], v150 offset:52224
	ds_read_b128 v[200:203], v150 offset:53248
	ds_read_b128 v[204:207], v150 offset:54272
	ds_read_b128 v[208:211], v150 offset:55296
	ds_read_b128 v[212:215], v150 offset:56320
	global_load_lds_dwordx4 v[216:217], off
	s_add_i32 m0, s52, 0x2000
	s_add_u32 s44, s44, 0x80080
	v_lshl_add_u64 v[216:217], v[218:219], 0, s[16:17]
	s_addc_u32 s45, s45, 0
	s_add_i32 s52, s68, s13
	global_load_lds_dwordx4 v[216:217], off
	v_lshl_add_u64 v[216:217], s[44:45], 0, v[134:135]
	s_mov_b32 m0, s52
	s_nop 0
	global_load_lds_dwordx4 v[216:217], off
	v_lshl_add_u64 v[216:217], s[44:45], 0, v[130:131]
	s_add_i32 m0, s52, 0x2000
	s_nop 0
	global_load_lds_dwordx4 v[216:217], off
	v_lshl_add_u64 v[216:217], v[220:221], 0, s[16:17]
	s_mov_b32 m0, s38
	s_nop 0
	global_load_lds_dwordx4 v[216:217], off
	v_lshl_add_u64 v[216:217], v[222:223], 0, s[16:17]
	s_mov_b32 m0, s39
	s_nop 0
	global_load_lds_dwordx4 v[216:217], off
	s_waitcnt vmcnt(8)
	s_waitcnt lgkmcnt(0)
	s_setprio 1
	s_barrier
	v_mfma_f32_16x16x32_bf16 v[62:65], v[152:155], v[184:187], v[62:65]
	v_mfma_f32_16x16x32_bf16 v[58:61], v[160:163], v[184:187], v[58:61]
	v_mfma_f32_16x16x32_bf16 v[46:49], v[152:155], v[192:195], v[46:49]
	v_mfma_f32_16x16x32_bf16 v[42:45], v[160:163], v[192:195], v[42:45]
	v_mfma_f32_16x16x32_bf16 v[30:33], v[152:155], v[200:203], v[30:33]
	v_mfma_f32_16x16x32_bf16 v[26:29], v[160:163], v[200:203], v[26:29]
	v_mfma_f32_16x16x32_bf16 v[14:17], v[152:155], v[208:211], v[14:17]
	v_mfma_f32_16x16x32_bf16 v[10:13], v[160:163], v[208:211], v[10:13]
	v_mfma_f32_16x16x32_bf16 v[62:65], v[156:159], v[188:191], v[62:65]
	v_mfma_f32_16x16x32_bf16 v[58:61], v[164:167], v[188:191], v[58:61]
	v_mfma_f32_16x16x32_bf16 v[46:49], v[156:159], v[196:199], v[46:49]
	v_mfma_f32_16x16x32_bf16 v[42:45], v[164:167], v[196:199], v[42:45]
	v_mfma_f32_16x16x32_bf16 v[30:33], v[156:159], v[204:207], v[30:33]
	v_mfma_f32_16x16x32_bf16 v[26:29], v[164:167], v[204:207], v[26:29]
	v_mfma_f32_16x16x32_bf16 v[14:17], v[156:159], v[212:215], v[14:17]
	v_mfma_f32_16x16x32_bf16 v[10:13], v[164:167], v[212:215], v[10:13]
	s_setprio 0
	s_setprio 1
	v_mfma_f32_16x16x32_bf16 v[54:57], v[168:171], v[184:187], v[54:57]
	v_mfma_f32_16x16x32_bf16 v[50:53], v[176:179], v[184:187], v[50:53]
	v_mfma_f32_16x16x32_bf16 v[38:41], v[168:171], v[192:195], v[38:41]
	v_mfma_f32_16x16x32_bf16 v[34:37], v[176:179], v[192:195], v[34:37]
	v_mfma_f32_16x16x32_bf16 v[22:25], v[168:171], v[200:203], v[22:25]
	v_mfma_f32_16x16x32_bf16 v[18:21], v[176:179], v[200:203], v[18:21]
	v_mfma_f32_16x16x32_bf16 v[6:9], v[168:171], v[208:211], v[6:9]
	v_mfma_f32_16x16x32_bf16 v[2:5], v[176:179], v[208:211], v[2:5]
	v_mfma_f32_16x16x32_bf16 v[54:57], v[172:175], v[188:191], v[54:57]
	v_mfma_f32_16x16x32_bf16 v[50:53], v[180:183], v[188:191], v[50:53]
	v_mfma_f32_16x16x32_bf16 v[38:41], v[172:175], v[196:199], v[38:41]
	v_mfma_f32_16x16x32_bf16 v[34:37], v[180:183], v[196:199], v[34:37]
	v_mfma_f32_16x16x32_bf16 v[22:25], v[172:175], v[204:207], v[22:25]
	v_mfma_f32_16x16x32_bf16 v[18:21], v[180:183], v[204:207], v[18:21]
	v_mfma_f32_16x16x32_bf16 v[6:9], v[172:175], v[212:215], v[6:9]
	v_mfma_f32_16x16x32_bf16 v[2:5], v[180:183], v[212:215], v[2:5]
	s_barrier
	s_setprio 0
	s_add_i32 s54, s54, 2
	s_add_u32 s50, s50, 0x100
	s_addc_u32 s51, s51, 0
	s_add_u32 s36, s36, 0x100
	s_addc_u32 s37, s37, 0
	s_cmp_gt_u32 s54, 29
	s_cbranch_scc0 .LBB0_122
	s_and_b64 vcc, exec, s[20:21]
	s_cbranch_vccz .LBB0_125
	s_barrier

.LBB0_139:
	ds_read_b128 v[150:153], v146
	ds_read_b128 v[154:157], v146 offset:1024
	ds_read_b128 v[158:161], v146 offset:2048
	ds_read_b128 v[162:165], v146 offset:3072
	ds_read_b128 v[166:169], v147
	ds_read_b128 v[170:173], v147 offset:1024
	ds_read_b128 v[174:177], v147 offset:2048
	ds_read_b128 v[178:181], v147 offset:3072
	s_add_u32 s44, s36, 0xfff80080
	s_addc_u32 s45, s37, -1
	s_cmp_eq_u32 s68, 28
	s_cselect_b32 s53, s23, s45
	s_cselect_b32 s52, s50, s44
	s_cselect_b32 s45, s21, s55
	s_cselect_b32 s44, s51, s54
	v_lshl_add_u64 v[142:143], s[36:37], 0, v[140:141]
	s_add_i32 m0, s34, 0xc000
	ds_read_b128 v[182:185], v148
	ds_read_b128 v[186:189], v148 offset:1024
	ds_read_b128 v[190:193], v148 offset:2048
	ds_read_b128 v[194:197], v148 offset:3072
	ds_read_b128 v[198:201], v148 offset:4096
	ds_read_b128 v[202:205], v148 offset:5120
	ds_read_b128 v[206:209], v148 offset:6144
	ds_read_b128 v[210:213], v148 offset:7168
	global_load_lds_dwordx4 v[142:143], off
	v_lshl_add_u64 v[142:143], s[36:37], 0, v[138:139]
	s_add_i32 m0, s34, 0xe000
	s_nop 0
	global_load_lds_dwordx4 v[142:143], off
	s_waitcnt vmcnt(8)
	s_waitcnt lgkmcnt(0)
	s_setprio 1
	s_barrier
	v_mfma_f32_16x16x32_bf16 v[126:129], v[150:153], v[182:185], v[126:129]
	v_mfma_f32_16x16x32_bf16 v[122:125], v[158:161], v[182:185], v[122:125]
	v_mfma_f32_16x16x32_bf16 v[118:121], v[150:153], v[190:193], v[118:121]
	v_mfma_f32_16x16x32_bf16 v[110:113], v[158:161], v[190:193], v[110:113]
	v_mfma_f32_16x16x32_bf16 v[102:105], v[150:153], v[198:201], v[102:105]
	v_mfma_f32_16x16x32_bf16 v[94:97], v[158:161], v[198:201], v[94:97]
	v_mfma_f32_16x16x32_bf16 v[86:89], v[150:153], v[206:209], v[86:89]
	v_mfma_f32_16x16x32_bf16 v[78:81], v[158:161], v[206:209], v[78:81]
	v_mfma_f32_16x16x32_bf16 v[126:129], v[154:157], v[186:189], v[126:129]
	v_mfma_f32_16x16x32_bf16 v[122:125], v[162:165], v[186:189], v[122:125]
	v_mfma_f32_16x16x32_bf16 v[118:121], v[154:157], v[194:197], v[118:121]
	v_mfma_f32_16x16x32_bf16 v[110:113], v[162:165], v[194:197], v[110:113]
	v_mfma_f32_16x16x32_bf16 v[102:105], v[154:157], v[202:205], v[102:105]
	v_mfma_f32_16x16x32_bf16 v[94:97], v[162:165], v[202:205], v[94:97]
	v_mfma_f32_16x16x32_bf16 v[86:89], v[154:157], v[210:213], v[86:89]
	v_mfma_f32_16x16x32_bf16 v[78:81], v[162:165], v[210:213], v[78:81]
	s_setprio 0
	s_setprio 1
	v_mfma_f32_16x16x32_bf16 v[114:117], v[166:169], v[182:185], v[114:117]
	v_mfma_f32_16x16x32_bf16 v[106:109], v[174:177], v[182:185], v[106:109]
	v_mfma_f32_16x16x32_bf16 v[98:101], v[166:169], v[190:193], v[98:101]
	v_mfma_f32_16x16x32_bf16 v[90:93], v[174:177], v[190:193], v[90:93]
	v_mfma_f32_16x16x32_bf16 v[82:85], v[166:169], v[198:201], v[82:85]
	v_mfma_f32_16x16x32_bf16 v[74:77], v[174:177], v[198:201], v[74:77]
	v_mfma_f32_16x16x32_bf16 v[70:73], v[166:169], v[206:209], v[70:73]
	v_mfma_f32_16x16x32_bf16 v[66:69], v[174:177], v[206:209], v[66:69]
	v_mfma_f32_16x16x32_bf16 v[114:117], v[170:173], v[186:189], v[114:117]
	v_mfma_f32_16x16x32_bf16 v[106:109], v[178:181], v[186:189], v[106:109]
	v_mfma_f32_16x16x32_bf16 v[98:101], v[170:173], v[194:197], v[98:101]
	v_mfma_f32_16x16x32_bf16 v[90:93], v[178:181], v[194:197], v[90:93]
	v_mfma_f32_16x16x32_bf16 v[82:85], v[170:173], v[202:205], v[82:85]
	v_mfma_f32_16x16x32_bf16 v[74:77], v[178:181], v[202:205], v[74:77]
	v_mfma_f32_16x16x32_bf16 v[70:73], v[170:173], v[210:213], v[70:73]
	v_mfma_f32_16x16x32_bf16 v[66:69], v[178:181], v[210:213], v[66:69]
	s_barrier
	s_setprio 0
	s_add_i32 s69, s48, s19
	v_lshl_add_u64 v[142:143], s[44:45], 0, v[134:135]
	s_mov_b32 m0, s69
	ds_read_b128 v[182:185], v148 offset:16384
	ds_read_b128 v[186:189], v148 offset:17408
	ds_read_b128 v[190:193], v148 offset:18432
	ds_read_b128 v[194:197], v148 offset:19456
	ds_read_b128 v[198:201], v148 offset:20480
	ds_read_b128 v[202:205], v148 offset:21504
	ds_read_b128 v[206:209], v148 offset:22528
	ds_read_b128 v[210:213], v148 offset:23552
	global_load_lds_dwordx4 v[142:143], off
	s_add_i32 m0, s69, 0x2000
	s_add_u32 s70, s44, 0x80000
	v_lshl_add_u64 v[214:215], s[44:45], 0, v[130:131]
	s_addc_u32 s71, s45, 0
	s_add_i32 s69, s49, s19
	global_load_lds_dwordx4 v[214:215], off
	v_lshl_add_u64 v[216:217], s[70:71], 0, v[134:135]
	s_mov_b32 m0, s69
	v_lshl_add_u64 v[218:219], s[52:53], 0, v[132:133]
	global_load_lds_dwordx4 v[216:217], off
	v_lshl_add_u64 v[216:217], s[70:71], 0, v[130:131]
	s_add_i32 m0, s69, 0x2000
	s_nop 0
	global_load_lds_dwordx4 v[216:217], off
	v_lshl_add_u64 v[216:217], s[52:53], 0, v[136:137]
	s_mov_b32 m0, s34
	s_nop 0
	global_load_lds_dwordx4 v[216:217], off
	s_mov_b32 m0, s35
	s_nop 0
	global_load_lds_dwordx4 v[218:219], off
	s_waitcnt vmcnt(8)
	s_waitcnt lgkmcnt(0)
	s_setprio 1
	s_barrier
	v_mfma_f32_16x16x32_bf16 v[62:65], v[150:153], v[182:185], v[62:65]
	v_mfma_f32_16x16x32_bf16 v[58:61], v[158:161], v[182:185], v[58:61]
	v_mfma_f32_16x16x32_bf16 v[54:57], v[150:153], v[190:193], v[54:57]
	v_mfma_f32_16x16x32_bf16 v[46:49], v[158:161], v[190:193], v[46:49]
	v_mfma_f32_16x16x32_bf16 v[38:41], v[150:153], v[198:201], v[38:41]
	v_mfma_f32_16x16x32_bf16 v[30:33], v[158:161], v[198:201], v[30:33]
	v_mfma_f32_16x16x32_bf16 v[22:25], v[150:153], v[206:209], v[22:25]
	v_mfma_f32_16x16x32_bf16 v[14:17], v[158:161], v[206:209], v[14:17]
	v_mfma_f32_16x16x32_bf16 v[62:65], v[154:157], v[186:189], v[62:65]
	v_mfma_f32_16x16x32_bf16 v[58:61], v[162:165], v[186:189], v[58:61]
	v_mfma_f32_16x16x32_bf16 v[54:57], v[154:157], v[194:197], v[54:57]
	v_mfma_f32_16x16x32_bf16 v[46:49], v[162:165], v[194:197], v[46:49]
	v_mfma_f32_16x16x32_bf16 v[38:41], v[154:157], v[202:205], v[38:41]
	v_mfma_f32_16x16x32_bf16 v[30:33], v[162:165], v[202:205], v[30:33]
	v_mfma_f32_16x16x32_bf16 v[22:25], v[154:157], v[210:213], v[22:25]
	v_mfma_f32_16x16x32_bf16 v[14:17], v[162:165], v[210:213], v[14:17]
	s_setprio 0
	s_setprio 1
	v_mfma_f32_16x16x32_bf16 v[50:53], v[166:169], v[182:185], v[50:53]
	v_mfma_f32_16x16x32_bf16 v[42:45], v[174:177], v[182:185], v[42:45]
	v_mfma_f32_16x16x32_bf16 v[34:37], v[166:169], v[190:193], v[34:37]
	v_mfma_f32_16x16x32_bf16 v[26:29], v[174:177], v[190:193], v[26:29]
	v_mfma_f32_16x16x32_bf16 v[18:21], v[166:169], v[198:201], v[18:21]
	v_mfma_f32_16x16x32_bf16 v[10:13], v[174:177], v[198:201], v[10:13]
	v_mfma_f32_16x16x32_bf16 v[6:9], v[166:169], v[206:209], v[6:9]
	v_mfma_f32_16x16x32_bf16 v[2:5], v[174:177], v[206:209], v[2:5]
	v_mfma_f32_16x16x32_bf16 v[50:53], v[170:173], v[186:189], v[50:53]
	v_mfma_f32_16x16x32_bf16 v[42:45], v[178:181], v[186:189], v[42:45]
	v_mfma_f32_16x16x32_bf16 v[34:37], v[170:173], v[194:197], v[34:37]
	v_mfma_f32_16x16x32_bf16 v[26:29], v[178:181], v[194:197], v[26:29]
	v_mfma_f32_16x16x32_bf16 v[18:21], v[170:173], v[202:205], v[18:21]
	v_mfma_f32_16x16x32_bf16 v[10:13], v[178:181], v[202:205], v[10:13]
	v_mfma_f32_16x16x32_bf16 v[6:9], v[170:173], v[210:213], v[6:9]
	v_mfma_f32_16x16x32_bf16 v[2:5], v[178:181], v[210:213], v[2:5]
	s_barrier
	s_setprio 0
	s_add_i32 s69, 0, 0x18000
	v_add_u32_e32 v149, s69, v145
	s_add_i32 s70, 0, 0x1c000
	ds_read_b128 v[150:153], v149
	ds_read_b128 v[154:157], v149 offset:1024
	ds_read_b128 v[158:161], v149 offset:2048
	ds_read_b128 v[162:165], v149 offset:3072
	v_add_u32_e32 v149, s70, v145
	ds_read_b128 v[166:169], v149
	ds_read_b128 v[170:173], v149 offset:1024
	ds_read_b128 v[174:177], v149 offset:2048
	ds_read_b128 v[178:181], v149 offset:3072
	s_add_u32 s52, s52, 0x80000
	s_addc_u32 s53, s53, 0
	s_mov_b32 m0, s38
	v_lshl_add_u64 v[220:221], s[52:53], 0, v[136:137]
	ds_read_b128 v[182:185], v148 offset:32768
	ds_read_b128 v[186:189], v148 offset:33792
	ds_read_b128 v[190:193], v148 offset:34816
	ds_read_b128 v[194:197], v148 offset:35840
	ds_read_b128 v[198:201], v148 offset:36864
	ds_read_b128 v[202:205], v148 offset:37888
	ds_read_b128 v[206:209], v148 offset:38912
	ds_read_b128 v[210:213], v148 offset:39936
	global_load_lds_dwordx4 v[220:221], off
	v_lshl_add_u64 v[220:221], s[52:53], 0, v[132:133]
	s_mov_b32 m0, s39
	s_nop 0
	global_load_lds_dwordx4 v[220:221], off
	s_waitcnt vmcnt(8)
	s_waitcnt lgkmcnt(0)
	s_setprio 1
	s_barrier
	v_mfma_f32_16x16x32_bf16 v[126:129], v[150:153], v[182:185], v[126:129]
	v_mfma_f32_16x16x32_bf16 v[122:125], v[158:161], v[182:185], v[122:125]
	v_mfma_f32_16x16x32_bf16 v[118:121], v[150:153], v[190:193], v[118:121]
	v_mfma_f32_16x16x32_bf16 v[110:113], v[158:161], v[190:193], v[110:113]
	v_mfma_f32_16x16x32_bf16 v[102:105], v[150:153], v[198:201], v[102:105]
	v_mfma_f32_16x16x32_bf16 v[94:97], v[158:161], v[198:201], v[94:97]
	v_mfma_f32_16x16x32_bf16 v[86:89], v[150:153], v[206:209], v[86:89]
	v_mfma_f32_16x16x32_bf16 v[78:81], v[158:161], v[206:209], v[78:81]
	v_mfma_f32_16x16x32_bf16 v[126:129], v[154:157], v[186:189], v[126:129]
	v_mfma_f32_16x16x32_bf16 v[122:125], v[162:165], v[186:189], v[122:125]
	v_mfma_f32_16x16x32_bf16 v[118:121], v[154:157], v[194:197], v[118:121]
	v_mfma_f32_16x16x32_bf16 v[110:113], v[162:165], v[194:197], v[110:113]
	v_mfma_f32_16x16x32_bf16 v[102:105], v[154:157], v[202:205], v[102:105]
	v_mfma_f32_16x16x32_bf16 v[94:97], v[162:165], v[202:205], v[94:97]
	v_mfma_f32_16x16x32_bf16 v[86:89], v[154:157], v[210:213], v[86:89]
	v_mfma_f32_16x16x32_bf16 v[78:81], v[162:165], v[210:213], v[78:81]
	s_setprio 0
	s_setprio 1
	v_mfma_f32_16x16x32_bf16 v[114:117], v[166:169], v[182:185], v[114:117]
	v_mfma_f32_16x16x32_bf16 v[106:109], v[174:177], v[182:185], v[106:109]
	v_mfma_f32_16x16x32_bf16 v[98:101], v[166:169], v[190:193], v[98:101]
	v_mfma_f32_16x16x32_bf16 v[90:93], v[174:177], v[190:193], v[90:93]
	v_mfma_f32_16x16x32_bf16 v[82:85], v[166:169], v[198:201], v[82:85]
	v_mfma_f32_16x16x32_bf16 v[74:77], v[174:177], v[198:201], v[74:77]
	v_mfma_f32_16x16x32_bf16 v[70:73], v[166:169], v[206:209], v[70:73]
	v_mfma_f32_16x16x32_bf16 v[66:69], v[174:177], v[206:209], v[66:69]
	v_mfma_f32_16x16x32_bf16 v[114:117], v[170:173], v[186:189], v[114:117]
	v_mfma_f32_16x16x32_bf16 v[106:109], v[178:181], v[186:189], v[106:109]
	v_mfma_f32_16x16x32_bf16 v[98:101], v[170:173], v[194:197], v[98:101]
	v_mfma_f32_16x16x32_bf16 v[90:93], v[178:181], v[194:197], v[90:93]
	v_mfma_f32_16x16x32_bf16 v[82:85], v[170:173], v[202:205], v[82:85]
	v_mfma_f32_16x16x32_bf16 v[74:77], v[178:181], v[202:205], v[74:77]
	v_mfma_f32_16x16x32_bf16 v[70:73], v[170:173], v[210:213], v[70:73]
	v_mfma_f32_16x16x32_bf16 v[66:69], v[178:181], v[210:213], v[66:69]
	s_barrier
	s_setprio 0
	s_add_i32 s52, s69, s19
	v_lshl_add_u64 v[142:143], v[142:143], 0, s[8:9]
	s_mov_b32 m0, s52
	ds_read_b128 v[182:185], v148 offset:49152
	ds_read_b128 v[186:189], v148 offset:50176
	ds_read_b128 v[190:193], v148 offset:51200
	ds_read_b128 v[194:197], v148 offset:52224
	ds_read_b128 v[198:201], v148 offset:53248
	ds_read_b128 v[202:205], v148 offset:54272
	ds_read_b128 v[206:209], v148 offset:55296
	ds_read_b128 v[210:213], v148 offset:56320
	global_load_lds_dwordx4 v[142:143], off
	s_add_i32 m0, s52, 0x2000
	s_add_u32 s44, s44, 0x80080
	v_lshl_add_u64 v[142:143], v[214:215], 0, s[8:9]
	s_addc_u32 s45, s45, 0
	s_add_i32 s52, s70, s19
	global_load_lds_dwordx4 v[142:143], off
	v_lshl_add_u64 v[142:143], s[44:45], 0, v[134:135]
	s_mov_b32 m0, s52
	s_nop 0
	global_load_lds_dwordx4 v[142:143], off
	v_lshl_add_u64 v[142:143], s[44:45], 0, v[130:131]
	s_add_i32 m0, s52, 0x2000
	s_nop 0
	global_load_lds_dwordx4 v[142:143], off
	v_lshl_add_u64 v[142:143], v[216:217], 0, s[8:9]
	s_mov_b32 m0, s42
	s_nop 0
	global_load_lds_dwordx4 v[142:143], off
	v_lshl_add_u64 v[142:143], v[218:219], 0, s[8:9]
	s_mov_b32 m0, s43
	s_nop 0
	global_load_lds_dwordx4 v[142:143], off
	s_waitcnt vmcnt(8)
	s_waitcnt lgkmcnt(0)
	s_setprio 1
	s_barrier
	v_mfma_f32_16x16x32_bf16 v[62:65], v[150:153], v[182:185], v[62:65]
	v_mfma_f32_16x16x32_bf16 v[58:61], v[158:161], v[182:185], v[58:61]
	v_mfma_f32_16x16x32_bf16 v[54:57], v[150:153], v[190:193], v[54:57]
	v_mfma_f32_16x16x32_bf16 v[46:49], v[158:161], v[190:193], v[46:49]
	v_mfma_f32_16x16x32_bf16 v[38:41], v[150:153], v[198:201], v[38:41]
	v_mfma_f32_16x16x32_bf16 v[30:33], v[158:161], v[198:201], v[30:33]
	v_mfma_f32_16x16x32_bf16 v[22:25], v[150:153], v[206:209], v[22:25]
	v_mfma_f32_16x16x32_bf16 v[14:17], v[158:161], v[206:209], v[14:17]
	v_mfma_f32_16x16x32_bf16 v[62:65], v[154:157], v[186:189], v[62:65]
	v_mfma_f32_16x16x32_bf16 v[58:61], v[162:165], v[186:189], v[58:61]
	v_mfma_f32_16x16x32_bf16 v[54:57], v[154:157], v[194:197], v[54:57]
	v_mfma_f32_16x16x32_bf16 v[46:49], v[162:165], v[194:197], v[46:49]
	v_mfma_f32_16x16x32_bf16 v[38:41], v[154:157], v[202:205], v[38:41]
	v_mfma_f32_16x16x32_bf16 v[30:33], v[162:165], v[202:205], v[30:33]
	v_mfma_f32_16x16x32_bf16 v[22:25], v[154:157], v[210:213], v[22:25]
	v_mfma_f32_16x16x32_bf16 v[14:17], v[162:165], v[210:213], v[14:17]
	s_setprio 0
	s_setprio 1
	v_mfma_f32_16x16x32_bf16 v[50:53], v[166:169], v[182:185], v[50:53]
	v_mfma_f32_16x16x32_bf16 v[42:45], v[174:177], v[182:185], v[42:45]
	v_mfma_f32_16x16x32_bf16 v[34:37], v[166:169], v[190:193], v[34:37]
	v_mfma_f32_16x16x32_bf16 v[26:29], v[174:177], v[190:193], v[26:29]
	v_mfma_f32_16x16x32_bf16 v[18:21], v[166:169], v[198:201], v[18:21]
	v_mfma_f32_16x16x32_bf16 v[10:13], v[174:177], v[198:201], v[10:13]
	v_mfma_f32_16x16x32_bf16 v[6:9], v[166:169], v[206:209], v[6:9]
	v_mfma_f32_16x16x32_bf16 v[2:5], v[174:177], v[206:209], v[2:5]
	v_mfma_f32_16x16x32_bf16 v[50:53], v[170:173], v[186:189], v[50:53]
	v_mfma_f32_16x16x32_bf16 v[42:45], v[178:181], v[186:189], v[42:45]
	v_mfma_f32_16x16x32_bf16 v[34:37], v[170:173], v[194:197], v[34:37]
	v_mfma_f32_16x16x32_bf16 v[26:29], v[178:181], v[194:197], v[26:29]
	v_mfma_f32_16x16x32_bf16 v[18:21], v[170:173], v[202:205], v[18:21]
	v_mfma_f32_16x16x32_bf16 v[10:13], v[178:181], v[202:205], v[10:13]
	v_mfma_f32_16x16x32_bf16 v[6:9], v[170:173], v[210:213], v[6:9]
	v_mfma_f32_16x16x32_bf16 v[2:5], v[178:181], v[210:213], v[2:5]
	s_barrier
	s_setprio 0
	s_add_i32 s68, s68, 2
	s_add_u32 s54, s54, 0x100
	s_addc_u32 s55, s55, 0
	s_add_u32 s36, s36, 0x100
	s_addc_u32 s37, s37, 0
	s_cmp_gt_u32 s68, 29
	s_cbranch_scc0 .LBB0_139
	s_and_b64 vcc, exec, s[16:17]
	s_cbranch_vccz .LBB0_142
	s_barrier

.LBB0_266:
	ds_read_b128 v[82:85], v188
	ds_read_b128 v[86:89], v188 offset:1024
	ds_read_b128 v[94:97], v188 offset:2048
	ds_read_b128 v[98:101], v188 offset:3072
	ds_read_b128 v[146:149], v189
	ds_read_b128 v[150:153], v189 offset:1024
	ds_read_b128 v[154:157], v189 offset:2048
	ds_read_b128 v[158:161], v189 offset:3072
	s_add_u32 s6, s44, 0x100
	s_addc_u32 s7, s45, 0
	s_cmpk_eq_i32 s70, 0x54
	s_cselect_b32 s55, s31, s7
	s_cselect_b32 s54, s30, s6
	s_cselect_b32 s53, s37, s69
	s_cselect_b32 s52, s36, s68
	v_lshl_add_u64 v[216:217], s[44:45], 0, v[172:173]
	s_add_i32 m0, s14, 0xc000
	ds_read_b128 v[178:181], v190
	ds_read_b128 v[182:185], v190 offset:1024
	ds_read_b128 v[192:195], v190 offset:2048
	ds_read_b128 v[196:199], v190 offset:3072
	ds_read_b128 v[200:203], v190 offset:4096
	ds_read_b128 v[204:207], v190 offset:5120
	ds_read_b128 v[208:211], v190 offset:6144
	ds_read_b128 v[212:215], v190 offset:7168
	global_load_lds_dwordx4 v[216:217], off
	v_lshl_add_u64 v[216:217], s[44:45], 0, v[170:171]
	s_add_i32 m0, s14, 0xe000
	s_nop 0
	global_load_lds_dwordx4 v[216:217], off
	s_waitcnt vmcnt(8)
	s_waitcnt lgkmcnt(0)
	s_setprio 1
	s_barrier
	v_mfma_f32_16x16x32_bf16 v[142:145], v[82:85], v[178:181], v[142:145]
	v_mfma_f32_16x16x32_bf16 v[138:141], v[94:97], v[178:181], v[138:141]
	v_mfma_f32_16x16x32_bf16 v[126:129], v[82:85], v[192:195], v[126:129]
	v_mfma_f32_16x16x32_bf16 v[122:125], v[94:97], v[192:195], v[122:125]
	v_mfma_f32_16x16x32_bf16 v[110:113], v[82:85], v[200:203], v[110:113]
	v_mfma_f32_16x16x32_bf16 v[106:109], v[94:97], v[200:203], v[106:109]
	v_mfma_f32_16x16x32_bf16 v[78:81], v[82:85], v[208:211], v[78:81]
	v_mfma_f32_16x16x32_bf16 v[74:77], v[94:97], v[208:211], v[74:77]
	v_mfma_f32_16x16x32_bf16 v[142:145], v[86:89], v[182:185], v[142:145]
	v_mfma_f32_16x16x32_bf16 v[138:141], v[98:101], v[182:185], v[138:141]
	v_mfma_f32_16x16x32_bf16 v[126:129], v[86:89], v[196:199], v[126:129]
	v_mfma_f32_16x16x32_bf16 v[122:125], v[98:101], v[196:199], v[122:125]
	v_mfma_f32_16x16x32_bf16 v[110:113], v[86:89], v[204:207], v[110:113]
	v_mfma_f32_16x16x32_bf16 v[106:109], v[98:101], v[204:207], v[106:109]
	v_mfma_f32_16x16x32_bf16 v[78:81], v[86:89], v[212:215], v[78:81]
	v_mfma_f32_16x16x32_bf16 v[74:77], v[98:101], v[212:215], v[74:77]
	s_setprio 0
	s_setprio 1
	v_mfma_f32_16x16x32_bf16 v[134:137], v[146:149], v[178:181], v[134:137]
	v_mfma_f32_16x16x32_bf16 v[130:133], v[154:157], v[178:181], v[130:133]
	v_mfma_f32_16x16x32_bf16 v[118:121], v[146:149], v[192:195], v[118:121]
	v_mfma_f32_16x16x32_bf16 v[114:117], v[154:157], v[192:195], v[114:117]
	v_mfma_f32_16x16x32_bf16 v[102:105], v[146:149], v[200:203], v[102:105]
	v_mfma_f32_16x16x32_bf16 v[90:93], v[154:157], v[200:203], v[90:93]
	v_mfma_f32_16x16x32_bf16 v[70:73], v[146:149], v[208:211], v[70:73]
	v_mfma_f32_16x16x32_bf16 v[66:69], v[154:157], v[208:211], v[66:69]
	v_mfma_f32_16x16x32_bf16 v[134:137], v[150:153], v[182:185], v[134:137]
	v_mfma_f32_16x16x32_bf16 v[130:133], v[158:161], v[182:185], v[130:133]
	v_mfma_f32_16x16x32_bf16 v[118:121], v[150:153], v[196:199], v[118:121]
	v_mfma_f32_16x16x32_bf16 v[114:117], v[158:161], v[196:199], v[114:117]
	v_mfma_f32_16x16x32_bf16 v[102:105], v[150:153], v[204:207], v[102:105]
	v_mfma_f32_16x16x32_bf16 v[90:93], v[158:161], v[204:207], v[90:93]
	v_mfma_f32_16x16x32_bf16 v[70:73], v[150:153], v[212:215], v[70:73]
	v_mfma_f32_16x16x32_bf16 v[66:69], v[158:161], v[212:215], v[66:69]
	s_barrier
	s_setprio 0
	s_add_i32 s44, s46, s13
	v_lshl_add_u64 v[216:217], s[52:53], 0, v[164:165]
	s_mov_b32 m0, s44
	ds_read_b128 v[178:181], v190 offset:16384
	ds_read_b128 v[182:185], v190 offset:17408
	ds_read_b128 v[192:195], v190 offset:18432
	ds_read_b128 v[196:199], v190 offset:19456
	ds_read_b128 v[200:203], v190 offset:20480
	ds_read_b128 v[204:207], v190 offset:21504
	ds_read_b128 v[208:211], v190 offset:22528
	ds_read_b128 v[212:215], v190 offset:23552
	global_load_lds_dwordx4 v[216:217], off
	s_add_i32 m0, s44, 0x2000
	s_add_u32 s44, s52, 0x160000
	v_lshl_add_u64 v[218:219], s[52:53], 0, v[168:169]
	s_addc_u32 s45, s53, 0
	s_add_i32 s71, s47, s13
	global_load_lds_dwordx4 v[218:219], off
	v_lshl_add_u64 v[220:221], s[44:45], 0, v[164:165]
	s_mov_b32 m0, s71
	v_lshl_add_u64 v[222:223], s[54:55], 0, v[166:167]
	global_load_lds_dwordx4 v[220:221], off
	v_lshl_add_u64 v[220:221], s[44:45], 0, v[168:169]
	s_add_i32 m0, s71, 0x2000
	s_nop 0
	global_load_lds_dwordx4 v[220:221], off
	v_lshl_add_u64 v[220:221], s[54:55], 0, v[162:163]
	s_mov_b32 m0, s14
	s_nop 0
	global_load_lds_dwordx4 v[220:221], off
	s_mov_b32 m0, s15
	s_nop 0
	global_load_lds_dwordx4 v[222:223], off
	s_waitcnt vmcnt(8)
	s_waitcnt lgkmcnt(0)
	s_setprio 1
	s_barrier
	v_mfma_f32_16x16x32_bf16 v[62:65], v[82:85], v[178:181], v[62:65]
	v_mfma_f32_16x16x32_bf16 v[58:61], v[94:97], v[178:181], v[58:61]
	v_mfma_f32_16x16x32_bf16 v[46:49], v[82:85], v[192:195], v[46:49]
	v_mfma_f32_16x16x32_bf16 v[42:45], v[94:97], v[192:195], v[42:45]
	v_mfma_f32_16x16x32_bf16 v[30:33], v[82:85], v[200:203], v[30:33]
	v_mfma_f32_16x16x32_bf16 v[26:29], v[94:97], v[200:203], v[26:29]
	v_mfma_f32_16x16x32_bf16 v[14:17], v[82:85], v[208:211], v[14:17]
	v_mfma_f32_16x16x32_bf16 v[10:13], v[94:97], v[208:211], v[10:13]
	v_mfma_f32_16x16x32_bf16 v[62:65], v[86:89], v[182:185], v[62:65]
	v_mfma_f32_16x16x32_bf16 v[58:61], v[98:101], v[182:185], v[58:61]
	v_mfma_f32_16x16x32_bf16 v[46:49], v[86:89], v[196:199], v[46:49]
	v_mfma_f32_16x16x32_bf16 v[42:45], v[98:101], v[196:199], v[42:45]
	v_mfma_f32_16x16x32_bf16 v[30:33], v[86:89], v[204:207], v[30:33]
	v_mfma_f32_16x16x32_bf16 v[26:29], v[98:101], v[204:207], v[26:29]
	v_mfma_f32_16x16x32_bf16 v[14:17], v[86:89], v[212:215], v[14:17]
	v_mfma_f32_16x16x32_bf16 v[10:13], v[98:101], v[212:215], v[10:13]
	s_setprio 0
	s_setprio 1
	v_mfma_f32_16x16x32_bf16 v[54:57], v[146:149], v[178:181], v[54:57]
	v_mfma_f32_16x16x32_bf16 v[50:53], v[154:157], v[178:181], v[50:53]
	v_mfma_f32_16x16x32_bf16 v[38:41], v[146:149], v[192:195], v[38:41]
	v_mfma_f32_16x16x32_bf16 v[34:37], v[154:157], v[192:195], v[34:37]
	v_mfma_f32_16x16x32_bf16 v[22:25], v[146:149], v[200:203], v[22:25]
	v_mfma_f32_16x16x32_bf16 v[18:21], v[154:157], v[200:203], v[18:21]
	v_mfma_f32_16x16x32_bf16 v[6:9], v[146:149], v[208:211], v[6:9]
	v_mfma_f32_16x16x32_bf16 v[2:5], v[154:157], v[208:211], v[2:5]
	v_mfma_f32_16x16x32_bf16 v[54:57], v[150:153], v[182:185], v[54:57]
	v_mfma_f32_16x16x32_bf16 v[50:53], v[158:161], v[182:185], v[50:53]
	v_mfma_f32_16x16x32_bf16 v[38:41], v[150:153], v[196:199], v[38:41]
	v_mfma_f32_16x16x32_bf16 v[34:37], v[158:161], v[196:199], v[34:37]
	v_mfma_f32_16x16x32_bf16 v[22:25], v[150:153], v[204:207], v[22:25]
	v_mfma_f32_16x16x32_bf16 v[18:21], v[158:161], v[204:207], v[18:21]
	v_mfma_f32_16x16x32_bf16 v[6:9], v[150:153], v[212:215], v[6:9]
	v_mfma_f32_16x16x32_bf16 v[2:5], v[158:161], v[212:215], v[2:5]
	s_barrier
	s_setprio 0
	s_add_i32 s71, 0, 0x18000
	s_add_i32 s72, 0, 0x1c000
	v_add_u32_e32 v98, s71, v187
	v_add_u32_e32 v158, s72, v187
	ds_read_b128 v[82:85], v98
	ds_read_b128 v[86:89], v98 offset:1024
	ds_read_b128 v[94:97], v98 offset:2048
	ds_read_b128 v[98:101], v98 offset:3072
	ds_read_b128 v[146:149], v158
	ds_read_b128 v[150:153], v158 offset:1024
	ds_read_b128 v[154:157], v158 offset:2048
	ds_read_b128 v[158:161], v158 offset:3072
	s_add_u32 s44, s54, 0x160000
	s_addc_u32 s45, s55, 0
	s_mov_b32 m0, s18
	v_lshl_add_u64 v[224:225], s[44:45], 0, v[162:163]
	ds_read_b128 v[178:181], v190 offset:32768
	ds_read_b128 v[182:185], v190 offset:33792
	ds_read_b128 v[192:195], v190 offset:34816
	ds_read_b128 v[196:199], v190 offset:35840
	ds_read_b128 v[200:203], v190 offset:36864
	ds_read_b128 v[204:207], v190 offset:37888
	ds_read_b128 v[208:211], v190 offset:38912
	ds_read_b128 v[212:215], v190 offset:39936
	global_load_lds_dwordx4 v[224:225], off
	v_lshl_add_u64 v[224:225], s[44:45], 0, v[166:167]
	s_mov_b32 m0, s19
	s_nop 0
	global_load_lds_dwordx4 v[224:225], off
	s_waitcnt vmcnt(8)
	s_waitcnt lgkmcnt(0)
	s_setprio 1
	s_barrier
	v_mfma_f32_16x16x32_bf16 v[142:145], v[82:85], v[178:181], v[142:145]
	v_mfma_f32_16x16x32_bf16 v[138:141], v[94:97], v[178:181], v[138:141]
	v_mfma_f32_16x16x32_bf16 v[126:129], v[82:85], v[192:195], v[126:129]
	v_mfma_f32_16x16x32_bf16 v[122:125], v[94:97], v[192:195], v[122:125]
	v_mfma_f32_16x16x32_bf16 v[110:113], v[82:85], v[200:203], v[110:113]
	v_mfma_f32_16x16x32_bf16 v[106:109], v[94:97], v[200:203], v[106:109]
	v_mfma_f32_16x16x32_bf16 v[78:81], v[82:85], v[208:211], v[78:81]
	v_mfma_f32_16x16x32_bf16 v[74:77], v[94:97], v[208:211], v[74:77]
	v_mfma_f32_16x16x32_bf16 v[142:145], v[86:89], v[182:185], v[142:145]
	v_mfma_f32_16x16x32_bf16 v[138:141], v[98:101], v[182:185], v[138:141]
	v_mfma_f32_16x16x32_bf16 v[126:129], v[86:89], v[196:199], v[126:129]
	v_mfma_f32_16x16x32_bf16 v[122:125], v[98:101], v[196:199], v[122:125]
	v_mfma_f32_16x16x32_bf16 v[110:113], v[86:89], v[204:207], v[110:113]
	v_mfma_f32_16x16x32_bf16 v[106:109], v[98:101], v[204:207], v[106:109]
	v_mfma_f32_16x16x32_bf16 v[78:81], v[86:89], v[212:215], v[78:81]
	v_mfma_f32_16x16x32_bf16 v[74:77], v[98:101], v[212:215], v[74:77]
	s_setprio 0
	s_setprio 1
	v_mfma_f32_16x16x32_bf16 v[134:137], v[146:149], v[178:181], v[134:137]
	v_mfma_f32_16x16x32_bf16 v[130:133], v[154:157], v[178:181], v[130:133]
	v_mfma_f32_16x16x32_bf16 v[118:121], v[146:149], v[192:195], v[118:121]
	v_mfma_f32_16x16x32_bf16 v[114:117], v[154:157], v[192:195], v[114:117]
	v_mfma_f32_16x16x32_bf16 v[102:105], v[146:149], v[200:203], v[102:105]
	v_mfma_f32_16x16x32_bf16 v[90:93], v[154:157], v[200:203], v[90:93]
	v_mfma_f32_16x16x32_bf16 v[70:73], v[146:149], v[208:211], v[70:73]
	v_mfma_f32_16x16x32_bf16 v[66:69], v[154:157], v[208:211], v[66:69]
	v_mfma_f32_16x16x32_bf16 v[134:137], v[150:153], v[182:185], v[134:137]
	v_mfma_f32_16x16x32_bf16 v[130:133], v[158:161], v[182:185], v[130:133]
	v_mfma_f32_16x16x32_bf16 v[118:121], v[150:153], v[196:199], v[118:121]
	v_mfma_f32_16x16x32_bf16 v[114:117], v[158:161], v[196:199], v[114:117]
	v_mfma_f32_16x16x32_bf16 v[102:105], v[150:153], v[204:207], v[102:105]
	v_mfma_f32_16x16x32_bf16 v[90:93], v[158:161], v[204:207], v[90:93]
	v_mfma_f32_16x16x32_bf16 v[70:73], v[150:153], v[212:215], v[70:73]
	v_mfma_f32_16x16x32_bf16 v[66:69], v[158:161], v[212:215], v[66:69]
	s_barrier
	s_setprio 0
	s_add_i32 s44, s71, s13
	v_lshl_add_u64 v[216:217], v[216:217], 0, s[26:27]
	s_mov_b32 m0, s44
	ds_read_b128 v[178:181], v190 offset:49152
	ds_read_b128 v[182:185], v190 offset:50176
	ds_read_b128 v[192:195], v190 offset:51200
	ds_read_b128 v[196:199], v190 offset:52224
	ds_read_b128 v[200:203], v190 offset:53248
	ds_read_b128 v[204:207], v190 offset:54272
	ds_read_b128 v[208:211], v190 offset:55296
	ds_read_b128 v[212:215], v190 offset:56320
	global_load_lds_dwordx4 v[216:217], off
	s_add_i32 m0, s44, 0x2000
	s_add_u32 s44, s52, 0x160080
	v_lshl_add_u64 v[216:217], v[218:219], 0, s[26:27]
	s_addc_u32 s45, s53, 0
	s_add_i32 s52, s72, s13
	global_load_lds_dwordx4 v[216:217], off
	v_lshl_add_u64 v[216:217], s[44:45], 0, v[164:165]
	s_mov_b32 m0, s52
	s_nop 0
	global_load_lds_dwordx4 v[216:217], off
	v_lshl_add_u64 v[216:217], s[44:45], 0, v[168:169]
	s_add_i32 m0, s52, 0x2000
	s_nop 0
	global_load_lds_dwordx4 v[216:217], off
	v_lshl_add_u64 v[216:217], v[220:221], 0, s[26:27]
	s_mov_b32 m0, s40
	s_nop 0
	global_load_lds_dwordx4 v[216:217], off
	v_lshl_add_u64 v[216:217], v[222:223], 0, s[26:27]
	s_mov_b32 m0, s41
	s_nop 0
	global_load_lds_dwordx4 v[216:217], off
	s_waitcnt vmcnt(8)
	s_waitcnt lgkmcnt(0)
	s_setprio 1
	s_barrier
	v_mfma_f32_16x16x32_bf16 v[62:65], v[82:85], v[178:181], v[62:65]
	v_mfma_f32_16x16x32_bf16 v[58:61], v[94:97], v[178:181], v[58:61]
	v_mfma_f32_16x16x32_bf16 v[46:49], v[82:85], v[192:195], v[46:49]
	v_mfma_f32_16x16x32_bf16 v[42:45], v[94:97], v[192:195], v[42:45]
	v_mfma_f32_16x16x32_bf16 v[30:33], v[82:85], v[200:203], v[30:33]
	v_mfma_f32_16x16x32_bf16 v[26:29], v[94:97], v[200:203], v[26:29]
	v_mfma_f32_16x16x32_bf16 v[14:17], v[82:85], v[208:211], v[14:17]
	v_mfma_f32_16x16x32_bf16 v[10:13], v[94:97], v[208:211], v[10:13]
	v_mfma_f32_16x16x32_bf16 v[62:65], v[86:89], v[182:185], v[62:65]
	v_mfma_f32_16x16x32_bf16 v[58:61], v[98:101], v[182:185], v[58:61]
	v_mfma_f32_16x16x32_bf16 v[46:49], v[86:89], v[196:199], v[46:49]
	v_mfma_f32_16x16x32_bf16 v[42:45], v[98:101], v[196:199], v[42:45]
	v_mfma_f32_16x16x32_bf16 v[30:33], v[86:89], v[204:207], v[30:33]
	v_mfma_f32_16x16x32_bf16 v[26:29], v[98:101], v[204:207], v[26:29]
	v_mfma_f32_16x16x32_bf16 v[14:17], v[86:89], v[212:215], v[14:17]
	v_mfma_f32_16x16x32_bf16 v[10:13], v[98:101], v[212:215], v[10:13]
	s_setprio 0
	s_setprio 1
	v_mfma_f32_16x16x32_bf16 v[54:57], v[146:149], v[178:181], v[54:57]
	v_mfma_f32_16x16x32_bf16 v[50:53], v[154:157], v[178:181], v[50:53]
	v_mfma_f32_16x16x32_bf16 v[38:41], v[146:149], v[192:195], v[38:41]
	v_mfma_f32_16x16x32_bf16 v[34:37], v[154:157], v[192:195], v[34:37]
	v_mfma_f32_16x16x32_bf16 v[22:25], v[146:149], v[200:203], v[22:25]
	v_mfma_f32_16x16x32_bf16 v[18:21], v[154:157], v[200:203], v[18:21]
	v_mfma_f32_16x16x32_bf16 v[6:9], v[146:149], v[208:211], v[6:9]
	v_mfma_f32_16x16x32_bf16 v[2:5], v[154:157], v[208:211], v[2:5]
	v_mfma_f32_16x16x32_bf16 v[54:57], v[150:153], v[182:185], v[54:57]
	v_mfma_f32_16x16x32_bf16 v[50:53], v[158:161], v[182:185], v[50:53]
	v_mfma_f32_16x16x32_bf16 v[38:41], v[150:153], v[196:199], v[38:41]
	v_mfma_f32_16x16x32_bf16 v[34:37], v[158:161], v[196:199], v[34:37]
	v_mfma_f32_16x16x32_bf16 v[22:25], v[150:153], v[204:207], v[22:25]
	v_mfma_f32_16x16x32_bf16 v[18:21], v[158:161], v[204:207], v[18:21]
	v_mfma_f32_16x16x32_bf16 v[6:9], v[150:153], v[212:215], v[6:9]
	v_mfma_f32_16x16x32_bf16 v[2:5], v[158:161], v[212:215], v[2:5]
	s_barrier
	s_setprio 0
	s_add_i32 s70, s70, 2
	s_add_u32 s68, s68, 0x100
	s_addc_u32 s69, s69, 0
	s_cmpk_gt_u32 s70, 0x55
	s_mov_b64 s[44:45], s[6:7]
	s_cbranch_scc0 .LBB0_266
	s_and_b64 vcc, exec, s[28:29]
	s_cbranch_vccz .LBB0_269
	s_barrier

.LBB0_632:
	ds_read_b128 v[146:149], v162
	ds_read_b128 v[150:153], v162 offset:1024
	ds_read_b128 v[154:157], v162 offset:2048
	ds_read_b128 v[168:171], v162 offset:3072
	ds_read_b128 v[172:175], v163
	ds_read_b128 v[176:179], v163 offset:1024
	ds_read_b128 v[180:183], v163 offset:2048
	ds_read_b128 v[184:187], v163 offset:3072
	s_add_u32 s15, s52, 0xfff80080
	s_addc_u32 s16, s53, -1
	s_cmp_eq_u32 s14, 28
	s_cselect_b32 s57, s7, s16
	s_cselect_b32 s56, s9, s15
	s_cselect_b32 s55, s10, s13
	s_cselect_b32 s54, s11, s12
	v_lshl_add_u64 v[158:159], s[52:53], 0, v[140:141]
	s_add_i32 m0, s39, 0xc000
	ds_read_b128 v[188:191], v164
	ds_read_b128 v[192:195], v164 offset:1024
	ds_read_b128 v[196:199], v164 offset:2048
	ds_read_b128 v[200:203], v164 offset:3072
	ds_read_b128 v[204:207], v164 offset:4096
	ds_read_b128 v[208:211], v164 offset:5120
	ds_read_b128 v[212:215], v164 offset:6144
	ds_read_b128 v[216:219], v164 offset:7168
	global_load_lds_dwordx4 v[158:159], off
	v_lshl_add_u64 v[158:159], s[52:53], 0, v[138:139]
	s_add_i32 m0, s39, 0xe000
	s_nop 0
	global_load_lds_dwordx4 v[158:159], off
	s_waitcnt vmcnt(8)
	s_waitcnt lgkmcnt(0)
	s_setprio 1
	s_barrier
	v_mfma_f32_16x16x32_bf16 v[126:129], v[146:149], v[188:191], v[126:129]
	v_mfma_f32_16x16x32_bf16 v[122:125], v[154:157], v[188:191], v[122:125]
	v_mfma_f32_16x16x32_bf16 v[110:113], v[146:149], v[196:199], v[110:113]
	v_mfma_f32_16x16x32_bf16 v[106:109], v[154:157], v[196:199], v[106:109]
	v_mfma_f32_16x16x32_bf16 v[94:97], v[146:149], v[204:207], v[94:97]
	v_mfma_f32_16x16x32_bf16 v[90:93], v[154:157], v[204:207], v[90:93]
	v_mfma_f32_16x16x32_bf16 v[78:81], v[146:149], v[212:215], v[78:81]
	v_mfma_f32_16x16x32_bf16 v[74:77], v[154:157], v[212:215], v[74:77]
	v_mfma_f32_16x16x32_bf16 v[126:129], v[150:153], v[192:195], v[126:129]
	v_mfma_f32_16x16x32_bf16 v[122:125], v[168:171], v[192:195], v[122:125]
	v_mfma_f32_16x16x32_bf16 v[110:113], v[150:153], v[200:203], v[110:113]
	v_mfma_f32_16x16x32_bf16 v[106:109], v[168:171], v[200:203], v[106:109]
	v_mfma_f32_16x16x32_bf16 v[94:97], v[150:153], v[208:211], v[94:97]
	v_mfma_f32_16x16x32_bf16 v[90:93], v[168:171], v[208:211], v[90:93]
	v_mfma_f32_16x16x32_bf16 v[78:81], v[150:153], v[216:219], v[78:81]
	v_mfma_f32_16x16x32_bf16 v[74:77], v[168:171], v[216:219], v[74:77]
	s_setprio 0
	s_setprio 1
	v_mfma_f32_16x16x32_bf16 v[118:121], v[172:175], v[188:191], v[118:121]
	v_mfma_f32_16x16x32_bf16 v[114:117], v[180:183], v[188:191], v[114:117]
	v_mfma_f32_16x16x32_bf16 v[102:105], v[172:175], v[196:199], v[102:105]
	v_mfma_f32_16x16x32_bf16 v[98:101], v[180:183], v[196:199], v[98:101]
	v_mfma_f32_16x16x32_bf16 v[86:89], v[172:175], v[204:207], v[86:89]
	v_mfma_f32_16x16x32_bf16 v[82:85], v[180:183], v[204:207], v[82:85]
	v_mfma_f32_16x16x32_bf16 v[70:73], v[172:175], v[212:215], v[70:73]
	v_mfma_f32_16x16x32_bf16 v[66:69], v[180:183], v[212:215], v[66:69]
	v_mfma_f32_16x16x32_bf16 v[118:121], v[176:179], v[192:195], v[118:121]
	v_mfma_f32_16x16x32_bf16 v[114:117], v[184:187], v[192:195], v[114:117]
	v_mfma_f32_16x16x32_bf16 v[102:105], v[176:179], v[200:203], v[102:105]
	v_mfma_f32_16x16x32_bf16 v[98:101], v[184:187], v[200:203], v[98:101]
	v_mfma_f32_16x16x32_bf16 v[86:89], v[176:179], v[208:211], v[86:89]
	v_mfma_f32_16x16x32_bf16 v[82:85], v[184:187], v[208:211], v[82:85]
	v_mfma_f32_16x16x32_bf16 v[70:73], v[176:179], v[216:219], v[70:73]
	v_mfma_f32_16x16x32_bf16 v[66:69], v[184:187], v[216:219], v[66:69]
	s_barrier
	s_setprio 0
	s_add_i32 s15, s75, s38
	v_lshl_add_u64 v[158:159], s[54:55], 0, v[132:133]
	s_mov_b32 m0, s15
	ds_read_b128 v[188:191], v164 offset:16384
	ds_read_b128 v[192:195], v164 offset:17408
	ds_read_b128 v[196:199], v164 offset:18432
	ds_read_b128 v[200:203], v164 offset:19456
	ds_read_b128 v[204:207], v164 offset:20480
	ds_read_b128 v[208:211], v164 offset:21504
	ds_read_b128 v[212:215], v164 offset:22528
	ds_read_b128 v[216:219], v164 offset:23552
	global_load_lds_dwordx4 v[158:159], off
	s_add_i32 m0, s15, 0x2000
	s_add_u32 s58, s54, 0x80000
	v_lshl_add_u64 v[220:221], s[54:55], 0, v[136:137]
	s_addc_u32 s59, s55, 0
	s_add_i32 s15, s76, s38
	global_load_lds_dwordx4 v[220:221], off
	v_lshl_add_u64 v[222:223], s[58:59], 0, v[132:133]
	s_mov_b32 m0, s15
	v_lshl_add_u64 v[224:225], s[56:57], 0, v[134:135]
	global_load_lds_dwordx4 v[222:223], off
	v_lshl_add_u64 v[222:223], s[58:59], 0, v[136:137]
	s_add_i32 m0, s15, 0x2000
	s_nop 0
	global_load_lds_dwordx4 v[222:223], off
	v_lshl_add_u64 v[222:223], s[56:57], 0, v[130:131]
	s_mov_b32 m0, s39
	s_nop 0
	global_load_lds_dwordx4 v[222:223], off
	s_mov_b32 m0, s46
	s_nop 0
	global_load_lds_dwordx4 v[224:225], off
	s_waitcnt vmcnt(8)
	s_waitcnt lgkmcnt(0)
	s_setprio 1
	s_barrier
	v_mfma_f32_16x16x32_bf16 v[62:65], v[146:149], v[188:191], v[62:65]
	v_mfma_f32_16x16x32_bf16 v[58:61], v[154:157], v[188:191], v[58:61]
	v_mfma_f32_16x16x32_bf16 v[46:49], v[146:149], v[196:199], v[46:49]
	v_mfma_f32_16x16x32_bf16 v[42:45], v[154:157], v[196:199], v[42:45]
	v_mfma_f32_16x16x32_bf16 v[30:33], v[146:149], v[204:207], v[30:33]
	v_mfma_f32_16x16x32_bf16 v[26:29], v[154:157], v[204:207], v[26:29]
	v_mfma_f32_16x16x32_bf16 v[14:17], v[146:149], v[212:215], v[14:17]
	v_mfma_f32_16x16x32_bf16 v[10:13], v[154:157], v[212:215], v[10:13]
	v_mfma_f32_16x16x32_bf16 v[62:65], v[150:153], v[192:195], v[62:65]
	v_mfma_f32_16x16x32_bf16 v[58:61], v[168:171], v[192:195], v[58:61]
	v_mfma_f32_16x16x32_bf16 v[46:49], v[150:153], v[200:203], v[46:49]
	v_mfma_f32_16x16x32_bf16 v[42:45], v[168:171], v[200:203], v[42:45]
	v_mfma_f32_16x16x32_bf16 v[30:33], v[150:153], v[208:211], v[30:33]
	v_mfma_f32_16x16x32_bf16 v[26:29], v[168:171], v[208:211], v[26:29]
	v_mfma_f32_16x16x32_bf16 v[14:17], v[150:153], v[216:219], v[14:17]
	v_mfma_f32_16x16x32_bf16 v[10:13], v[168:171], v[216:219], v[10:13]
	s_setprio 0
	s_setprio 1
	v_mfma_f32_16x16x32_bf16 v[54:57], v[172:175], v[188:191], v[54:57]
	v_mfma_f32_16x16x32_bf16 v[50:53], v[180:183], v[188:191], v[50:53]
	v_mfma_f32_16x16x32_bf16 v[38:41], v[172:175], v[196:199], v[38:41]
	v_mfma_f32_16x16x32_bf16 v[34:37], v[180:183], v[196:199], v[34:37]
	v_mfma_f32_16x16x32_bf16 v[22:25], v[172:175], v[204:207], v[22:25]
	v_mfma_f32_16x16x32_bf16 v[18:21], v[180:183], v[204:207], v[18:21]
	v_mfma_f32_16x16x32_bf16 v[6:9], v[172:175], v[212:215], v[6:9]
	v_mfma_f32_16x16x32_bf16 v[2:5], v[180:183], v[212:215], v[2:5]
	v_mfma_f32_16x16x32_bf16 v[54:57], v[176:179], v[192:195], v[54:57]
	v_mfma_f32_16x16x32_bf16 v[50:53], v[184:187], v[192:195], v[50:53]
	v_mfma_f32_16x16x32_bf16 v[38:41], v[176:179], v[200:203], v[38:41]
	v_mfma_f32_16x16x32_bf16 v[34:37], v[184:187], v[200:203], v[34:37]
	v_mfma_f32_16x16x32_bf16 v[22:25], v[176:179], v[208:211], v[22:25]
	v_mfma_f32_16x16x32_bf16 v[18:21], v[184:187], v[208:211], v[18:21]
	v_mfma_f32_16x16x32_bf16 v[6:9], v[176:179], v[216:219], v[6:9]
	v_mfma_f32_16x16x32_bf16 v[2:5], v[184:187], v[216:219], v[2:5]
	s_barrier
	s_setprio 0
	s_add_i32 s15, 0, 0x18000
	v_add_u32_e32 v167, s15, v161
	s_add_i32 s16, 0, 0x1c000
	ds_read_b128 v[146:149], v167
	ds_read_b128 v[150:153], v167 offset:1024
	ds_read_b128 v[154:157], v167 offset:2048
	ds_read_b128 v[168:171], v167 offset:3072
	v_add_u32_e32 v167, s16, v161
	ds_read_b128 v[172:175], v167
	ds_read_b128 v[176:179], v167 offset:1024
	ds_read_b128 v[180:183], v167 offset:2048
	ds_read_b128 v[184:187], v167 offset:3072
	s_add_u32 s56, s56, 0x80000
	s_addc_u32 s57, s57, 0
	s_mov_b32 m0, s47
	v_lshl_add_u64 v[226:227], s[56:57], 0, v[130:131]
	ds_read_b128 v[188:191], v164 offset:32768
	ds_read_b128 v[192:195], v164 offset:33792
	ds_read_b128 v[196:199], v164 offset:34816
	ds_read_b128 v[200:203], v164 offset:35840
	ds_read_b128 v[204:207], v164 offset:36864
	ds_read_b128 v[208:211], v164 offset:37888
	ds_read_b128 v[212:215], v164 offset:38912
	ds_read_b128 v[216:219], v164 offset:39936
	global_load_lds_dwordx4 v[226:227], off
	v_lshl_add_u64 v[226:227], s[56:57], 0, v[134:135]
	s_mov_b32 m0, s48
	s_nop 0
	global_load_lds_dwordx4 v[226:227], off
	s_waitcnt vmcnt(8)
	s_waitcnt lgkmcnt(0)
	s_setprio 1
	s_barrier
	v_mfma_f32_16x16x32_bf16 v[126:129], v[146:149], v[188:191], v[126:129]
	v_mfma_f32_16x16x32_bf16 v[122:125], v[154:157], v[188:191], v[122:125]
	v_mfma_f32_16x16x32_bf16 v[110:113], v[146:149], v[196:199], v[110:113]
	v_mfma_f32_16x16x32_bf16 v[106:109], v[154:157], v[196:199], v[106:109]
	v_mfma_f32_16x16x32_bf16 v[94:97], v[146:149], v[204:207], v[94:97]
	v_mfma_f32_16x16x32_bf16 v[90:93], v[154:157], v[204:207], v[90:93]
	v_mfma_f32_16x16x32_bf16 v[78:81], v[146:149], v[212:215], v[78:81]
	v_mfma_f32_16x16x32_bf16 v[74:77], v[154:157], v[212:215], v[74:77]
	v_mfma_f32_16x16x32_bf16 v[126:129], v[150:153], v[192:195], v[126:129]
	v_mfma_f32_16x16x32_bf16 v[122:125], v[168:171], v[192:195], v[122:125]
	v_mfma_f32_16x16x32_bf16 v[110:113], v[150:153], v[200:203], v[110:113]
	v_mfma_f32_16x16x32_bf16 v[106:109], v[168:171], v[200:203], v[106:109]
	v_mfma_f32_16x16x32_bf16 v[94:97], v[150:153], v[208:211], v[94:97]
	v_mfma_f32_16x16x32_bf16 v[90:93], v[168:171], v[208:211], v[90:93]
	v_mfma_f32_16x16x32_bf16 v[78:81], v[150:153], v[216:219], v[78:81]
	v_mfma_f32_16x16x32_bf16 v[74:77], v[168:171], v[216:219], v[74:77]
	s_setprio 0
	s_setprio 1
	v_mfma_f32_16x16x32_bf16 v[118:121], v[172:175], v[188:191], v[118:121]
	v_mfma_f32_16x16x32_bf16 v[114:117], v[180:183], v[188:191], v[114:117]
	v_mfma_f32_16x16x32_bf16 v[102:105], v[172:175], v[196:199], v[102:105]
	v_mfma_f32_16x16x32_bf16 v[98:101], v[180:183], v[196:199], v[98:101]
	v_mfma_f32_16x16x32_bf16 v[86:89], v[172:175], v[204:207], v[86:89]
	v_mfma_f32_16x16x32_bf16 v[82:85], v[180:183], v[204:207], v[82:85]
	v_mfma_f32_16x16x32_bf16 v[70:73], v[172:175], v[212:215], v[70:73]
	v_mfma_f32_16x16x32_bf16 v[66:69], v[180:183], v[212:215], v[66:69]
	v_mfma_f32_16x16x32_bf16 v[118:121], v[176:179], v[192:195], v[118:121]
	v_mfma_f32_16x16x32_bf16 v[114:117], v[184:187], v[192:195], v[114:117]
	v_mfma_f32_16x16x32_bf16 v[102:105], v[176:179], v[200:203], v[102:105]
	v_mfma_f32_16x16x32_bf16 v[98:101], v[184:187], v[200:203], v[98:101]
	v_mfma_f32_16x16x32_bf16 v[86:89], v[176:179], v[208:211], v[86:89]
	v_mfma_f32_16x16x32_bf16 v[82:85], v[184:187], v[208:211], v[82:85]
	v_mfma_f32_16x16x32_bf16 v[70:73], v[176:179], v[216:219], v[70:73]
	v_mfma_f32_16x16x32_bf16 v[66:69], v[184:187], v[216:219], v[66:69]
	s_barrier
	s_setprio 0
	s_add_i32 s15, s15, s38
	v_lshl_add_u64 v[158:159], v[158:159], 0, s[24:25]
	s_mov_b32 m0, s15
	ds_read_b128 v[188:191], v164 offset:49152
	ds_read_b128 v[192:195], v164 offset:50176
	ds_read_b128 v[196:199], v164 offset:51200
	ds_read_b128 v[200:203], v164 offset:52224
	ds_read_b128 v[204:207], v164 offset:53248
	ds_read_b128 v[208:211], v164 offset:54272
	ds_read_b128 v[212:215], v164 offset:55296
	ds_read_b128 v[216:219], v164 offset:56320
	global_load_lds_dwordx4 v[158:159], off
	s_add_i32 m0, s15, 0x2000
	s_add_u32 s54, s54, 0x80080
	v_lshl_add_u64 v[158:159], v[220:221], 0, s[24:25]
	s_addc_u32 s55, s55, 0
	s_add_i32 s15, s16, s38
	global_load_lds_dwordx4 v[158:159], off
	v_lshl_add_u64 v[158:159], s[54:55], 0, v[132:133]
	s_mov_b32 m0, s15
	s_nop 0
	global_load_lds_dwordx4 v[158:159], off
	v_lshl_add_u64 v[158:159], s[54:55], 0, v[136:137]
	s_add_i32 m0, s15, 0x2000
	s_nop 0
	global_load_lds_dwordx4 v[158:159], off
	v_lshl_add_u64 v[158:159], v[222:223], 0, s[24:25]
	s_mov_b32 m0, s71
	s_nop 0
	global_load_lds_dwordx4 v[158:159], off
	v_lshl_add_u64 v[158:159], v[224:225], 0, s[24:25]
	s_mov_b32 m0, s72
	s_nop 0
	global_load_lds_dwordx4 v[158:159], off
	s_waitcnt vmcnt(8)
	s_waitcnt lgkmcnt(0)
	s_setprio 1
	s_barrier
	v_mfma_f32_16x16x32_bf16 v[62:65], v[146:149], v[188:191], v[62:65]
	v_mfma_f32_16x16x32_bf16 v[58:61], v[154:157], v[188:191], v[58:61]
	v_mfma_f32_16x16x32_bf16 v[46:49], v[146:149], v[196:199], v[46:49]
	v_mfma_f32_16x16x32_bf16 v[42:45], v[154:157], v[196:199], v[42:45]
	v_mfma_f32_16x16x32_bf16 v[30:33], v[146:149], v[204:207], v[30:33]
	v_mfma_f32_16x16x32_bf16 v[26:29], v[154:157], v[204:207], v[26:29]
	v_mfma_f32_16x16x32_bf16 v[14:17], v[146:149], v[212:215], v[14:17]
	v_mfma_f32_16x16x32_bf16 v[10:13], v[154:157], v[212:215], v[10:13]
	v_mfma_f32_16x16x32_bf16 v[62:65], v[150:153], v[192:195], v[62:65]
	v_mfma_f32_16x16x32_bf16 v[58:61], v[168:171], v[192:195], v[58:61]
	v_mfma_f32_16x16x32_bf16 v[46:49], v[150:153], v[200:203], v[46:49]
	v_mfma_f32_16x16x32_bf16 v[42:45], v[168:171], v[200:203], v[42:45]
	v_mfma_f32_16x16x32_bf16 v[30:33], v[150:153], v[208:211], v[30:33]
	v_mfma_f32_16x16x32_bf16 v[26:29], v[168:171], v[208:211], v[26:29]
	v_mfma_f32_16x16x32_bf16 v[14:17], v[150:153], v[216:219], v[14:17]
	v_mfma_f32_16x16x32_bf16 v[10:13], v[168:171], v[216:219], v[10:13]
	s_setprio 0
	s_setprio 1
	v_mfma_f32_16x16x32_bf16 v[54:57], v[172:175], v[188:191], v[54:57]
	v_mfma_f32_16x16x32_bf16 v[50:53], v[180:183], v[188:191], v[50:53]
	v_mfma_f32_16x16x32_bf16 v[38:41], v[172:175], v[196:199], v[38:41]
	v_mfma_f32_16x16x32_bf16 v[34:37], v[180:183], v[196:199], v[34:37]
	v_mfma_f32_16x16x32_bf16 v[22:25], v[172:175], v[204:207], v[22:25]
	v_mfma_f32_16x16x32_bf16 v[18:21], v[180:183], v[204:207], v[18:21]
	v_mfma_f32_16x16x32_bf16 v[6:9], v[172:175], v[212:215], v[6:9]
	v_mfma_f32_16x16x32_bf16 v[2:5], v[180:183], v[212:215], v[2:5]
	v_mfma_f32_16x16x32_bf16 v[54:57], v[176:179], v[192:195], v[54:57]
	v_mfma_f32_16x16x32_bf16 v[50:53], v[184:187], v[192:195], v[50:53]
	v_mfma_f32_16x16x32_bf16 v[38:41], v[176:179], v[200:203], v[38:41]
	v_mfma_f32_16x16x32_bf16 v[34:37], v[184:187], v[200:203], v[34:37]
	v_mfma_f32_16x16x32_bf16 v[22:25], v[176:179], v[208:211], v[22:25]
	v_mfma_f32_16x16x32_bf16 v[18:21], v[184:187], v[208:211], v[18:21]
	v_mfma_f32_16x16x32_bf16 v[6:9], v[176:179], v[216:219], v[6:9]
	v_mfma_f32_16x16x32_bf16 v[2:5], v[184:187], v[216:219], v[2:5]
	s_barrier
	s_setprio 0
	s_add_i32 s14, s14, 2
	s_add_u32 s12, s12, 0x100
	s_addc_u32 s13, s13, 0
	s_add_u32 s52, s52, 0x100
	s_addc_u32 s53, s53, 0
	s_cmp_gt_u32 s14, 29
	s_cbranch_scc0 .LBB0_632
	s_and_b64 vcc, exec, s[26:27]
	s_cbranch_vccz .LBB0_635
	s_barrier

.LBB0_1130:
	ds_read_b128 v[86:89], v166
	ds_read_b128 v[90:93], v166 offset:1024
	ds_read_b128 v[98:101], v166 offset:2048
	ds_read_b128 v[106:109], v166 offset:3072
	ds_read_b128 v[170:173], v167
	ds_read_b128 v[174:177], v167 offset:1024
	ds_read_b128 v[178:181], v167 offset:2048
	ds_read_b128 v[182:185], v167 offset:3072
	s_add_u32 s62, s60, 0xfff80080
	s_addc_u32 s63, s61, -1
	s_cmp_eq_u32 s70, 28
	s_cselect_b32 s65, s53, s63
	s_cselect_b32 s64, s66, s62
	s_cselect_b32 s63, s45, s69
	s_cselect_b32 s62, s67, s68
	v_lshl_add_u64 v[162:163], s[60:61], 0, v[156:157]
	s_add_i32 m0, s14, 0xc000
	ds_read_b128 v[186:189], v168
	ds_read_b128 v[190:193], v168 offset:1024
	ds_read_b128 v[194:197], v168 offset:2048
	ds_read_b128 v[198:201], v168 offset:3072
	ds_read_b128 v[202:205], v168 offset:4096
	ds_read_b128 v[206:209], v168 offset:5120
	ds_read_b128 v[210:213], v168 offset:6144
	ds_read_b128 v[214:217], v168 offset:7168
	global_load_lds_dwordx4 v[162:163], off
	v_lshl_add_u64 v[162:163], s[60:61], 0, v[154:155]
	s_add_i32 m0, s14, 0xe000
	s_nop 0
	global_load_lds_dwordx4 v[162:163], off
	s_waitcnt vmcnt(8)
	s_waitcnt lgkmcnt(0)
	s_setprio 1
	s_barrier
	v_mfma_f32_16x16x32_bf16 v[142:145], v[86:89], v[186:189], v[142:145]
	v_mfma_f32_16x16x32_bf16 v[134:137], v[98:101], v[186:189], v[134:137]
	v_mfma_f32_16x16x32_bf16 v[126:129], v[86:89], v[194:197], v[126:129]
	v_mfma_f32_16x16x32_bf16 v[118:121], v[98:101], v[194:197], v[118:121]
	v_mfma_f32_16x16x32_bf16 v[110:113], v[86:89], v[202:205], v[110:113]
	v_mfma_f32_16x16x32_bf16 v[94:97], v[98:101], v[202:205], v[94:97]
	v_mfma_f32_16x16x32_bf16 v[78:81], v[86:89], v[210:213], v[78:81]
	v_mfma_f32_16x16x32_bf16 v[70:73], v[98:101], v[210:213], v[70:73]
	v_mfma_f32_16x16x32_bf16 v[142:145], v[90:93], v[190:193], v[142:145]
	v_mfma_f32_16x16x32_bf16 v[134:137], v[106:109], v[190:193], v[134:137]
	v_mfma_f32_16x16x32_bf16 v[126:129], v[90:93], v[198:201], v[126:129]
	v_mfma_f32_16x16x32_bf16 v[118:121], v[106:109], v[198:201], v[118:121]
	v_mfma_f32_16x16x32_bf16 v[110:113], v[90:93], v[206:209], v[110:113]
	v_mfma_f32_16x16x32_bf16 v[94:97], v[106:109], v[206:209], v[94:97]
	v_mfma_f32_16x16x32_bf16 v[78:81], v[90:93], v[214:217], v[78:81]
	v_mfma_f32_16x16x32_bf16 v[70:73], v[106:109], v[214:217], v[70:73]
	s_setprio 0
	s_setprio 1
	v_mfma_f32_16x16x32_bf16 v[138:141], v[170:173], v[186:189], v[138:141]
	v_mfma_f32_16x16x32_bf16 v[130:133], v[178:181], v[186:189], v[130:133]
	v_mfma_f32_16x16x32_bf16 v[122:125], v[170:173], v[194:197], v[122:125]
	v_mfma_f32_16x16x32_bf16 v[114:117], v[178:181], v[194:197], v[114:117]
	v_mfma_f32_16x16x32_bf16 v[102:105], v[170:173], v[202:205], v[102:105]
	v_mfma_f32_16x16x32_bf16 v[82:85], v[178:181], v[202:205], v[82:85]
	v_mfma_f32_16x16x32_bf16 v[74:77], v[170:173], v[210:213], v[74:77]
	v_mfma_f32_16x16x32_bf16 v[66:69], v[178:181], v[210:213], v[66:69]
	v_mfma_f32_16x16x32_bf16 v[138:141], v[174:177], v[190:193], v[138:141]
	v_mfma_f32_16x16x32_bf16 v[130:133], v[182:185], v[190:193], v[130:133]
	v_mfma_f32_16x16x32_bf16 v[122:125], v[174:177], v[198:201], v[122:125]
	v_mfma_f32_16x16x32_bf16 v[114:117], v[182:185], v[198:201], v[114:117]
	v_mfma_f32_16x16x32_bf16 v[102:105], v[174:177], v[206:209], v[102:105]
	v_mfma_f32_16x16x32_bf16 v[82:85], v[182:185], v[206:209], v[82:85]
	v_mfma_f32_16x16x32_bf16 v[74:77], v[174:177], v[214:217], v[74:77]
	v_mfma_f32_16x16x32_bf16 v[66:69], v[182:185], v[214:217], v[66:69]
	s_barrier
	s_setprio 0
	s_add_i32 s71, s49, s11
	v_lshl_add_u64 v[162:163], s[62:63], 0, v[150:151]
	s_mov_b32 m0, s71
	ds_read_b128 v[186:189], v168 offset:16384
	ds_read_b128 v[190:193], v168 offset:17408
	ds_read_b128 v[194:197], v168 offset:18432
	ds_read_b128 v[198:201], v168 offset:19456
	ds_read_b128 v[202:205], v168 offset:20480
	ds_read_b128 v[206:209], v168 offset:21504
	ds_read_b128 v[210:213], v168 offset:22528
	ds_read_b128 v[214:217], v168 offset:23552
	global_load_lds_dwordx4 v[162:163], off
	s_add_i32 m0, s71, 0x2000
	s_add_u32 s72, s62, 0x80000
	v_lshl_add_u64 v[218:219], s[62:63], 0, v[146:147]
	s_addc_u32 s73, s63, 0
	s_add_i32 s71, s50, s11
	global_load_lds_dwordx4 v[218:219], off
	v_lshl_add_u64 v[220:221], s[72:73], 0, v[150:151]
	s_mov_b32 m0, s71
	v_lshl_add_u64 v[222:223], s[64:65], 0, v[148:149]
	global_load_lds_dwordx4 v[220:221], off
	v_lshl_add_u64 v[220:221], s[72:73], 0, v[146:147]
	s_add_i32 m0, s71, 0x2000
	s_nop 0
	global_load_lds_dwordx4 v[220:221], off
	v_lshl_add_u64 v[220:221], s[64:65], 0, v[152:153]
	s_mov_b32 m0, s14
	s_nop 0
	global_load_lds_dwordx4 v[220:221], off
	s_mov_b32 m0, s15
	s_nop 0
	global_load_lds_dwordx4 v[222:223], off
	s_waitcnt vmcnt(8)
	s_waitcnt lgkmcnt(0)
	s_setprio 1
	s_barrier
	v_mfma_f32_16x16x32_bf16 v[62:65], v[86:89], v[186:189], v[62:65]
	v_mfma_f32_16x16x32_bf16 v[54:57], v[98:101], v[186:189], v[54:57]
	v_mfma_f32_16x16x32_bf16 v[46:49], v[86:89], v[194:197], v[46:49]
	v_mfma_f32_16x16x32_bf16 v[38:41], v[98:101], v[194:197], v[38:41]
	v_mfma_f32_16x16x32_bf16 v[30:33], v[86:89], v[202:205], v[30:33]
	v_mfma_f32_16x16x32_bf16 v[22:25], v[98:101], v[202:205], v[22:25]
	v_mfma_f32_16x16x32_bf16 v[14:17], v[86:89], v[210:213], v[14:17]
	v_mfma_f32_16x16x32_bf16 v[6:9], v[98:101], v[210:213], v[6:9]
	v_mfma_f32_16x16x32_bf16 v[62:65], v[90:93], v[190:193], v[62:65]
	v_mfma_f32_16x16x32_bf16 v[54:57], v[106:109], v[190:193], v[54:57]
	v_mfma_f32_16x16x32_bf16 v[46:49], v[90:93], v[198:201], v[46:49]
	v_mfma_f32_16x16x32_bf16 v[38:41], v[106:109], v[198:201], v[38:41]
	v_mfma_f32_16x16x32_bf16 v[30:33], v[90:93], v[206:209], v[30:33]
	v_mfma_f32_16x16x32_bf16 v[22:25], v[106:109], v[206:209], v[22:25]
	v_mfma_f32_16x16x32_bf16 v[14:17], v[90:93], v[214:217], v[14:17]
	v_mfma_f32_16x16x32_bf16 v[6:9], v[106:109], v[214:217], v[6:9]
	s_setprio 0
	s_setprio 1
	v_mfma_f32_16x16x32_bf16 v[58:61], v[170:173], v[186:189], v[58:61]
	v_mfma_f32_16x16x32_bf16 v[50:53], v[178:181], v[186:189], v[50:53]
	v_mfma_f32_16x16x32_bf16 v[42:45], v[170:173], v[194:197], v[42:45]
	v_mfma_f32_16x16x32_bf16 v[34:37], v[178:181], v[194:197], v[34:37]
	v_mfma_f32_16x16x32_bf16 v[26:29], v[170:173], v[202:205], v[26:29]
	v_mfma_f32_16x16x32_bf16 v[18:21], v[178:181], v[202:205], v[18:21]
	v_mfma_f32_16x16x32_bf16 v[10:13], v[170:173], v[210:213], v[10:13]
	v_mfma_f32_16x16x32_bf16 v[2:5], v[178:181], v[210:213], v[2:5]
	v_mfma_f32_16x16x32_bf16 v[58:61], v[174:177], v[190:193], v[58:61]
	v_mfma_f32_16x16x32_bf16 v[50:53], v[182:185], v[190:193], v[50:53]
	v_mfma_f32_16x16x32_bf16 v[42:45], v[174:177], v[198:201], v[42:45]
	v_mfma_f32_16x16x32_bf16 v[34:37], v[182:185], v[198:201], v[34:37]
	v_mfma_f32_16x16x32_bf16 v[26:29], v[174:177], v[206:209], v[26:29]
	v_mfma_f32_16x16x32_bf16 v[18:21], v[182:185], v[206:209], v[18:21]
	v_mfma_f32_16x16x32_bf16 v[10:13], v[174:177], v[214:217], v[10:13]
	v_mfma_f32_16x16x32_bf16 v[2:5], v[182:185], v[214:217], v[2:5]
	s_barrier
	s_setprio 0
	s_add_i32 s71, 0, 0x18000
	s_add_i32 s72, 0, 0x1c000
	v_add_u32_e32 v106, s71, v165
	v_add_u32_e32 v182, s72, v165
	ds_read_b128 v[86:89], v106
	ds_read_b128 v[90:93], v106 offset:1024
	ds_read_b128 v[98:101], v106 offset:2048
	ds_read_b128 v[106:109], v106 offset:3072
	ds_read_b128 v[170:173], v182
	ds_read_b128 v[174:177], v182 offset:1024
	ds_read_b128 v[178:181], v182 offset:2048
	ds_read_b128 v[182:185], v182 offset:3072
	s_add_u32 s64, s64, 0x80000
	s_addc_u32 s65, s65, 0
	s_mov_b32 m0, s33
	v_lshl_add_u64 v[224:225], s[64:65], 0, v[152:153]
	ds_read_b128 v[186:189], v168 offset:32768
	ds_read_b128 v[190:193], v168 offset:33792
	ds_read_b128 v[194:197], v168 offset:34816
	ds_read_b128 v[198:201], v168 offset:35840
	ds_read_b128 v[202:205], v168 offset:36864
	ds_read_b128 v[206:209], v168 offset:37888
	ds_read_b128 v[210:213], v168 offset:38912
	ds_read_b128 v[214:217], v168 offset:39936
	global_load_lds_dwordx4 v[224:225], off
	v_lshl_add_u64 v[224:225], s[64:65], 0, v[148:149]
	s_mov_b32 m0, s34
	s_nop 0
	global_load_lds_dwordx4 v[224:225], off
	s_waitcnt vmcnt(8)
	s_waitcnt lgkmcnt(0)
	s_setprio 1
	s_barrier
	v_mfma_f32_16x16x32_bf16 v[142:145], v[86:89], v[186:189], v[142:145]
	v_mfma_f32_16x16x32_bf16 v[134:137], v[98:101], v[186:189], v[134:137]
	v_mfma_f32_16x16x32_bf16 v[126:129], v[86:89], v[194:197], v[126:129]
	v_mfma_f32_16x16x32_bf16 v[118:121], v[98:101], v[194:197], v[118:121]
	v_mfma_f32_16x16x32_bf16 v[110:113], v[86:89], v[202:205], v[110:113]
	v_mfma_f32_16x16x32_bf16 v[94:97], v[98:101], v[202:205], v[94:97]
	v_mfma_f32_16x16x32_bf16 v[78:81], v[86:89], v[210:213], v[78:81]
	v_mfma_f32_16x16x32_bf16 v[70:73], v[98:101], v[210:213], v[70:73]
	v_mfma_f32_16x16x32_bf16 v[142:145], v[90:93], v[190:193], v[142:145]
	v_mfma_f32_16x16x32_bf16 v[134:137], v[106:109], v[190:193], v[134:137]
	v_mfma_f32_16x16x32_bf16 v[126:129], v[90:93], v[198:201], v[126:129]
	v_mfma_f32_16x16x32_bf16 v[118:121], v[106:109], v[198:201], v[118:121]
	v_mfma_f32_16x16x32_bf16 v[110:113], v[90:93], v[206:209], v[110:113]
	v_mfma_f32_16x16x32_bf16 v[94:97], v[106:109], v[206:209], v[94:97]
	v_mfma_f32_16x16x32_bf16 v[78:81], v[90:93], v[214:217], v[78:81]
	v_mfma_f32_16x16x32_bf16 v[70:73], v[106:109], v[214:217], v[70:73]
	s_setprio 0
	s_setprio 1
	v_mfma_f32_16x16x32_bf16 v[138:141], v[170:173], v[186:189], v[138:141]
	v_mfma_f32_16x16x32_bf16 v[130:133], v[178:181], v[186:189], v[130:133]
	v_mfma_f32_16x16x32_bf16 v[122:125], v[170:173], v[194:197], v[122:125]
	v_mfma_f32_16x16x32_bf16 v[114:117], v[178:181], v[194:197], v[114:117]
	v_mfma_f32_16x16x32_bf16 v[102:105], v[170:173], v[202:205], v[102:105]
	v_mfma_f32_16x16x32_bf16 v[82:85], v[178:181], v[202:205], v[82:85]
	v_mfma_f32_16x16x32_bf16 v[74:77], v[170:173], v[210:213], v[74:77]
	v_mfma_f32_16x16x32_bf16 v[66:69], v[178:181], v[210:213], v[66:69]
	v_mfma_f32_16x16x32_bf16 v[138:141], v[174:177], v[190:193], v[138:141]
	v_mfma_f32_16x16x32_bf16 v[130:133], v[182:185], v[190:193], v[130:133]
	v_mfma_f32_16x16x32_bf16 v[122:125], v[174:177], v[198:201], v[122:125]
	v_mfma_f32_16x16x32_bf16 v[114:117], v[182:185], v[198:201], v[114:117]
	v_mfma_f32_16x16x32_bf16 v[102:105], v[174:177], v[206:209], v[102:105]
	v_mfma_f32_16x16x32_bf16 v[82:85], v[182:185], v[206:209], v[82:85]
	v_mfma_f32_16x16x32_bf16 v[74:77], v[174:177], v[214:217], v[74:77]
	v_mfma_f32_16x16x32_bf16 v[66:69], v[182:185], v[214:217], v[66:69]
	s_barrier
	s_setprio 0
	s_add_i32 s64, s71, s11
	v_lshl_add_u64 v[162:163], v[162:163], 0, s[22:23]
	s_mov_b32 m0, s64
	ds_read_b128 v[186:189], v168 offset:49152
	ds_read_b128 v[190:193], v168 offset:50176
	ds_read_b128 v[194:197], v168 offset:51200
	ds_read_b128 v[198:201], v168 offset:52224
	ds_read_b128 v[202:205], v168 offset:53248
	ds_read_b128 v[206:209], v168 offset:54272
	ds_read_b128 v[210:213], v168 offset:55296
	ds_read_b128 v[214:217], v168 offset:56320
	global_load_lds_dwordx4 v[162:163], off
	s_add_i32 m0, s64, 0x2000
	s_add_u32 s62, s62, 0x80080
	v_lshl_add_u64 v[162:163], v[218:219], 0, s[22:23]
	s_addc_u32 s63, s63, 0
	s_add_i32 s64, s72, s11
	global_load_lds_dwordx4 v[162:163], off
	v_lshl_add_u64 v[162:163], s[62:63], 0, v[150:151]
	s_mov_b32 m0, s64
	s_nop 0
	global_load_lds_dwordx4 v[162:163], off
	v_lshl_add_u64 v[162:163], s[62:63], 0, v[146:147]
	s_add_i32 m0, s64, 0x2000
	s_nop 0
	global_load_lds_dwordx4 v[162:163], off
	v_lshl_add_u64 v[162:163], v[220:221], 0, s[22:23]
	s_mov_b32 m0, s39
	s_nop 0
	global_load_lds_dwordx4 v[162:163], off
	v_lshl_add_u64 v[162:163], v[222:223], 0, s[22:23]
	s_mov_b32 m0, s46
	s_nop 0
	global_load_lds_dwordx4 v[162:163], off
	s_waitcnt vmcnt(8)
	s_waitcnt lgkmcnt(0)
	s_setprio 1
	s_barrier
	v_mfma_f32_16x16x32_bf16 v[62:65], v[86:89], v[186:189], v[62:65]
	v_mfma_f32_16x16x32_bf16 v[54:57], v[98:101], v[186:189], v[54:57]
	v_mfma_f32_16x16x32_bf16 v[46:49], v[86:89], v[194:197], v[46:49]
	v_mfma_f32_16x16x32_bf16 v[38:41], v[98:101], v[194:197], v[38:41]
	v_mfma_f32_16x16x32_bf16 v[30:33], v[86:89], v[202:205], v[30:33]
	v_mfma_f32_16x16x32_bf16 v[22:25], v[98:101], v[202:205], v[22:25]
	v_mfma_f32_16x16x32_bf16 v[14:17], v[86:89], v[210:213], v[14:17]
	v_mfma_f32_16x16x32_bf16 v[6:9], v[98:101], v[210:213], v[6:9]
	v_mfma_f32_16x16x32_bf16 v[62:65], v[90:93], v[190:193], v[62:65]
	v_mfma_f32_16x16x32_bf16 v[54:57], v[106:109], v[190:193], v[54:57]
	v_mfma_f32_16x16x32_bf16 v[46:49], v[90:93], v[198:201], v[46:49]
	v_mfma_f32_16x16x32_bf16 v[38:41], v[106:109], v[198:201], v[38:41]
	v_mfma_f32_16x16x32_bf16 v[30:33], v[90:93], v[206:209], v[30:33]
	v_mfma_f32_16x16x32_bf16 v[22:25], v[106:109], v[206:209], v[22:25]
	v_mfma_f32_16x16x32_bf16 v[14:17], v[90:93], v[214:217], v[14:17]
	v_mfma_f32_16x16x32_bf16 v[6:9], v[106:109], v[214:217], v[6:9]
	s_setprio 0
	s_setprio 1
	v_mfma_f32_16x16x32_bf16 v[58:61], v[170:173], v[186:189], v[58:61]
	v_mfma_f32_16x16x32_bf16 v[50:53], v[178:181], v[186:189], v[50:53]
	v_mfma_f32_16x16x32_bf16 v[42:45], v[170:173], v[194:197], v[42:45]
	v_mfma_f32_16x16x32_bf16 v[34:37], v[178:181], v[194:197], v[34:37]
	v_mfma_f32_16x16x32_bf16 v[26:29], v[170:173], v[202:205], v[26:29]
	v_mfma_f32_16x16x32_bf16 v[18:21], v[178:181], v[202:205], v[18:21]
	v_mfma_f32_16x16x32_bf16 v[10:13], v[170:173], v[210:213], v[10:13]
	v_mfma_f32_16x16x32_bf16 v[2:5], v[178:181], v[210:213], v[2:5]
	v_mfma_f32_16x16x32_bf16 v[58:61], v[174:177], v[190:193], v[58:61]
	v_mfma_f32_16x16x32_bf16 v[50:53], v[182:185], v[190:193], v[50:53]
	v_mfma_f32_16x16x32_bf16 v[42:45], v[174:177], v[198:201], v[42:45]
	v_mfma_f32_16x16x32_bf16 v[34:37], v[182:185], v[198:201], v[34:37]
	v_mfma_f32_16x16x32_bf16 v[26:29], v[174:177], v[206:209], v[26:29]
	v_mfma_f32_16x16x32_bf16 v[18:21], v[182:185], v[206:209], v[18:21]
	v_mfma_f32_16x16x32_bf16 v[10:13], v[174:177], v[214:217], v[10:13]
	v_mfma_f32_16x16x32_bf16 v[2:5], v[182:185], v[214:217], v[2:5]
	s_barrier
	s_setprio 0
	s_add_i32 s70, s70, 2
	s_add_u32 s68, s68, 0x100
	s_addc_u32 s69, s69, 0
	s_add_u32 s60, s60, 0x100
	s_addc_u32 s61, s61, 0
	s_cmp_gt_u32 s70, 29
	s_cbranch_scc0 .LBB0_1130
	s_and_b64 vcc, exec, s[24:25]
	s_cbranch_vccz .LBB0_1133
	s_barrier

.LBB0_1201:
	s_add_u32 s62, s58, s60
	s_addc_u32 s63, s59, s61
	s_add_u32 s62, s62, 0x100
	s_addc_u32 s63, s63, 0
	s_add_u32 s71, s68, s60
	s_addc_u32 s72, s69, s61
	s_cmpk_eq_i32 s60, 0xf00
	s_cselect_b32 s65, s50, s63
	s_cselect_b32 s64, s51, s62
	s_cselect_b32 s63, s66, s72
	s_cselect_b32 s62, s67, s71
	s_add_i32 s71, 0, 0x10000
	v_add_u32_e32 v3, s71, v171
	ds_read_b128 v[134:137], v3
	ds_read_b128 v[138:141], v3 offset:1024
	ds_read_b128 v[142:145], v3 offset:2048
	ds_read_b128 v[146:149], v3 offset:3072
	v_add_u32_e32 v3, s49, v171
	ds_read_b128 v[174:177], v3
	ds_read_b128 v[178:181], v3 offset:1024
	ds_read_b128 v[182:185], v3 offset:2048
	ds_read_b128 v[186:189], v3 offset:3072
	v_lshl_add_u64 v[4:5], v[168:169], 0, s[60:61]
	s_add_i32 m0, s14, 0xc000
	ds_read_b128 v[190:193], v172
	ds_read_b128 v[194:197], v172 offset:1024
	ds_read_b128 v[198:201], v172 offset:2048
	ds_read_b128 v[202:205], v172 offset:3072
	ds_read_b128 v[206:209], v172 offset:4096
	ds_read_b128 v[210:213], v172 offset:5120
	ds_read_b128 v[214:217], v172 offset:6144
	ds_read_b128 v[218:221], v172 offset:7168
	global_load_lds_dwordx4 v[4:5], off
	v_lshl_add_u64 v[4:5], v[166:167], 0, s[60:61]
	s_add_i32 m0, s14, 0xe000
	s_nop 0
	global_load_lds_dwordx4 v[4:5], off
	s_waitcnt vmcnt(8)
	s_waitcnt lgkmcnt(0)
	s_setprio 1
	s_barrier
	v_mfma_f32_16x16x32_bf16 v[130:133], v[134:137], v[190:193], v[130:133]
	v_mfma_f32_16x16x32_bf16 v[126:129], v[142:145], v[190:193], v[126:129]
	v_mfma_f32_16x16x32_bf16 v[122:125], v[134:137], v[198:201], v[122:125]
	v_mfma_f32_16x16x32_bf16 v[114:117], v[142:145], v[198:201], v[114:117]
	v_mfma_f32_16x16x32_bf16 v[98:101], v[134:137], v[206:209], v[98:101]
	v_mfma_f32_16x16x32_bf16 v[94:97], v[142:145], v[206:209], v[94:97]
	v_mfma_f32_16x16x32_bf16 v[82:85], v[134:137], v[214:217], v[82:85]
	v_mfma_f32_16x16x32_bf16 v[78:81], v[142:145], v[214:217], v[78:81]
	v_mfma_f32_16x16x32_bf16 v[130:133], v[138:141], v[194:197], v[130:133]
	v_mfma_f32_16x16x32_bf16 v[126:129], v[146:149], v[194:197], v[126:129]
	v_mfma_f32_16x16x32_bf16 v[122:125], v[138:141], v[202:205], v[122:125]
	v_mfma_f32_16x16x32_bf16 v[114:117], v[146:149], v[202:205], v[114:117]
	v_mfma_f32_16x16x32_bf16 v[98:101], v[138:141], v[210:213], v[98:101]
	v_mfma_f32_16x16x32_bf16 v[94:97], v[146:149], v[210:213], v[94:97]
	v_mfma_f32_16x16x32_bf16 v[82:85], v[138:141], v[218:221], v[82:85]
	v_mfma_f32_16x16x32_bf16 v[78:81], v[146:149], v[218:221], v[78:81]
	s_setprio 0
	s_setprio 1
	v_mfma_f32_16x16x32_bf16 v[118:121], v[174:177], v[190:193], v[118:121]
	v_mfma_f32_16x16x32_bf16 v[110:113], v[182:185], v[190:193], v[110:113]
	v_mfma_f32_16x16x32_bf16 v[106:109], v[174:177], v[198:201], v[106:109]
	v_mfma_f32_16x16x32_bf16 v[102:105], v[182:185], v[198:201], v[102:105]
	v_mfma_f32_16x16x32_bf16 v[90:93], v[174:177], v[206:209], v[90:93]
	v_mfma_f32_16x16x32_bf16 v[86:89], v[182:185], v[206:209], v[86:89]
	v_mfma_f32_16x16x32_bf16 v[74:77], v[174:177], v[214:217], v[74:77]
	v_mfma_f32_16x16x32_bf16 v[70:73], v[182:185], v[214:217], v[70:73]
	v_mfma_f32_16x16x32_bf16 v[118:121], v[178:181], v[194:197], v[118:121]
	v_mfma_f32_16x16x32_bf16 v[110:113], v[186:189], v[194:197], v[110:113]
	v_mfma_f32_16x16x32_bf16 v[106:109], v[178:181], v[202:205], v[106:109]
	v_mfma_f32_16x16x32_bf16 v[102:105], v[186:189], v[202:205], v[102:105]
	v_mfma_f32_16x16x32_bf16 v[90:93], v[178:181], v[210:213], v[90:93]
	v_mfma_f32_16x16x32_bf16 v[86:89], v[186:189], v[210:213], v[86:89]
	v_mfma_f32_16x16x32_bf16 v[74:77], v[178:181], v[218:221], v[74:77]
	v_mfma_f32_16x16x32_bf16 v[70:73], v[186:189], v[218:221], v[70:73]
	s_barrier
	s_setprio 0
	s_add_i32 s71, s71, s11
	v_lshl_add_u64 v[222:223], s[62:63], 0, v[154:155]
	s_mov_b32 m0, s71
	ds_read_b128 v[190:193], v172 offset:16384
	ds_read_b128 v[194:197], v172 offset:17408
	ds_read_b128 v[198:201], v172 offset:18432
	ds_read_b128 v[202:205], v172 offset:19456
	ds_read_b128 v[206:209], v172 offset:20480
	ds_read_b128 v[210:213], v172 offset:21504
	ds_read_b128 v[214:217], v172 offset:22528
	ds_read_b128 v[218:221], v172 offset:23552
	global_load_lds_dwordx4 v[222:223], off
	s_add_i32 m0, s71, 0x2000
	s_add_u32 s72, s62, 0x80000
	v_lshl_add_u64 v[224:225], s[62:63], 0, v[150:151]
	s_addc_u32 s73, s63, 0
	s_add_i32 s71, s49, s11
	global_load_lds_dwordx4 v[224:225], off
	v_lshl_add_u64 v[4:5], s[72:73], 0, v[154:155]
	s_mov_b32 m0, s71
	v_lshl_add_u64 v[226:227], s[64:65], 0, v[156:157]
	global_load_lds_dwordx4 v[4:5], off
	v_lshl_add_u64 v[4:5], s[72:73], 0, v[150:151]
	s_add_i32 m0, s71, 0x2000
	v_lshl_add_u64 v[228:229], s[64:65], 0, v[152:153]
	global_load_lds_dwordx4 v[4:5], off
	s_mov_b32 m0, s14
	s_nop 0
	global_load_lds_dwordx4 v[226:227], off
	s_mov_b32 m0, s15
	s_nop 0
	global_load_lds_dwordx4 v[228:229], off
	s_waitcnt vmcnt(8)
	s_waitcnt lgkmcnt(0)
	s_setprio 1
	s_barrier
	v_mfma_f32_16x16x32_bf16 v[66:69], v[134:137], v[190:193], v[66:69]
	v_mfma_f32_16x16x32_bf16 v[62:65], v[142:145], v[190:193], v[62:65]
	v_mfma_f32_16x16x32_bf16 v[50:53], v[134:137], v[198:201], v[50:53]
	v_mfma_f32_16x16x32_bf16 v[46:49], v[142:145], v[198:201], v[46:49]
	v_mfma_f32_16x16x32_bf16 v[34:37], v[134:137], v[206:209], v[34:37]
	v_mfma_f32_16x16x32_bf16 v[30:33], v[142:145], v[206:209], v[30:33]
	v_mfma_f32_16x16x32_bf16 v[18:21], v[134:137], v[214:217], v[18:21]
	v_mfma_f32_16x16x32_bf16 v[14:17], v[142:145], v[214:217], v[14:17]
	v_mfma_f32_16x16x32_bf16 v[66:69], v[138:141], v[194:197], v[66:69]
	v_mfma_f32_16x16x32_bf16 v[62:65], v[146:149], v[194:197], v[62:65]
	v_mfma_f32_16x16x32_bf16 v[50:53], v[138:141], v[202:205], v[50:53]
	v_mfma_f32_16x16x32_bf16 v[46:49], v[146:149], v[202:205], v[46:49]
	v_mfma_f32_16x16x32_bf16 v[34:37], v[138:141], v[210:213], v[34:37]
	v_mfma_f32_16x16x32_bf16 v[30:33], v[146:149], v[210:213], v[30:33]
	v_mfma_f32_16x16x32_bf16 v[18:21], v[138:141], v[218:221], v[18:21]
	v_mfma_f32_16x16x32_bf16 v[14:17], v[146:149], v[218:221], v[14:17]
	s_setprio 0
	s_setprio 1
	v_mfma_f32_16x16x32_bf16 v[58:61], v[174:177], v[190:193], v[58:61]
	v_mfma_f32_16x16x32_bf16 v[54:57], v[182:185], v[190:193], v[54:57]
	v_mfma_f32_16x16x32_bf16 v[42:45], v[174:177], v[198:201], v[42:45]
	v_mfma_f32_16x16x32_bf16 v[38:41], v[182:185], v[198:201], v[38:41]
	v_mfma_f32_16x16x32_bf16 v[26:29], v[174:177], v[206:209], v[26:29]
	v_mfma_f32_16x16x32_bf16 v[22:25], v[182:185], v[206:209], v[22:25]
	v_mfma_f32_16x16x32_bf16 v[10:13], v[174:177], v[214:217], v[10:13]
	v_mfma_f32_16x16x32_bf16 v[4:7], v[182:185], v[214:217], v[6:9]
	v_mfma_f32_16x16x32_bf16 v[58:61], v[178:181], v[194:197], v[58:61]
	v_mfma_f32_16x16x32_bf16 v[54:57], v[186:189], v[194:197], v[54:57]
	v_mfma_f32_16x16x32_bf16 v[42:45], v[178:181], v[202:205], v[42:45]
	v_mfma_f32_16x16x32_bf16 v[38:41], v[186:189], v[202:205], v[38:41]
	v_mfma_f32_16x16x32_bf16 v[26:29], v[178:181], v[210:213], v[26:29]
	v_mfma_f32_16x16x32_bf16 v[22:25], v[186:189], v[210:213], v[22:25]
	v_mfma_f32_16x16x32_bf16 v[10:13], v[178:181], v[218:221], v[10:13]
	v_mfma_f32_16x16x32_bf16 v[4:7], v[186:189], v[218:221], v[4:7]
	s_barrier
	s_setprio 0
	s_add_i32 s71, 0, 0x18000
	v_add_u32_e32 v3, s71, v171
	s_add_i32 s72, 0, 0x1c000
	ds_read_b128 v[134:137], v3
	ds_read_b128 v[138:141], v3 offset:1024
	ds_read_b128 v[142:145], v3 offset:2048
	ds_read_b128 v[146:149], v3 offset:3072
	v_add_u32_e32 v3, s72, v171
	ds_read_b128 v[174:177], v3
	ds_read_b128 v[178:181], v3 offset:1024
	ds_read_b128 v[182:185], v3 offset:2048
	ds_read_b128 v[186:189], v3 offset:3072
	s_add_u32 s64, s64, 0x80000
	s_addc_u32 s65, s65, 0
	s_mov_b32 m0, s33
	v_lshl_add_u64 v[8:9], s[64:65], 0, v[156:157]
	ds_read_b128 v[190:193], v172 offset:32768
	ds_read_b128 v[194:197], v172 offset:33792
	ds_read_b128 v[198:201], v172 offset:34816
	ds_read_b128 v[202:205], v172 offset:35840
	ds_read_b128 v[206:209], v172 offset:36864
	ds_read_b128 v[210:213], v172 offset:37888
	ds_read_b128 v[214:217], v172 offset:38912
	ds_read_b128 v[218:221], v172 offset:39936
	global_load_lds_dwordx4 v[8:9], off
	v_lshl_add_u64 v[8:9], s[64:65], 0, v[152:153]
	s_mov_b32 m0, s34
	s_nop 0
	global_load_lds_dwordx4 v[8:9], off
	s_waitcnt vmcnt(8)
	s_waitcnt lgkmcnt(0)
	s_setprio 1
	s_barrier
	v_mfma_f32_16x16x32_bf16 v[130:133], v[134:137], v[190:193], v[130:133]
	v_mfma_f32_16x16x32_bf16 v[126:129], v[142:145], v[190:193], v[126:129]
	v_mfma_f32_16x16x32_bf16 v[122:125], v[134:137], v[198:201], v[122:125]
	v_mfma_f32_16x16x32_bf16 v[114:117], v[142:145], v[198:201], v[114:117]
	v_mfma_f32_16x16x32_bf16 v[98:101], v[134:137], v[206:209], v[98:101]
	v_mfma_f32_16x16x32_bf16 v[94:97], v[142:145], v[206:209], v[94:97]
	v_mfma_f32_16x16x32_bf16 v[82:85], v[134:137], v[214:217], v[82:85]
	v_mfma_f32_16x16x32_bf16 v[78:81], v[142:145], v[214:217], v[78:81]
	v_mfma_f32_16x16x32_bf16 v[130:133], v[138:141], v[194:197], v[130:133]
	v_mfma_f32_16x16x32_bf16 v[126:129], v[146:149], v[194:197], v[126:129]
	v_mfma_f32_16x16x32_bf16 v[122:125], v[138:141], v[202:205], v[122:125]
	v_mfma_f32_16x16x32_bf16 v[114:117], v[146:149], v[202:205], v[114:117]
	v_mfma_f32_16x16x32_bf16 v[98:101], v[138:141], v[210:213], v[98:101]
	v_mfma_f32_16x16x32_bf16 v[94:97], v[146:149], v[210:213], v[94:97]
	v_mfma_f32_16x16x32_bf16 v[82:85], v[138:141], v[218:221], v[82:85]
	v_mfma_f32_16x16x32_bf16 v[78:81], v[146:149], v[218:221], v[78:81]
	s_setprio 0
	s_setprio 1
	v_mfma_f32_16x16x32_bf16 v[118:121], v[174:177], v[190:193], v[118:121]
	v_mfma_f32_16x16x32_bf16 v[110:113], v[182:185], v[190:193], v[110:113]
	v_mfma_f32_16x16x32_bf16 v[106:109], v[174:177], v[198:201], v[106:109]
	v_mfma_f32_16x16x32_bf16 v[102:105], v[182:185], v[198:201], v[102:105]
	v_mfma_f32_16x16x32_bf16 v[90:93], v[174:177], v[206:209], v[90:93]
	v_mfma_f32_16x16x32_bf16 v[86:89], v[182:185], v[206:209], v[86:89]
	v_mfma_f32_16x16x32_bf16 v[74:77], v[174:177], v[214:217], v[74:77]
	v_mfma_f32_16x16x32_bf16 v[70:73], v[182:185], v[214:217], v[70:73]
	v_mfma_f32_16x16x32_bf16 v[118:121], v[178:181], v[194:197], v[118:121]
	v_mfma_f32_16x16x32_bf16 v[110:113], v[186:189], v[194:197], v[110:113]
	v_mfma_f32_16x16x32_bf16 v[106:109], v[178:181], v[202:205], v[106:109]
	v_mfma_f32_16x16x32_bf16 v[102:105], v[186:189], v[202:205], v[102:105]
	v_mfma_f32_16x16x32_bf16 v[90:93], v[178:181], v[210:213], v[90:93]
	v_mfma_f32_16x16x32_bf16 v[86:89], v[186:189], v[210:213], v[86:89]
	v_mfma_f32_16x16x32_bf16 v[74:77], v[178:181], v[218:221], v[74:77]
	v_mfma_f32_16x16x32_bf16 v[70:73], v[186:189], v[218:221], v[70:73]
	s_barrier
	s_setprio 0
	s_add_i32 s64, s71, s11
	v_lshl_add_u64 v[8:9], v[222:223], 0, s[22:23]
	s_mov_b32 m0, s64
	ds_read_b128 v[190:193], v172 offset:49152
	ds_read_b128 v[194:197], v172 offset:50176
	ds_read_b128 v[198:201], v172 offset:51200
	ds_read_b128 v[202:205], v172 offset:52224
	ds_read_b128 v[206:209], v172 offset:53248
	ds_read_b128 v[210:213], v172 offset:54272
	ds_read_b128 v[214:217], v172 offset:55296
	ds_read_b128 v[218:221], v172 offset:56320
	global_load_lds_dwordx4 v[8:9], off
	s_add_i32 m0, s64, 0x2000
	s_add_u32 s62, s62, 0x80080
	v_lshl_add_u64 v[8:9], v[224:225], 0, s[22:23]
	s_addc_u32 s63, s63, 0
	s_add_i32 s64, s72, s11
	global_load_lds_dwordx4 v[8:9], off
	v_lshl_add_u64 v[8:9], s[62:63], 0, v[154:155]
	s_mov_b32 m0, s64
	s_nop 0
	global_load_lds_dwordx4 v[8:9], off
	v_lshl_add_u64 v[8:9], s[62:63], 0, v[150:151]
	s_add_i32 m0, s64, 0x2000
	s_nop 0
	global_load_lds_dwordx4 v[8:9], off
	v_lshl_add_u64 v[8:9], v[226:227], 0, s[22:23]
	s_mov_b32 m0, s39
	s_nop 0
	global_load_lds_dwordx4 v[8:9], off
	v_lshl_add_u64 v[8:9], v[228:229], 0, s[22:23]
	s_mov_b32 m0, s46
	s_nop 0
	global_load_lds_dwordx4 v[8:9], off
	s_waitcnt vmcnt(8)
	s_waitcnt lgkmcnt(0)
	s_setprio 1
	s_barrier
	v_mfma_f32_16x16x32_bf16 v[66:69], v[134:137], v[190:193], v[66:69]
	v_mfma_f32_16x16x32_bf16 v[62:65], v[142:145], v[190:193], v[62:65]
	v_mfma_f32_16x16x32_bf16 v[50:53], v[134:137], v[198:201], v[50:53]
	v_mfma_f32_16x16x32_bf16 v[46:49], v[142:145], v[198:201], v[46:49]
	v_mfma_f32_16x16x32_bf16 v[34:37], v[134:137], v[206:209], v[34:37]
	v_mfma_f32_16x16x32_bf16 v[30:33], v[142:145], v[206:209], v[30:33]
	v_mfma_f32_16x16x32_bf16 v[18:21], v[134:137], v[214:217], v[18:21]
	v_mfma_f32_16x16x32_bf16 v[14:17], v[142:145], v[214:217], v[14:17]
	v_mfma_f32_16x16x32_bf16 v[66:69], v[138:141], v[194:197], v[66:69]
	v_mfma_f32_16x16x32_bf16 v[62:65], v[146:149], v[194:197], v[62:65]
	v_mfma_f32_16x16x32_bf16 v[50:53], v[138:141], v[202:205], v[50:53]
	v_mfma_f32_16x16x32_bf16 v[46:49], v[146:149], v[202:205], v[46:49]
	v_mfma_f32_16x16x32_bf16 v[34:37], v[138:141], v[210:213], v[34:37]
	v_mfma_f32_16x16x32_bf16 v[30:33], v[146:149], v[210:213], v[30:33]
	v_mfma_f32_16x16x32_bf16 v[18:21], v[138:141], v[218:221], v[18:21]
	v_mfma_f32_16x16x32_bf16 v[14:17], v[146:149], v[218:221], v[14:17]
	s_setprio 0
	s_setprio 1
	v_mfma_f32_16x16x32_bf16 v[58:61], v[174:177], v[190:193], v[58:61]
	v_mfma_f32_16x16x32_bf16 v[54:57], v[182:185], v[190:193], v[54:57]
	v_mfma_f32_16x16x32_bf16 v[42:45], v[174:177], v[198:201], v[42:45]
	v_mfma_f32_16x16x32_bf16 v[38:41], v[182:185], v[198:201], v[38:41]
	v_mfma_f32_16x16x32_bf16 v[26:29], v[174:177], v[206:209], v[26:29]
	v_mfma_f32_16x16x32_bf16 v[22:25], v[182:185], v[206:209], v[22:25]
	v_mfma_f32_16x16x32_bf16 v[8:11], v[174:177], v[214:217], v[10:13]
	v_mfma_f32_16x16x32_bf16 v[4:7], v[182:185], v[214:217], v[4:7]
	v_mfma_f32_16x16x32_bf16 v[58:61], v[178:181], v[194:197], v[58:61]
	v_mfma_f32_16x16x32_bf16 v[54:57], v[186:189], v[194:197], v[54:57]
	v_mfma_f32_16x16x32_bf16 v[42:45], v[178:181], v[202:205], v[42:45]
	v_mfma_f32_16x16x32_bf16 v[38:41], v[186:189], v[202:205], v[38:41]
	v_mfma_f32_16x16x32_bf16 v[26:29], v[178:181], v[210:213], v[26:29]
	v_mfma_f32_16x16x32_bf16 v[22:25], v[186:189], v[210:213], v[22:25]
	v_mfma_f32_16x16x32_bf16 v[10:13], v[178:181], v[218:221], v[8:11]
	v_mfma_f32_16x16x32_bf16 v[6:9], v[186:189], v[218:221], v[4:7]
	s_barrier
	s_setprio 0
	s_add_i32 s70, s70, 2
	s_add_u32 s60, s60, 0x100
	s_addc_u32 s61, s61, 0
	s_cmp_gt_u32 s70, 29
	s_cbranch_scc1 .LBB0_1204

.LBB0_1364:
	ds_read_b128 v[86:89], v220
	ds_read_b128 v[90:93], v220 offset:1024
	ds_read_b128 v[114:117], v220 offset:2048
	ds_read_b128 v[118:121], v220 offset:3072
	ds_read_b128 v[146:149], v221
	ds_read_b128 v[150:153], v221 offset:1024
	ds_read_b128 v[154:157], v221 offset:2048
	ds_read_b128 v[158:161], v221 offset:3072
	s_add_u32 s10, s8, 0xfff80080
	s_addc_u32 s11, s9, -1
	s_cmp_eq_u32 s63, 28
	s_cselect_b32 s13, s7, s11
	s_cselect_b32 s12, s14, s10
	s_cselect_b32 s11, s15, s41
	s_cselect_b32 s10, s18, s39
	v_lshl_add_u64 v[208:209], s[8:9], 0, v[180:181]
	s_add_i32 m0, s47, 0xc000
	ds_read_b128 v[162:165], v222
	ds_read_b128 v[166:169], v222 offset:1024
	ds_read_b128 v[184:187], v222 offset:2048
	ds_read_b128 v[188:191], v222 offset:3072
	ds_read_b128 v[192:195], v222 offset:4096
	ds_read_b128 v[196:199], v222 offset:5120
	ds_read_b128 v[200:203], v222 offset:6144
	ds_read_b128 v[204:207], v222 offset:7168
	global_load_lds_dwordx4 v[208:209], off
	v_lshl_add_u64 v[208:209], s[8:9], 0, v[178:179]
	s_add_i32 m0, s47, 0xe000
	s_nop 0
	global_load_lds_dwordx4 v[208:209], off
	s_waitcnt vmcnt(8)
	s_waitcnt lgkmcnt(0)
	s_setprio 1
	s_barrier
	v_mfma_f32_16x16x32_bf16 v[142:145], v[86:89], v[162:165], v[142:145]
	v_mfma_f32_16x16x32_bf16 v[138:141], v[114:117], v[162:165], v[138:141]
	v_mfma_f32_16x16x32_bf16 v[126:129], v[86:89], v[184:187], v[126:129]
	v_mfma_f32_16x16x32_bf16 v[122:125], v[114:117], v[184:187], v[122:125]
	v_mfma_f32_16x16x32_bf16 v[102:105], v[86:89], v[192:195], v[102:105]
	v_mfma_f32_16x16x32_bf16 v[98:101], v[114:117], v[192:195], v[98:101]
	v_mfma_f32_16x16x32_bf16 v[78:81], v[86:89], v[200:203], v[78:81]
	v_mfma_f32_16x16x32_bf16 v[74:77], v[114:117], v[200:203], v[74:77]
	v_mfma_f32_16x16x32_bf16 v[142:145], v[90:93], v[166:169], v[142:145]
	v_mfma_f32_16x16x32_bf16 v[138:141], v[118:121], v[166:169], v[138:141]
	v_mfma_f32_16x16x32_bf16 v[126:129], v[90:93], v[188:191], v[126:129]
	v_mfma_f32_16x16x32_bf16 v[122:125], v[118:121], v[188:191], v[122:125]
	v_mfma_f32_16x16x32_bf16 v[102:105], v[90:93], v[196:199], v[102:105]
	v_mfma_f32_16x16x32_bf16 v[98:101], v[118:121], v[196:199], v[98:101]
	v_mfma_f32_16x16x32_bf16 v[78:81], v[90:93], v[204:207], v[78:81]
	v_mfma_f32_16x16x32_bf16 v[74:77], v[118:121], v[204:207], v[74:77]
	s_setprio 0
	s_setprio 1
	v_mfma_f32_16x16x32_bf16 v[134:137], v[146:149], v[162:165], v[134:137]
	v_mfma_f32_16x16x32_bf16 v[130:133], v[154:157], v[162:165], v[130:133]
	v_mfma_f32_16x16x32_bf16 v[110:113], v[146:149], v[184:187], v[110:113]
	v_mfma_f32_16x16x32_bf16 v[106:109], v[154:157], v[184:187], v[106:109]
	v_mfma_f32_16x16x32_bf16 v[94:97], v[146:149], v[192:195], v[94:97]
	v_mfma_f32_16x16x32_bf16 v[82:85], v[154:157], v[192:195], v[82:85]
	v_mfma_f32_16x16x32_bf16 v[70:73], v[146:149], v[200:203], v[70:73]
	v_mfma_f32_16x16x32_bf16 v[66:69], v[154:157], v[200:203], v[66:69]
	v_mfma_f32_16x16x32_bf16 v[134:137], v[150:153], v[166:169], v[134:137]
	v_mfma_f32_16x16x32_bf16 v[130:133], v[158:161], v[166:169], v[130:133]
	v_mfma_f32_16x16x32_bf16 v[110:113], v[150:153], v[188:191], v[110:113]
	v_mfma_f32_16x16x32_bf16 v[106:109], v[158:161], v[188:191], v[106:109]
	v_mfma_f32_16x16x32_bf16 v[94:97], v[150:153], v[196:199], v[94:97]
	v_mfma_f32_16x16x32_bf16 v[82:85], v[158:161], v[196:199], v[82:85]
	v_mfma_f32_16x16x32_bf16 v[70:73], v[150:153], v[204:207], v[70:73]
	v_mfma_f32_16x16x32_bf16 v[66:69], v[158:161], v[204:207], v[66:69]
	s_barrier
	s_setprio 0
	s_add_i32 s64, s60, s49
	v_lshl_add_u64 v[208:209], s[10:11], 0, v[172:173]
	s_mov_b32 m0, s64
	ds_read_b128 v[162:165], v222 offset:16384
	ds_read_b128 v[166:169], v222 offset:17408
	ds_read_b128 v[184:187], v222 offset:18432
	ds_read_b128 v[188:191], v222 offset:19456
	ds_read_b128 v[192:195], v222 offset:20480
	ds_read_b128 v[196:199], v222 offset:21504
	ds_read_b128 v[200:203], v222 offset:22528
	ds_read_b128 v[204:207], v222 offset:23552
	global_load_lds_dwordx4 v[208:209], off
	s_add_i32 m0, s64, 0x2000
	s_add_u32 s64, s10, 0x80000
	v_lshl_add_u64 v[210:211], s[10:11], 0, v[176:177]
	s_addc_u32 s65, s11, 0
	s_add_i32 s66, s61, s49
	global_load_lds_dwordx4 v[210:211], off
	v_lshl_add_u64 v[212:213], s[64:65], 0, v[172:173]
	s_mov_b32 m0, s66
	v_lshl_add_u64 v[214:215], s[12:13], 0, v[174:175]
	global_load_lds_dwordx4 v[212:213], off
	v_lshl_add_u64 v[212:213], s[64:65], 0, v[176:177]
	s_add_i32 m0, s66, 0x2000
	s_nop 0
	global_load_lds_dwordx4 v[212:213], off
	v_lshl_add_u64 v[212:213], s[12:13], 0, v[170:171]
	s_mov_b32 m0, s47
	s_nop 0
	global_load_lds_dwordx4 v[212:213], off
	s_mov_b32 m0, s50
	s_nop 0
	global_load_lds_dwordx4 v[214:215], off
	s_waitcnt vmcnt(8)
	s_waitcnt lgkmcnt(0)
	s_setprio 1
	s_barrier
	v_mfma_f32_16x16x32_bf16 v[62:65], v[86:89], v[162:165], v[62:65]
	v_mfma_f32_16x16x32_bf16 v[58:61], v[114:117], v[162:165], v[58:61]
	v_mfma_f32_16x16x32_bf16 v[46:49], v[86:89], v[184:187], v[46:49]
	v_mfma_f32_16x16x32_bf16 v[42:45], v[114:117], v[184:187], v[42:45]
	v_mfma_f32_16x16x32_bf16 v[30:33], v[86:89], v[192:195], v[30:33]
	v_mfma_f32_16x16x32_bf16 v[26:29], v[114:117], v[192:195], v[26:29]
	v_mfma_f32_16x16x32_bf16 v[14:17], v[86:89], v[200:203], v[14:17]
	v_mfma_f32_16x16x32_bf16 v[10:13], v[114:117], v[200:203], v[10:13]
	v_mfma_f32_16x16x32_bf16 v[62:65], v[90:93], v[166:169], v[62:65]
	v_mfma_f32_16x16x32_bf16 v[58:61], v[118:121], v[166:169], v[58:61]
	v_mfma_f32_16x16x32_bf16 v[46:49], v[90:93], v[188:191], v[46:49]
	v_mfma_f32_16x16x32_bf16 v[42:45], v[118:121], v[188:191], v[42:45]
	v_mfma_f32_16x16x32_bf16 v[30:33], v[90:93], v[196:199], v[30:33]
	v_mfma_f32_16x16x32_bf16 v[26:29], v[118:121], v[196:199], v[26:29]
	v_mfma_f32_16x16x32_bf16 v[14:17], v[90:93], v[204:207], v[14:17]
	v_mfma_f32_16x16x32_bf16 v[10:13], v[118:121], v[204:207], v[10:13]
	s_setprio 0
	s_setprio 1
	v_mfma_f32_16x16x32_bf16 v[54:57], v[146:149], v[162:165], v[54:57]
	v_mfma_f32_16x16x32_bf16 v[50:53], v[154:157], v[162:165], v[50:53]
	v_mfma_f32_16x16x32_bf16 v[38:41], v[146:149], v[184:187], v[38:41]
	v_mfma_f32_16x16x32_bf16 v[34:37], v[154:157], v[184:187], v[34:37]
	v_mfma_f32_16x16x32_bf16 v[22:25], v[146:149], v[192:195], v[22:25]
	v_mfma_f32_16x16x32_bf16 v[18:21], v[154:157], v[192:195], v[18:21]
	v_mfma_f32_16x16x32_bf16 v[6:9], v[146:149], v[200:203], v[6:9]
	v_mfma_f32_16x16x32_bf16 v[2:5], v[154:157], v[200:203], v[2:5]
	v_mfma_f32_16x16x32_bf16 v[54:57], v[150:153], v[166:169], v[54:57]
	v_mfma_f32_16x16x32_bf16 v[50:53], v[158:161], v[166:169], v[50:53]
	v_mfma_f32_16x16x32_bf16 v[38:41], v[150:153], v[188:191], v[38:41]
	v_mfma_f32_16x16x32_bf16 v[34:37], v[158:161], v[188:191], v[34:37]
	v_mfma_f32_16x16x32_bf16 v[22:25], v[150:153], v[196:199], v[22:25]
	v_mfma_f32_16x16x32_bf16 v[18:21], v[158:161], v[196:199], v[18:21]
	v_mfma_f32_16x16x32_bf16 v[6:9], v[150:153], v[204:207], v[6:9]
	v_mfma_f32_16x16x32_bf16 v[2:5], v[158:161], v[204:207], v[2:5]
	s_barrier
	s_setprio 0
	s_add_i32 s64, 0, 0x18000
	s_add_i32 s65, 0, 0x1c000
	v_add_u32_e32 v118, s64, v219
	v_add_u32_e32 v158, s65, v219
	ds_read_b128 v[86:89], v118
	ds_read_b128 v[90:93], v118 offset:1024
	ds_read_b128 v[114:117], v118 offset:2048
	ds_read_b128 v[118:121], v118 offset:3072
	ds_read_b128 v[146:149], v158
	ds_read_b128 v[150:153], v158 offset:1024
	ds_read_b128 v[154:157], v158 offset:2048
	ds_read_b128 v[158:161], v158 offset:3072
	s_add_u32 s12, s12, 0x80000
	s_addc_u32 s13, s13, 0
	s_mov_b32 m0, s51
	v_lshl_add_u64 v[216:217], s[12:13], 0, v[170:171]
	ds_read_b128 v[162:165], v222 offset:32768
	ds_read_b128 v[166:169], v222 offset:33792
	ds_read_b128 v[184:187], v222 offset:34816
	ds_read_b128 v[188:191], v222 offset:35840
	ds_read_b128 v[192:195], v222 offset:36864
	ds_read_b128 v[196:199], v222 offset:37888
	ds_read_b128 v[200:203], v222 offset:38912
	ds_read_b128 v[204:207], v222 offset:39936
	global_load_lds_dwordx4 v[216:217], off
	v_lshl_add_u64 v[216:217], s[12:13], 0, v[174:175]
	s_mov_b32 m0, s52
	s_nop 0
	global_load_lds_dwordx4 v[216:217], off
	s_waitcnt vmcnt(8)
	s_waitcnt lgkmcnt(0)
	s_setprio 1
	s_barrier
	v_mfma_f32_16x16x32_bf16 v[142:145], v[86:89], v[162:165], v[142:145]
	v_mfma_f32_16x16x32_bf16 v[138:141], v[114:117], v[162:165], v[138:141]
	v_mfma_f32_16x16x32_bf16 v[126:129], v[86:89], v[184:187], v[126:129]
	v_mfma_f32_16x16x32_bf16 v[122:125], v[114:117], v[184:187], v[122:125]
	v_mfma_f32_16x16x32_bf16 v[102:105], v[86:89], v[192:195], v[102:105]
	v_mfma_f32_16x16x32_bf16 v[98:101], v[114:117], v[192:195], v[98:101]
	v_mfma_f32_16x16x32_bf16 v[78:81], v[86:89], v[200:203], v[78:81]
	v_mfma_f32_16x16x32_bf16 v[74:77], v[114:117], v[200:203], v[74:77]
	v_mfma_f32_16x16x32_bf16 v[142:145], v[90:93], v[166:169], v[142:145]
	v_mfma_f32_16x16x32_bf16 v[138:141], v[118:121], v[166:169], v[138:141]
	v_mfma_f32_16x16x32_bf16 v[126:129], v[90:93], v[188:191], v[126:129]
	v_mfma_f32_16x16x32_bf16 v[122:125], v[118:121], v[188:191], v[122:125]
	v_mfma_f32_16x16x32_bf16 v[102:105], v[90:93], v[196:199], v[102:105]
	v_mfma_f32_16x16x32_bf16 v[98:101], v[118:121], v[196:199], v[98:101]
	v_mfma_f32_16x16x32_bf16 v[78:81], v[90:93], v[204:207], v[78:81]
	v_mfma_f32_16x16x32_bf16 v[74:77], v[118:121], v[204:207], v[74:77]
	s_setprio 0
	s_setprio 1
	v_mfma_f32_16x16x32_bf16 v[134:137], v[146:149], v[162:165], v[134:137]
	v_mfma_f32_16x16x32_bf16 v[130:133], v[154:157], v[162:165], v[130:133]
	v_mfma_f32_16x16x32_bf16 v[110:113], v[146:149], v[184:187], v[110:113]
	v_mfma_f32_16x16x32_bf16 v[106:109], v[154:157], v[184:187], v[106:109]
	v_mfma_f32_16x16x32_bf16 v[94:97], v[146:149], v[192:195], v[94:97]
	v_mfma_f32_16x16x32_bf16 v[82:85], v[154:157], v[192:195], v[82:85]
	v_mfma_f32_16x16x32_bf16 v[70:73], v[146:149], v[200:203], v[70:73]
	v_mfma_f32_16x16x32_bf16 v[66:69], v[154:157], v[200:203], v[66:69]
	v_mfma_f32_16x16x32_bf16 v[134:137], v[150:153], v[166:169], v[134:137]
	v_mfma_f32_16x16x32_bf16 v[130:133], v[158:161], v[166:169], v[130:133]
	v_mfma_f32_16x16x32_bf16 v[110:113], v[150:153], v[188:191], v[110:113]
	v_mfma_f32_16x16x32_bf16 v[106:109], v[158:161], v[188:191], v[106:109]
	v_mfma_f32_16x16x32_bf16 v[94:97], v[150:153], v[196:199], v[94:97]
	v_mfma_f32_16x16x32_bf16 v[82:85], v[158:161], v[196:199], v[82:85]
	v_mfma_f32_16x16x32_bf16 v[70:73], v[150:153], v[204:207], v[70:73]
	v_mfma_f32_16x16x32_bf16 v[66:69], v[158:161], v[204:207], v[66:69]
	s_barrier
	s_setprio 0
	s_add_i32 s12, s64, s49
	v_lshl_add_u64 v[208:209], v[208:209], 0, s[30:31]
	s_mov_b32 m0, s12
	ds_read_b128 v[162:165], v222 offset:49152
	ds_read_b128 v[166:169], v222 offset:50176
	ds_read_b128 v[184:187], v222 offset:51200
	ds_read_b128 v[188:191], v222 offset:52224
	ds_read_b128 v[192:195], v222 offset:53248
	ds_read_b128 v[196:199], v222 offset:54272
	ds_read_b128 v[200:203], v222 offset:55296
	ds_read_b128 v[204:207], v222 offset:56320
	global_load_lds_dwordx4 v[208:209], off
	s_add_i32 m0, s12, 0x2000
	s_add_u32 s10, s10, 0x80080
	v_lshl_add_u64 v[208:209], v[210:211], 0, s[30:31]
	s_addc_u32 s11, s11, 0
	s_add_i32 s12, s65, s49
	global_load_lds_dwordx4 v[208:209], off
	v_lshl_add_u64 v[208:209], s[10:11], 0, v[172:173]
	s_mov_b32 m0, s12
	s_nop 0
	global_load_lds_dwordx4 v[208:209], off
	v_lshl_add_u64 v[208:209], s[10:11], 0, v[176:177]
	s_add_i32 m0, s12, 0x2000
	s_nop 0
	global_load_lds_dwordx4 v[208:209], off
	v_lshl_add_u64 v[208:209], v[212:213], 0, s[30:31]
	s_mov_b32 m0, s56
	s_nop 0
	global_load_lds_dwordx4 v[208:209], off
	v_lshl_add_u64 v[208:209], v[214:215], 0, s[30:31]
	s_mov_b32 m0, s57
	s_nop 0
	global_load_lds_dwordx4 v[208:209], off
	s_waitcnt vmcnt(8)
	s_waitcnt lgkmcnt(0)
	s_setprio 1
	s_barrier
	v_mfma_f32_16x16x32_bf16 v[62:65], v[86:89], v[162:165], v[62:65]
	v_mfma_f32_16x16x32_bf16 v[58:61], v[114:117], v[162:165], v[58:61]
	v_mfma_f32_16x16x32_bf16 v[46:49], v[86:89], v[184:187], v[46:49]
	v_mfma_f32_16x16x32_bf16 v[42:45], v[114:117], v[184:187], v[42:45]
	v_mfma_f32_16x16x32_bf16 v[30:33], v[86:89], v[192:195], v[30:33]
	v_mfma_f32_16x16x32_bf16 v[26:29], v[114:117], v[192:195], v[26:29]
	v_mfma_f32_16x16x32_bf16 v[14:17], v[86:89], v[200:203], v[14:17]
	v_mfma_f32_16x16x32_bf16 v[10:13], v[114:117], v[200:203], v[10:13]
	v_mfma_f32_16x16x32_bf16 v[62:65], v[90:93], v[166:169], v[62:65]
	v_mfma_f32_16x16x32_bf16 v[58:61], v[118:121], v[166:169], v[58:61]
	v_mfma_f32_16x16x32_bf16 v[46:49], v[90:93], v[188:191], v[46:49]
	v_mfma_f32_16x16x32_bf16 v[42:45], v[118:121], v[188:191], v[42:45]
	v_mfma_f32_16x16x32_bf16 v[30:33], v[90:93], v[196:199], v[30:33]
	v_mfma_f32_16x16x32_bf16 v[26:29], v[118:121], v[196:199], v[26:29]
	v_mfma_f32_16x16x32_bf16 v[14:17], v[90:93], v[204:207], v[14:17]
	v_mfma_f32_16x16x32_bf16 v[10:13], v[118:121], v[204:207], v[10:13]
	s_setprio 0
	s_setprio 1
	v_mfma_f32_16x16x32_bf16 v[54:57], v[146:149], v[162:165], v[54:57]
	v_mfma_f32_16x16x32_bf16 v[50:53], v[154:157], v[162:165], v[50:53]
	v_mfma_f32_16x16x32_bf16 v[38:41], v[146:149], v[184:187], v[38:41]
	v_mfma_f32_16x16x32_bf16 v[34:37], v[154:157], v[184:187], v[34:37]
	v_mfma_f32_16x16x32_bf16 v[22:25], v[146:149], v[192:195], v[22:25]
	v_mfma_f32_16x16x32_bf16 v[18:21], v[154:157], v[192:195], v[18:21]
	v_mfma_f32_16x16x32_bf16 v[6:9], v[146:149], v[200:203], v[6:9]
	v_mfma_f32_16x16x32_bf16 v[2:5], v[154:157], v[200:203], v[2:5]
	v_mfma_f32_16x16x32_bf16 v[54:57], v[150:153], v[166:169], v[54:57]
	v_mfma_f32_16x16x32_bf16 v[50:53], v[158:161], v[166:169], v[50:53]
	v_mfma_f32_16x16x32_bf16 v[38:41], v[150:153], v[188:191], v[38:41]
	v_mfma_f32_16x16x32_bf16 v[34:37], v[158:161], v[188:191], v[34:37]
	v_mfma_f32_16x16x32_bf16 v[22:25], v[150:153], v[196:199], v[22:25]
	v_mfma_f32_16x16x32_bf16 v[18:21], v[158:161], v[196:199], v[18:21]
	v_mfma_f32_16x16x32_bf16 v[6:9], v[150:153], v[204:207], v[6:9]
	v_mfma_f32_16x16x32_bf16 v[2:5], v[158:161], v[204:207], v[2:5]
	s_barrier
	s_setprio 0
	s_add_i32 s63, s63, 2
	s_add_u32 s39, s39, 0x100
	s_addc_u32 s41, s41, 0
	s_add_u32 s8, s8, 0x100
	s_addc_u32 s9, s9, 0
	s_cmp_gt_u32 s63, 29
	s_cbranch_scc0 .LBB0_1364
	s_and_b64 vcc, exec, s[36:37]
	s_cbranch_vccz .LBB0_1367
	s_barrier

.LBB0_1390:
	ds_read_b128 v[148:151], v143
	ds_read_b128 v[152:155], v143 offset:1024
	ds_read_b128 v[156:159], v143 offset:2048
	ds_read_b128 v[160:163], v143 offset:3072
	ds_read_b128 v[164:167], v144
	ds_read_b128 v[168:171], v144 offset:1024
	ds_read_b128 v[172:175], v144 offset:2048
	ds_read_b128 v[176:179], v144 offset:3072
	s_add_u32 s12, s10, 0x100
	s_addc_u32 s13, s11, 0
	s_cmp_lg_u32 s0, 4
	s_cselect_b32 s14, s12, 0
	s_cselect_b32 s15, s13, 0
	s_add_u32 s16, s6, s14
	s_addc_u32 s17, s7, s15
	s_add_u32 s14, s4, s14
	s_addc_u32 s15, s5, s15
	s_mov_b32 m0, s1
	v_lshl_add_u64 v[212:213], v[140:141], 0, s[10:11]
	ds_read_b128 v[180:183], v145
	ds_read_b128 v[184:187], v145 offset:1024
	ds_read_b128 v[188:191], v145 offset:2048
	ds_read_b128 v[192:195], v145 offset:3072
	ds_read_b128 v[196:199], v145 offset:4096
	ds_read_b128 v[200:203], v145 offset:5120
	ds_read_b128 v[204:207], v145 offset:6144
	ds_read_b128 v[208:211], v145 offset:7168
	global_load_lds_dwordx4 v[212:213], off
	v_lshl_add_u64 v[212:213], v[138:139], 0, s[10:11]
	s_mov_b32 m0, s30
	s_nop 0
	global_load_lds_dwordx4 v[212:213], off
	s_waitcnt vmcnt(8)
	s_waitcnt lgkmcnt(0)
	s_setprio 1
	s_barrier
	v_mfma_f32_16x16x32_bf16 v[126:129], v[148:151], v[180:183], v[126:129]
	v_mfma_f32_16x16x32_bf16 v[122:125], v[156:159], v[180:183], v[122:125]
	v_mfma_f32_16x16x32_bf16 v[118:121], v[148:151], v[188:191], v[118:121]
	v_mfma_f32_16x16x32_bf16 v[114:117], v[156:159], v[188:191], v[114:117]
	v_mfma_f32_16x16x32_bf16 v[106:109], v[148:151], v[196:199], v[106:109]
	v_mfma_f32_16x16x32_bf16 v[98:101], v[156:159], v[196:199], v[98:101]
	v_mfma_f32_16x16x32_bf16 v[90:93], v[148:151], v[204:207], v[90:93]
	v_mfma_f32_16x16x32_bf16 v[82:85], v[156:159], v[204:207], v[82:85]
	v_mfma_f32_16x16x32_bf16 v[126:129], v[152:155], v[184:187], v[126:129]
	v_mfma_f32_16x16x32_bf16 v[122:125], v[160:163], v[184:187], v[122:125]
	v_mfma_f32_16x16x32_bf16 v[118:121], v[152:155], v[192:195], v[118:121]
	v_mfma_f32_16x16x32_bf16 v[114:117], v[160:163], v[192:195], v[114:117]
	v_mfma_f32_16x16x32_bf16 v[106:109], v[152:155], v[200:203], v[106:109]
	v_mfma_f32_16x16x32_bf16 v[98:101], v[160:163], v[200:203], v[98:101]
	v_mfma_f32_16x16x32_bf16 v[90:93], v[152:155], v[208:211], v[90:93]
	v_mfma_f32_16x16x32_bf16 v[82:85], v[160:163], v[208:211], v[82:85]
	s_setprio 0
	s_setprio 1
	v_mfma_f32_16x16x32_bf16 v[110:113], v[164:167], v[180:183], v[110:113]
	v_mfma_f32_16x16x32_bf16 v[102:105], v[172:175], v[180:183], v[102:105]
	v_mfma_f32_16x16x32_bf16 v[94:97], v[164:167], v[188:191], v[94:97]
	v_mfma_f32_16x16x32_bf16 v[86:89], v[172:175], v[188:191], v[86:89]
	v_mfma_f32_16x16x32_bf16 v[78:81], v[164:167], v[196:199], v[78:81]
	v_mfma_f32_16x16x32_bf16 v[74:77], v[172:175], v[196:199], v[74:77]
	v_mfma_f32_16x16x32_bf16 v[70:73], v[164:167], v[204:207], v[70:73]
	v_mfma_f32_16x16x32_bf16 v[66:69], v[172:175], v[204:207], v[66:69]
	v_mfma_f32_16x16x32_bf16 v[110:113], v[168:171], v[184:187], v[110:113]
	v_mfma_f32_16x16x32_bf16 v[102:105], v[176:179], v[184:187], v[102:105]
	v_mfma_f32_16x16x32_bf16 v[94:97], v[168:171], v[192:195], v[94:97]
	v_mfma_f32_16x16x32_bf16 v[86:89], v[176:179], v[192:195], v[86:89]
	v_mfma_f32_16x16x32_bf16 v[78:81], v[168:171], v[200:203], v[78:81]
	v_mfma_f32_16x16x32_bf16 v[74:77], v[176:179], v[200:203], v[74:77]
	v_mfma_f32_16x16x32_bf16 v[70:73], v[168:171], v[208:211], v[70:73]
	v_mfma_f32_16x16x32_bf16 v[66:69], v[176:179], v[208:211], v[66:69]
	s_barrier
	s_setprio 0
	s_mov_b32 m0, s31
	v_lshl_add_u64 v[212:213], s[14:15], 0, v[132:133]
	s_add_u32 s10, s14, 0x80000
	ds_read_b128 v[180:183], v145 offset:16384
	ds_read_b128 v[184:187], v145 offset:17408
	ds_read_b128 v[188:191], v145 offset:18432
	ds_read_b128 v[192:195], v145 offset:19456
	ds_read_b128 v[196:199], v145 offset:20480
	ds_read_b128 v[200:203], v145 offset:21504
	ds_read_b128 v[204:207], v145 offset:22528
	ds_read_b128 v[208:211], v145 offset:23552
	global_load_lds_dwordx4 v[212:213], off
	v_lshl_add_u64 v[214:215], s[14:15], 0, v[136:137]
	s_mov_b32 m0, s33
	s_addc_u32 s11, s15, 0
	global_load_lds_dwordx4 v[214:215], off
	v_lshl_add_u64 v[216:217], s[10:11], 0, v[132:133]
	s_mov_b32 m0, s34
	v_lshl_add_u64 v[218:219], s[16:17], 0, v[134:135]
	global_load_lds_dwordx4 v[216:217], off
	v_lshl_add_u64 v[216:217], s[10:11], 0, v[136:137]
	s_mov_b32 m0, s35
	s_nop 0
	global_load_lds_dwordx4 v[216:217], off
	v_lshl_add_u64 v[216:217], s[16:17], 0, v[130:131]
	s_mov_b32 m0, s20
	s_nop 0
	global_load_lds_dwordx4 v[216:217], off
	s_mov_b32 m0, s23
	s_nop 0
	global_load_lds_dwordx4 v[218:219], off
	s_waitcnt vmcnt(8)
	s_waitcnt lgkmcnt(0)
	s_setprio 1
	s_barrier
	v_mfma_f32_16x16x32_bf16 v[62:65], v[148:151], v[180:183], v[62:65]
	v_mfma_f32_16x16x32_bf16 v[58:61], v[156:159], v[180:183], v[58:61]
	v_mfma_f32_16x16x32_bf16 v[54:57], v[148:151], v[188:191], v[54:57]
	v_mfma_f32_16x16x32_bf16 v[50:53], v[156:159], v[188:191], v[50:53]
	v_mfma_f32_16x16x32_bf16 v[42:45], v[148:151], v[196:199], v[42:45]
	v_mfma_f32_16x16x32_bf16 v[34:37], v[156:159], v[196:199], v[34:37]
	v_mfma_f32_16x16x32_bf16 v[26:29], v[148:151], v[204:207], v[26:29]
	v_mfma_f32_16x16x32_bf16 v[18:21], v[156:159], v[204:207], v[18:21]
	v_mfma_f32_16x16x32_bf16 v[62:65], v[152:155], v[184:187], v[62:65]
	v_mfma_f32_16x16x32_bf16 v[58:61], v[160:163], v[184:187], v[58:61]
	v_mfma_f32_16x16x32_bf16 v[54:57], v[152:155], v[192:195], v[54:57]
	v_mfma_f32_16x16x32_bf16 v[50:53], v[160:163], v[192:195], v[50:53]
	v_mfma_f32_16x16x32_bf16 v[42:45], v[152:155], v[200:203], v[42:45]
	v_mfma_f32_16x16x32_bf16 v[34:37], v[160:163], v[200:203], v[34:37]
	v_mfma_f32_16x16x32_bf16 v[26:29], v[152:155], v[208:211], v[26:29]
	v_mfma_f32_16x16x32_bf16 v[18:21], v[160:163], v[208:211], v[18:21]
	s_setprio 0
	s_setprio 1
	v_mfma_f32_16x16x32_bf16 v[46:49], v[164:167], v[180:183], v[46:49]
	v_mfma_f32_16x16x32_bf16 v[38:41], v[172:175], v[180:183], v[38:41]
	v_mfma_f32_16x16x32_bf16 v[30:33], v[164:167], v[188:191], v[30:33]
	v_mfma_f32_16x16x32_bf16 v[22:25], v[172:175], v[188:191], v[22:25]
	v_mfma_f32_16x16x32_bf16 v[14:17], v[164:167], v[196:199], v[14:17]
	v_mfma_f32_16x16x32_bf16 v[10:13], v[172:175], v[196:199], v[10:13]
	v_mfma_f32_16x16x32_bf16 v[6:9], v[164:167], v[204:207], v[6:9]
	v_mfma_f32_16x16x32_bf16 v[2:5], v[172:175], v[204:207], v[2:5]
	v_mfma_f32_16x16x32_bf16 v[46:49], v[168:171], v[184:187], v[46:49]
	v_mfma_f32_16x16x32_bf16 v[38:41], v[176:179], v[184:187], v[38:41]
	v_mfma_f32_16x16x32_bf16 v[30:33], v[168:171], v[192:195], v[30:33]
	v_mfma_f32_16x16x32_bf16 v[22:25], v[176:179], v[192:195], v[22:25]
	v_mfma_f32_16x16x32_bf16 v[14:17], v[168:171], v[200:203], v[14:17]
	v_mfma_f32_16x16x32_bf16 v[10:13], v[176:179], v[200:203], v[10:13]
	v_mfma_f32_16x16x32_bf16 v[6:9], v[168:171], v[208:211], v[6:9]
	v_mfma_f32_16x16x32_bf16 v[2:5], v[176:179], v[208:211], v[2:5]
	s_barrier
	s_setprio 0
	ds_read_b128 v[148:151], v146
	ds_read_b128 v[152:155], v146 offset:1024
	ds_read_b128 v[156:159], v146 offset:2048
	ds_read_b128 v[160:163], v146 offset:3072
	ds_read_b128 v[164:167], v147
	ds_read_b128 v[168:171], v147 offset:1024
	ds_read_b128 v[172:175], v147 offset:2048
	ds_read_b128 v[176:179], v147 offset:3072
	s_add_u32 s10, s16, 0x80000
	s_addc_u32 s11, s17, 0
	s_mov_b32 m0, s24
	v_lshl_add_u64 v[220:221], s[10:11], 0, v[130:131]
	ds_read_b128 v[180:183], v145 offset:32768
	ds_read_b128 v[184:187], v145 offset:33792
	ds_read_b128 v[188:191], v145 offset:34816
	ds_read_b128 v[192:195], v145 offset:35840
	ds_read_b128 v[196:199], v145 offset:36864
	ds_read_b128 v[200:203], v145 offset:37888
	ds_read_b128 v[204:207], v145 offset:38912
	ds_read_b128 v[208:211], v145 offset:39936
	global_load_lds_dwordx4 v[220:221], off
	v_lshl_add_u64 v[220:221], s[10:11], 0, v[134:135]
	s_mov_b32 m0, s26
	s_nop 0
	global_load_lds_dwordx4 v[220:221], off
	s_waitcnt vmcnt(8)
	s_waitcnt lgkmcnt(0)
	s_setprio 1
	s_barrier
	v_mfma_f32_16x16x32_bf16 v[126:129], v[148:151], v[180:183], v[126:129]
	v_mfma_f32_16x16x32_bf16 v[122:125], v[156:159], v[180:183], v[122:125]
	v_mfma_f32_16x16x32_bf16 v[118:121], v[148:151], v[188:191], v[118:121]
	v_mfma_f32_16x16x32_bf16 v[114:117], v[156:159], v[188:191], v[114:117]
	v_mfma_f32_16x16x32_bf16 v[106:109], v[148:151], v[196:199], v[106:109]
	v_mfma_f32_16x16x32_bf16 v[98:101], v[156:159], v[196:199], v[98:101]
	v_mfma_f32_16x16x32_bf16 v[90:93], v[148:151], v[204:207], v[90:93]
	v_mfma_f32_16x16x32_bf16 v[82:85], v[156:159], v[204:207], v[82:85]
	v_mfma_f32_16x16x32_bf16 v[126:129], v[152:155], v[184:187], v[126:129]
	v_mfma_f32_16x16x32_bf16 v[122:125], v[160:163], v[184:187], v[122:125]
	v_mfma_f32_16x16x32_bf16 v[118:121], v[152:155], v[192:195], v[118:121]
	v_mfma_f32_16x16x32_bf16 v[114:117], v[160:163], v[192:195], v[114:117]
	v_mfma_f32_16x16x32_bf16 v[106:109], v[152:155], v[200:203], v[106:109]
	v_mfma_f32_16x16x32_bf16 v[98:101], v[160:163], v[200:203], v[98:101]
	v_mfma_f32_16x16x32_bf16 v[90:93], v[152:155], v[208:211], v[90:93]
	v_mfma_f32_16x16x32_bf16 v[82:85], v[160:163], v[208:211], v[82:85]
	s_setprio 0
	s_setprio 1
	v_mfma_f32_16x16x32_bf16 v[110:113], v[164:167], v[180:183], v[110:113]
	v_mfma_f32_16x16x32_bf16 v[102:105], v[172:175], v[180:183], v[102:105]
	v_mfma_f32_16x16x32_bf16 v[94:97], v[164:167], v[188:191], v[94:97]
	v_mfma_f32_16x16x32_bf16 v[86:89], v[172:175], v[188:191], v[86:89]
	v_mfma_f32_16x16x32_bf16 v[78:81], v[164:167], v[196:199], v[78:81]
	v_mfma_f32_16x16x32_bf16 v[74:77], v[172:175], v[196:199], v[74:77]
	v_mfma_f32_16x16x32_bf16 v[70:73], v[164:167], v[204:207], v[70:73]
	v_mfma_f32_16x16x32_bf16 v[66:69], v[172:175], v[204:207], v[66:69]
	v_mfma_f32_16x16x32_bf16 v[110:113], v[168:171], v[184:187], v[110:113]
	v_mfma_f32_16x16x32_bf16 v[102:105], v[176:179], v[184:187], v[102:105]
	v_mfma_f32_16x16x32_bf16 v[94:97], v[168:171], v[192:195], v[94:97]
	v_mfma_f32_16x16x32_bf16 v[86:89], v[176:179], v[192:195], v[86:89]
	v_mfma_f32_16x16x32_bf16 v[78:81], v[168:171], v[200:203], v[78:81]
	v_mfma_f32_16x16x32_bf16 v[74:77], v[176:179], v[200:203], v[74:77]
	v_mfma_f32_16x16x32_bf16 v[70:73], v[168:171], v[208:211], v[70:73]
	v_mfma_f32_16x16x32_bf16 v[66:69], v[176:179], v[208:211], v[66:69]
	s_barrier
	s_setprio 0
	s_mov_b32 m0, s36
	v_lshl_add_u64 v[212:213], v[212:213], 0, s[8:9]
	s_add_u32 s10, s14, 0x80080
	ds_read_b128 v[180:183], v145 offset:49152
	ds_read_b128 v[184:187], v145 offset:50176
	ds_read_b128 v[188:191], v145 offset:51200
	ds_read_b128 v[192:195], v145 offset:52224
	ds_read_b128 v[196:199], v145 offset:53248
	ds_read_b128 v[200:203], v145 offset:54272
	ds_read_b128 v[204:207], v145 offset:55296
	ds_read_b128 v[208:211], v145 offset:56320
	global_load_lds_dwordx4 v[212:213], off
	v_lshl_add_u64 v[212:213], v[214:215], 0, s[8:9]
	s_mov_b32 m0, s37
	s_addc_u32 s11, s15, 0
	global_load_lds_dwordx4 v[212:213], off
	v_lshl_add_u64 v[212:213], s[10:11], 0, v[132:133]
	s_mov_b32 m0, s38
	s_nop 0
	global_load_lds_dwordx4 v[212:213], off
	v_lshl_add_u64 v[212:213], s[10:11], 0, v[136:137]
	s_mov_b32 m0, s39
	s_nop 0
	global_load_lds_dwordx4 v[212:213], off
	v_lshl_add_u64 v[212:213], v[216:217], 0, s[8:9]
	s_mov_b32 m0, s28
	s_nop 0
	global_load_lds_dwordx4 v[212:213], off
	v_lshl_add_u64 v[212:213], v[218:219], 0, s[8:9]
	s_mov_b32 m0, s29
	s_nop 0
	global_load_lds_dwordx4 v[212:213], off
	s_waitcnt vmcnt(8)
	s_waitcnt lgkmcnt(0)
	s_setprio 1
	s_barrier
	v_mfma_f32_16x16x32_bf16 v[62:65], v[148:151], v[180:183], v[62:65]
	v_mfma_f32_16x16x32_bf16 v[58:61], v[156:159], v[180:183], v[58:61]
	v_mfma_f32_16x16x32_bf16 v[54:57], v[148:151], v[188:191], v[54:57]
	v_mfma_f32_16x16x32_bf16 v[50:53], v[156:159], v[188:191], v[50:53]
	v_mfma_f32_16x16x32_bf16 v[42:45], v[148:151], v[196:199], v[42:45]
	v_mfma_f32_16x16x32_bf16 v[34:37], v[156:159], v[196:199], v[34:37]
	v_mfma_f32_16x16x32_bf16 v[26:29], v[148:151], v[204:207], v[26:29]
	v_mfma_f32_16x16x32_bf16 v[18:21], v[156:159], v[204:207], v[18:21]
	v_mfma_f32_16x16x32_bf16 v[62:65], v[152:155], v[184:187], v[62:65]
	v_mfma_f32_16x16x32_bf16 v[58:61], v[160:163], v[184:187], v[58:61]
	v_mfma_f32_16x16x32_bf16 v[54:57], v[152:155], v[192:195], v[54:57]
	v_mfma_f32_16x16x32_bf16 v[50:53], v[160:163], v[192:195], v[50:53]
	v_mfma_f32_16x16x32_bf16 v[42:45], v[152:155], v[200:203], v[42:45]
	v_mfma_f32_16x16x32_bf16 v[34:37], v[160:163], v[200:203], v[34:37]
	v_mfma_f32_16x16x32_bf16 v[26:29], v[152:155], v[208:211], v[26:29]
	v_mfma_f32_16x16x32_bf16 v[18:21], v[160:163], v[208:211], v[18:21]
	s_setprio 0
	s_setprio 1
	v_mfma_f32_16x16x32_bf16 v[46:49], v[164:167], v[180:183], v[46:49]
	v_mfma_f32_16x16x32_bf16 v[38:41], v[172:175], v[180:183], v[38:41]
	v_mfma_f32_16x16x32_bf16 v[30:33], v[164:167], v[188:191], v[30:33]
	v_mfma_f32_16x16x32_bf16 v[22:25], v[172:175], v[188:191], v[22:25]
	v_mfma_f32_16x16x32_bf16 v[14:17], v[164:167], v[196:199], v[14:17]
	v_mfma_f32_16x16x32_bf16 v[10:13], v[172:175], v[196:199], v[10:13]
	v_mfma_f32_16x16x32_bf16 v[6:9], v[164:167], v[204:207], v[6:9]
	v_mfma_f32_16x16x32_bf16 v[2:5], v[172:175], v[204:207], v[2:5]
	v_mfma_f32_16x16x32_bf16 v[46:49], v[168:171], v[184:187], v[46:49]
	v_mfma_f32_16x16x32_bf16 v[38:41], v[176:179], v[184:187], v[38:41]
	v_mfma_f32_16x16x32_bf16 v[30:33], v[168:171], v[192:195], v[30:33]
	v_mfma_f32_16x16x32_bf16 v[22:25], v[176:179], v[192:195], v[22:25]
	v_mfma_f32_16x16x32_bf16 v[14:17], v[168:171], v[200:203], v[14:17]
	v_mfma_f32_16x16x32_bf16 v[10:13], v[176:179], v[200:203], v[10:13]
	v_mfma_f32_16x16x32_bf16 v[6:9], v[168:171], v[208:211], v[6:9]
	v_mfma_f32_16x16x32_bf16 v[2:5], v[176:179], v[208:211], v[2:5]
	s_barrier
	s_setprio 0
	s_add_i32 s0, s0, 2
	s_cmp_gt_u32 s0, 5
	s_mov_b64 s[10:11], s[12:13]
	s_cbranch_scc0 .LBB0_1390
	s_cmpk_lt_u32 s19, 0x100
	s_cbranch_scc0 .LBB0_1393
	s_barrier

.LBB0_1525:
	ds_read_b128 v[146:149], v152
	ds_read_b128 v[156:159], v152 offset:1024
	ds_read_b128 v[160:163], v152 offset:2048
	ds_read_b128 v[164:167], v152 offset:3072
	ds_read_b128 v[168:171], v153
	ds_read_b128 v[172:175], v153 offset:1024
	ds_read_b128 v[176:179], v153 offset:2048
	ds_read_b128 v[180:183], v153 offset:3072
	s_add_u32 s46, s44, 0xfff80080
	s_addc_u32 s47, s45, -1
	s_cmp_eq_u32 s73, 28
	s_cselect_b32 s49, s37, s47
	s_cselect_b32 s48, s69, s46
	s_cselect_b32 s47, s31, s72
	s_cselect_b32 s46, s70, s71
	v_lshl_add_u64 v[216:217], s[44:45], 0, v[140:141]
	s_add_i32 m0, s43, 0xc000
	ds_read_b128 v[184:187], v154
	ds_read_b128 v[188:191], v154 offset:1024
	ds_read_b128 v[192:195], v154 offset:2048
	ds_read_b128 v[196:199], v154 offset:3072
	ds_read_b128 v[200:203], v154 offset:4096
	ds_read_b128 v[204:207], v154 offset:5120
	ds_read_b128 v[208:211], v154 offset:6144
	ds_read_b128 v[212:215], v154 offset:7168
	global_load_lds_dwordx4 v[216:217], off
	v_lshl_add_u64 v[216:217], s[44:45], 0, v[138:139]
	s_add_i32 m0, s43, 0xe000
	s_nop 0
	global_load_lds_dwordx4 v[216:217], off
	s_waitcnt vmcnt(8)
	s_waitcnt lgkmcnt(0)
	s_setprio 1
	s_barrier
	v_mfma_f32_16x16x32_bf16 v[126:129], v[146:149], v[184:187], v[126:129]
	v_mfma_f32_16x16x32_bf16 v[122:125], v[160:163], v[184:187], v[122:125]
	v_mfma_f32_16x16x32_bf16 v[110:113], v[146:149], v[192:195], v[110:113]
	v_mfma_f32_16x16x32_bf16 v[106:109], v[160:163], v[192:195], v[106:109]
	v_mfma_f32_16x16x32_bf16 v[94:97], v[146:149], v[200:203], v[94:97]
	v_mfma_f32_16x16x32_bf16 v[90:93], v[160:163], v[200:203], v[90:93]
	v_mfma_f32_16x16x32_bf16 v[78:81], v[146:149], v[208:211], v[78:81]
	v_mfma_f32_16x16x32_bf16 v[74:77], v[160:163], v[208:211], v[74:77]
	v_mfma_f32_16x16x32_bf16 v[126:129], v[156:159], v[188:191], v[126:129]
	v_mfma_f32_16x16x32_bf16 v[122:125], v[164:167], v[188:191], v[122:125]
	v_mfma_f32_16x16x32_bf16 v[110:113], v[156:159], v[196:199], v[110:113]
	v_mfma_f32_16x16x32_bf16 v[106:109], v[164:167], v[196:199], v[106:109]
	v_mfma_f32_16x16x32_bf16 v[94:97], v[156:159], v[204:207], v[94:97]
	v_mfma_f32_16x16x32_bf16 v[90:93], v[164:167], v[204:207], v[90:93]
	v_mfma_f32_16x16x32_bf16 v[78:81], v[156:159], v[212:215], v[78:81]
	v_mfma_f32_16x16x32_bf16 v[74:77], v[164:167], v[212:215], v[74:77]
	s_setprio 0
	s_setprio 1
	v_mfma_f32_16x16x32_bf16 v[118:121], v[168:171], v[184:187], v[118:121]
	v_mfma_f32_16x16x32_bf16 v[114:117], v[176:179], v[184:187], v[114:117]
	v_mfma_f32_16x16x32_bf16 v[102:105], v[168:171], v[192:195], v[102:105]
	v_mfma_f32_16x16x32_bf16 v[98:101], v[176:179], v[192:195], v[98:101]
	v_mfma_f32_16x16x32_bf16 v[86:89], v[168:171], v[200:203], v[86:89]
	v_mfma_f32_16x16x32_bf16 v[82:85], v[176:179], v[200:203], v[82:85]
	v_mfma_f32_16x16x32_bf16 v[70:73], v[168:171], v[208:211], v[70:73]
	v_mfma_f32_16x16x32_bf16 v[66:69], v[176:179], v[208:211], v[66:69]
	v_mfma_f32_16x16x32_bf16 v[118:121], v[172:175], v[188:191], v[118:121]
	v_mfma_f32_16x16x32_bf16 v[114:117], v[180:183], v[188:191], v[114:117]
	v_mfma_f32_16x16x32_bf16 v[102:105], v[172:175], v[196:199], v[102:105]
	v_mfma_f32_16x16x32_bf16 v[98:101], v[180:183], v[196:199], v[98:101]
	v_mfma_f32_16x16x32_bf16 v[86:89], v[172:175], v[204:207], v[86:89]
	v_mfma_f32_16x16x32_bf16 v[82:85], v[180:183], v[204:207], v[82:85]
	v_mfma_f32_16x16x32_bf16 v[70:73], v[172:175], v[212:215], v[70:73]
	v_mfma_f32_16x16x32_bf16 v[66:69], v[180:183], v[212:215], v[66:69]
	s_barrier
	s_setprio 0
	s_add_i32 s74, s61, s34
	v_lshl_add_u64 v[216:217], s[46:47], 0, v[134:135]
	s_mov_b32 m0, s74
	ds_read_b128 v[184:187], v154 offset:16384
	ds_read_b128 v[188:191], v154 offset:17408
	ds_read_b128 v[192:195], v154 offset:18432
	ds_read_b128 v[196:199], v154 offset:19456
	ds_read_b128 v[200:203], v154 offset:20480
	ds_read_b128 v[204:207], v154 offset:21504
	ds_read_b128 v[208:211], v154 offset:22528
	ds_read_b128 v[212:215], v154 offset:23552
	global_load_lds_dwordx4 v[216:217], off
	s_add_i32 m0, s74, 0x2000
	s_add_u32 s74, s46, 0x80000
	v_lshl_add_u64 v[218:219], s[46:47], 0, v[130:131]
	s_addc_u32 s75, s47, 0
	s_add_i32 s76, s62, s34
	global_load_lds_dwordx4 v[218:219], off
	v_lshl_add_u64 v[220:221], s[74:75], 0, v[134:135]
	s_mov_b32 m0, s76
	v_lshl_add_u64 v[222:223], s[48:49], 0, v[132:133]
	global_load_lds_dwordx4 v[220:221], off
	v_lshl_add_u64 v[220:221], s[74:75], 0, v[130:131]
	s_add_i32 m0, s76, 0x2000
	s_nop 0
	global_load_lds_dwordx4 v[220:221], off
	v_lshl_add_u64 v[220:221], s[48:49], 0, v[136:137]
	s_mov_b32 m0, s43
	s_nop 0
	global_load_lds_dwordx4 v[220:221], off
	s_mov_b32 m0, s50
	s_nop 0
	global_load_lds_dwordx4 v[222:223], off
	s_waitcnt vmcnt(8)
	s_waitcnt lgkmcnt(0)
	s_setprio 1
	s_barrier
	v_mfma_f32_16x16x32_bf16 v[62:65], v[146:149], v[184:187], v[62:65]
	v_mfma_f32_16x16x32_bf16 v[58:61], v[160:163], v[184:187], v[58:61]
	v_mfma_f32_16x16x32_bf16 v[46:49], v[146:149], v[192:195], v[46:49]
	v_mfma_f32_16x16x32_bf16 v[42:45], v[160:163], v[192:195], v[42:45]
	v_mfma_f32_16x16x32_bf16 v[30:33], v[146:149], v[200:203], v[30:33]
	v_mfma_f32_16x16x32_bf16 v[26:29], v[160:163], v[200:203], v[26:29]
	v_mfma_f32_16x16x32_bf16 v[14:17], v[146:149], v[208:211], v[14:17]
	v_mfma_f32_16x16x32_bf16 v[10:13], v[160:163], v[208:211], v[10:13]
	v_mfma_f32_16x16x32_bf16 v[62:65], v[156:159], v[188:191], v[62:65]
	v_mfma_f32_16x16x32_bf16 v[58:61], v[164:167], v[188:191], v[58:61]
	v_mfma_f32_16x16x32_bf16 v[46:49], v[156:159], v[196:199], v[46:49]
	v_mfma_f32_16x16x32_bf16 v[42:45], v[164:167], v[196:199], v[42:45]
	v_mfma_f32_16x16x32_bf16 v[30:33], v[156:159], v[204:207], v[30:33]
	v_mfma_f32_16x16x32_bf16 v[26:29], v[164:167], v[204:207], v[26:29]
	v_mfma_f32_16x16x32_bf16 v[14:17], v[156:159], v[212:215], v[14:17]
	v_mfma_f32_16x16x32_bf16 v[10:13], v[164:167], v[212:215], v[10:13]
	s_setprio 0
	s_setprio 1
	v_mfma_f32_16x16x32_bf16 v[54:57], v[168:171], v[184:187], v[54:57]
	v_mfma_f32_16x16x32_bf16 v[50:53], v[176:179], v[184:187], v[50:53]
	v_mfma_f32_16x16x32_bf16 v[38:41], v[168:171], v[192:195], v[38:41]
	v_mfma_f32_16x16x32_bf16 v[34:37], v[176:179], v[192:195], v[34:37]
	v_mfma_f32_16x16x32_bf16 v[22:25], v[168:171], v[200:203], v[22:25]
	v_mfma_f32_16x16x32_bf16 v[18:21], v[176:179], v[200:203], v[18:21]
	v_mfma_f32_16x16x32_bf16 v[6:9], v[168:171], v[208:211], v[6:9]
	v_mfma_f32_16x16x32_bf16 v[2:5], v[176:179], v[208:211], v[2:5]
	v_mfma_f32_16x16x32_bf16 v[54:57], v[172:175], v[188:191], v[54:57]
	v_mfma_f32_16x16x32_bf16 v[50:53], v[180:183], v[188:191], v[50:53]
	v_mfma_f32_16x16x32_bf16 v[38:41], v[172:175], v[196:199], v[38:41]
	v_mfma_f32_16x16x32_bf16 v[34:37], v[180:183], v[196:199], v[34:37]
	v_mfma_f32_16x16x32_bf16 v[22:25], v[172:175], v[204:207], v[22:25]
	v_mfma_f32_16x16x32_bf16 v[18:21], v[180:183], v[204:207], v[18:21]
	v_mfma_f32_16x16x32_bf16 v[6:9], v[172:175], v[212:215], v[6:9]
	v_mfma_f32_16x16x32_bf16 v[2:5], v[180:183], v[212:215], v[2:5]
	s_barrier
	s_setprio 0
	s_add_i32 s74, 0, 0x18000
	v_add_u32_e32 v155, s74, v151
	s_add_i32 s75, 0, 0x1c000
	ds_read_b128 v[146:149], v155
	ds_read_b128 v[156:159], v155 offset:1024
	ds_read_b128 v[160:163], v155 offset:2048
	ds_read_b128 v[164:167], v155 offset:3072
	v_add_u32_e32 v155, s75, v151
	ds_read_b128 v[168:171], v155
	ds_read_b128 v[172:175], v155 offset:1024
	ds_read_b128 v[176:179], v155 offset:2048
	ds_read_b128 v[180:183], v155 offset:3072
	s_add_u32 s48, s48, 0x80000
	s_addc_u32 s49, s49, 0
	s_mov_b32 m0, s51
	v_lshl_add_u64 v[224:225], s[48:49], 0, v[136:137]
	ds_read_b128 v[184:187], v154 offset:32768
	ds_read_b128 v[188:191], v154 offset:33792
	ds_read_b128 v[192:195], v154 offset:34816
	ds_read_b128 v[196:199], v154 offset:35840
	ds_read_b128 v[200:203], v154 offset:36864
	ds_read_b128 v[204:207], v154 offset:37888
	ds_read_b128 v[208:211], v154 offset:38912
	ds_read_b128 v[212:215], v154 offset:39936
	global_load_lds_dwordx4 v[224:225], off
	v_lshl_add_u64 v[224:225], s[48:49], 0, v[132:133]
	s_mov_b32 m0, s52
	s_nop 0
	global_load_lds_dwordx4 v[224:225], off
	s_waitcnt vmcnt(8)
	s_waitcnt lgkmcnt(0)
	s_setprio 1
	s_barrier
	v_mfma_f32_16x16x32_bf16 v[126:129], v[146:149], v[184:187], v[126:129]
	v_mfma_f32_16x16x32_bf16 v[122:125], v[160:163], v[184:187], v[122:125]
	v_mfma_f32_16x16x32_bf16 v[110:113], v[146:149], v[192:195], v[110:113]
	v_mfma_f32_16x16x32_bf16 v[106:109], v[160:163], v[192:195], v[106:109]
	v_mfma_f32_16x16x32_bf16 v[94:97], v[146:149], v[200:203], v[94:97]
	v_mfma_f32_16x16x32_bf16 v[90:93], v[160:163], v[200:203], v[90:93]
	v_mfma_f32_16x16x32_bf16 v[78:81], v[146:149], v[208:211], v[78:81]
	v_mfma_f32_16x16x32_bf16 v[74:77], v[160:163], v[208:211], v[74:77]
	v_mfma_f32_16x16x32_bf16 v[126:129], v[156:159], v[188:191], v[126:129]
	v_mfma_f32_16x16x32_bf16 v[122:125], v[164:167], v[188:191], v[122:125]
	v_mfma_f32_16x16x32_bf16 v[110:113], v[156:159], v[196:199], v[110:113]
	v_mfma_f32_16x16x32_bf16 v[106:109], v[164:167], v[196:199], v[106:109]
	v_mfma_f32_16x16x32_bf16 v[94:97], v[156:159], v[204:207], v[94:97]
	v_mfma_f32_16x16x32_bf16 v[90:93], v[164:167], v[204:207], v[90:93]
	v_mfma_f32_16x16x32_bf16 v[78:81], v[156:159], v[212:215], v[78:81]
	v_mfma_f32_16x16x32_bf16 v[74:77], v[164:167], v[212:215], v[74:77]
	s_setprio 0
	s_setprio 1
	v_mfma_f32_16x16x32_bf16 v[118:121], v[168:171], v[184:187], v[118:121]
	v_mfma_f32_16x16x32_bf16 v[114:117], v[176:179], v[184:187], v[114:117]
	v_mfma_f32_16x16x32_bf16 v[102:105], v[168:171], v[192:195], v[102:105]
	v_mfma_f32_16x16x32_bf16 v[98:101], v[176:179], v[192:195], v[98:101]
	v_mfma_f32_16x16x32_bf16 v[86:89], v[168:171], v[200:203], v[86:89]
	v_mfma_f32_16x16x32_bf16 v[82:85], v[176:179], v[200:203], v[82:85]
	v_mfma_f32_16x16x32_bf16 v[70:73], v[168:171], v[208:211], v[70:73]
	v_mfma_f32_16x16x32_bf16 v[66:69], v[176:179], v[208:211], v[66:69]
	v_mfma_f32_16x16x32_bf16 v[118:121], v[172:175], v[188:191], v[118:121]
	v_mfma_f32_16x16x32_bf16 v[114:117], v[180:183], v[188:191], v[114:117]
	v_mfma_f32_16x16x32_bf16 v[102:105], v[172:175], v[196:199], v[102:105]
	v_mfma_f32_16x16x32_bf16 v[98:101], v[180:183], v[196:199], v[98:101]
	v_mfma_f32_16x16x32_bf16 v[86:89], v[172:175], v[204:207], v[86:89]
	v_mfma_f32_16x16x32_bf16 v[82:85], v[180:183], v[204:207], v[82:85]
	v_mfma_f32_16x16x32_bf16 v[70:73], v[172:175], v[212:215], v[70:73]
	v_mfma_f32_16x16x32_bf16 v[66:69], v[180:183], v[212:215], v[66:69]
	s_barrier
	s_setprio 0
	s_add_i32 s48, s74, s34
	v_lshl_add_u64 v[216:217], v[216:217], 0, s[12:13]
	s_mov_b32 m0, s48
	ds_read_b128 v[184:187], v154 offset:49152
	ds_read_b128 v[188:191], v154 offset:50176
	ds_read_b128 v[192:195], v154 offset:51200
	ds_read_b128 v[196:199], v154 offset:52224
	ds_read_b128 v[200:203], v154 offset:53248
	ds_read_b128 v[204:207], v154 offset:54272
	ds_read_b128 v[208:211], v154 offset:55296
	ds_read_b128 v[212:215], v154 offset:56320
	global_load_lds_dwordx4 v[216:217], off
	s_add_i32 m0, s48, 0x2000
	s_add_u32 s46, s46, 0x80080
	v_lshl_add_u64 v[216:217], v[218:219], 0, s[12:13]
	s_addc_u32 s47, s47, 0
	s_add_i32 s48, s75, s34
	global_load_lds_dwordx4 v[216:217], off
	v_lshl_add_u64 v[216:217], s[46:47], 0, v[134:135]
	s_mov_b32 m0, s48
	s_nop 0
	global_load_lds_dwordx4 v[216:217], off
	v_lshl_add_u64 v[216:217], s[46:47], 0, v[130:131]
	s_add_i32 m0, s48, 0x2000
	s_nop 0
	global_load_lds_dwordx4 v[216:217], off
	v_lshl_add_u64 v[216:217], v[220:221], 0, s[12:13]
	s_mov_b32 m0, s56
	s_nop 0
	global_load_lds_dwordx4 v[216:217], off
	v_lshl_add_u64 v[216:217], v[222:223], 0, s[12:13]
	s_mov_b32 m0, s57
	s_nop 0
	global_load_lds_dwordx4 v[216:217], off
	s_waitcnt vmcnt(8)
	s_waitcnt lgkmcnt(0)
	s_setprio 1
	s_barrier
	v_mfma_f32_16x16x32_bf16 v[62:65], v[146:149], v[184:187], v[62:65]
	v_mfma_f32_16x16x32_bf16 v[58:61], v[160:163], v[184:187], v[58:61]
	v_mfma_f32_16x16x32_bf16 v[46:49], v[146:149], v[192:195], v[46:49]
	v_mfma_f32_16x16x32_bf16 v[42:45], v[160:163], v[192:195], v[42:45]
	v_mfma_f32_16x16x32_bf16 v[30:33], v[146:149], v[200:203], v[30:33]
	v_mfma_f32_16x16x32_bf16 v[26:29], v[160:163], v[200:203], v[26:29]
	v_mfma_f32_16x16x32_bf16 v[14:17], v[146:149], v[208:211], v[14:17]
	v_mfma_f32_16x16x32_bf16 v[10:13], v[160:163], v[208:211], v[10:13]
	v_mfma_f32_16x16x32_bf16 v[62:65], v[156:159], v[188:191], v[62:65]
	v_mfma_f32_16x16x32_bf16 v[58:61], v[164:167], v[188:191], v[58:61]
	v_mfma_f32_16x16x32_bf16 v[46:49], v[156:159], v[196:199], v[46:49]
	v_mfma_f32_16x16x32_bf16 v[42:45], v[164:167], v[196:199], v[42:45]
	v_mfma_f32_16x16x32_bf16 v[30:33], v[156:159], v[204:207], v[30:33]
	v_mfma_f32_16x16x32_bf16 v[26:29], v[164:167], v[204:207], v[26:29]
	v_mfma_f32_16x16x32_bf16 v[14:17], v[156:159], v[212:215], v[14:17]
	v_mfma_f32_16x16x32_bf16 v[10:13], v[164:167], v[212:215], v[10:13]
	s_setprio 0
	s_setprio 1
	v_mfma_f32_16x16x32_bf16 v[54:57], v[168:171], v[184:187], v[54:57]
	v_mfma_f32_16x16x32_bf16 v[50:53], v[176:179], v[184:187], v[50:53]
	v_mfma_f32_16x16x32_bf16 v[38:41], v[168:171], v[192:195], v[38:41]
	v_mfma_f32_16x16x32_bf16 v[34:37], v[176:179], v[192:195], v[34:37]
	v_mfma_f32_16x16x32_bf16 v[22:25], v[168:171], v[200:203], v[22:25]
	v_mfma_f32_16x16x32_bf16 v[18:21], v[176:179], v[200:203], v[18:21]
	v_mfma_f32_16x16x32_bf16 v[6:9], v[168:171], v[208:211], v[6:9]
	v_mfma_f32_16x16x32_bf16 v[2:5], v[176:179], v[208:211], v[2:5]
	v_mfma_f32_16x16x32_bf16 v[54:57], v[172:175], v[188:191], v[54:57]
	v_mfma_f32_16x16x32_bf16 v[50:53], v[180:183], v[188:191], v[50:53]
	v_mfma_f32_16x16x32_bf16 v[38:41], v[172:175], v[196:199], v[38:41]
	v_mfma_f32_16x16x32_bf16 v[34:37], v[180:183], v[196:199], v[34:37]
	v_mfma_f32_16x16x32_bf16 v[22:25], v[172:175], v[204:207], v[22:25]
	v_mfma_f32_16x16x32_bf16 v[18:21], v[180:183], v[204:207], v[18:21]
	v_mfma_f32_16x16x32_bf16 v[6:9], v[172:175], v[212:215], v[6:9]
	v_mfma_f32_16x16x32_bf16 v[2:5], v[180:183], v[212:215], v[2:5]
	s_barrier
	s_setprio 0
	s_add_i32 s73, s73, 2
	s_add_u32 s71, s71, 0x100
	s_addc_u32 s72, s72, 0
	s_add_u32 s44, s44, 0x100
	s_addc_u32 s45, s45, 0
	s_cmp_gt_u32 s73, 29
	s_cbranch_scc0 .LBB0_1525
	s_and_b64 vcc, exec, s[14:15]
	s_cbranch_vccz .LBB0_1528
	s_barrier

.LBB0_1681:
	ds_read_b128 v[86:89], v220
	ds_read_b128 v[90:93], v220 offset:1024
	ds_read_b128 v[114:117], v220 offset:2048
	ds_read_b128 v[118:121], v220 offset:3072
	ds_read_b128 v[146:149], v221
	ds_read_b128 v[150:153], v221 offset:1024
	ds_read_b128 v[154:157], v221 offset:2048
	ds_read_b128 v[158:161], v221 offset:3072
	s_add_u32 s10, s8, 0xfffe0080
	s_addc_u32 s11, s9, -1
	s_cmp_eq_u32 s63, 4
	s_cselect_b32 s13, s7, s11
	s_cselect_b32 s12, s14, s10
	s_cselect_b32 s11, s15, s41
	s_cselect_b32 s10, s18, s39
	v_lshl_add_u64 v[208:209], s[8:9], 0, v[180:181]
	s_add_i32 m0, s47, 0xc000
	ds_read_b128 v[162:165], v222
	ds_read_b128 v[166:169], v222 offset:1024
	ds_read_b128 v[184:187], v222 offset:2048
	ds_read_b128 v[188:191], v222 offset:3072
	ds_read_b128 v[192:195], v222 offset:4096
	ds_read_b128 v[196:199], v222 offset:5120
	ds_read_b128 v[200:203], v222 offset:6144
	ds_read_b128 v[204:207], v222 offset:7168
	global_load_lds_dwordx4 v[208:209], off
	v_lshl_add_u64 v[208:209], s[8:9], 0, v[178:179]
	s_add_i32 m0, s47, 0xe000
	s_nop 0
	global_load_lds_dwordx4 v[208:209], off
	s_waitcnt vmcnt(8)
	s_waitcnt lgkmcnt(0)
	s_setprio 1
	s_barrier
	v_mfma_f32_16x16x32_bf16 v[142:145], v[86:89], v[162:165], v[142:145]
	v_mfma_f32_16x16x32_bf16 v[138:141], v[114:117], v[162:165], v[138:141]
	v_mfma_f32_16x16x32_bf16 v[126:129], v[86:89], v[184:187], v[126:129]
	v_mfma_f32_16x16x32_bf16 v[122:125], v[114:117], v[184:187], v[122:125]
	v_mfma_f32_16x16x32_bf16 v[102:105], v[86:89], v[192:195], v[102:105]
	v_mfma_f32_16x16x32_bf16 v[98:101], v[114:117], v[192:195], v[98:101]
	v_mfma_f32_16x16x32_bf16 v[78:81], v[86:89], v[200:203], v[78:81]
	v_mfma_f32_16x16x32_bf16 v[74:77], v[114:117], v[200:203], v[74:77]
	v_mfma_f32_16x16x32_bf16 v[142:145], v[90:93], v[166:169], v[142:145]
	v_mfma_f32_16x16x32_bf16 v[138:141], v[118:121], v[166:169], v[138:141]
	v_mfma_f32_16x16x32_bf16 v[126:129], v[90:93], v[188:191], v[126:129]
	v_mfma_f32_16x16x32_bf16 v[122:125], v[118:121], v[188:191], v[122:125]
	v_mfma_f32_16x16x32_bf16 v[102:105], v[90:93], v[196:199], v[102:105]
	v_mfma_f32_16x16x32_bf16 v[98:101], v[118:121], v[196:199], v[98:101]
	v_mfma_f32_16x16x32_bf16 v[78:81], v[90:93], v[204:207], v[78:81]
	v_mfma_f32_16x16x32_bf16 v[74:77], v[118:121], v[204:207], v[74:77]
	s_setprio 0
	s_setprio 1
	v_mfma_f32_16x16x32_bf16 v[134:137], v[146:149], v[162:165], v[134:137]
	v_mfma_f32_16x16x32_bf16 v[130:133], v[154:157], v[162:165], v[130:133]
	v_mfma_f32_16x16x32_bf16 v[110:113], v[146:149], v[184:187], v[110:113]
	v_mfma_f32_16x16x32_bf16 v[106:109], v[154:157], v[184:187], v[106:109]
	v_mfma_f32_16x16x32_bf16 v[94:97], v[146:149], v[192:195], v[94:97]
	v_mfma_f32_16x16x32_bf16 v[82:85], v[154:157], v[192:195], v[82:85]
	v_mfma_f32_16x16x32_bf16 v[70:73], v[146:149], v[200:203], v[70:73]
	v_mfma_f32_16x16x32_bf16 v[66:69], v[154:157], v[200:203], v[66:69]
	v_mfma_f32_16x16x32_bf16 v[134:137], v[150:153], v[166:169], v[134:137]
	v_mfma_f32_16x16x32_bf16 v[130:133], v[158:161], v[166:169], v[130:133]
	v_mfma_f32_16x16x32_bf16 v[110:113], v[150:153], v[188:191], v[110:113]
	v_mfma_f32_16x16x32_bf16 v[106:109], v[158:161], v[188:191], v[106:109]
	v_mfma_f32_16x16x32_bf16 v[94:97], v[150:153], v[196:199], v[94:97]
	v_mfma_f32_16x16x32_bf16 v[82:85], v[158:161], v[196:199], v[82:85]
	v_mfma_f32_16x16x32_bf16 v[70:73], v[150:153], v[204:207], v[70:73]
	v_mfma_f32_16x16x32_bf16 v[66:69], v[158:161], v[204:207], v[66:69]
	s_barrier
	s_setprio 0
	s_add_i32 s64, s60, s49
	v_lshl_add_u64 v[208:209], s[10:11], 0, v[172:173]
	s_mov_b32 m0, s64
	ds_read_b128 v[162:165], v222 offset:16384
	ds_read_b128 v[166:169], v222 offset:17408
	ds_read_b128 v[184:187], v222 offset:18432
	ds_read_b128 v[188:191], v222 offset:19456
	ds_read_b128 v[192:195], v222 offset:20480
	ds_read_b128 v[196:199], v222 offset:21504
	ds_read_b128 v[200:203], v222 offset:22528
	ds_read_b128 v[204:207], v222 offset:23552
	global_load_lds_dwordx4 v[208:209], off
	s_add_i32 m0, s64, 0x2000
	s_add_u32 s64, s10, 0x20000
	v_lshl_add_u64 v[210:211], s[10:11], 0, v[176:177]
	s_addc_u32 s65, s11, 0
	s_add_i32 s66, s61, s49
	global_load_lds_dwordx4 v[210:211], off
	v_lshl_add_u64 v[212:213], s[64:65], 0, v[172:173]
	s_mov_b32 m0, s66
	v_lshl_add_u64 v[214:215], s[12:13], 0, v[174:175]
	global_load_lds_dwordx4 v[212:213], off
	v_lshl_add_u64 v[212:213], s[64:65], 0, v[176:177]
	s_add_i32 m0, s66, 0x2000
	s_nop 0
	global_load_lds_dwordx4 v[212:213], off
	v_lshl_add_u64 v[212:213], s[12:13], 0, v[170:171]
	s_mov_b32 m0, s47
	s_nop 0
	global_load_lds_dwordx4 v[212:213], off
	s_mov_b32 m0, s50
	s_nop 0
	global_load_lds_dwordx4 v[214:215], off
	s_waitcnt vmcnt(8)
	s_waitcnt lgkmcnt(0)
	s_setprio 1
	s_barrier
	v_mfma_f32_16x16x32_bf16 v[62:65], v[86:89], v[162:165], v[62:65]
	v_mfma_f32_16x16x32_bf16 v[58:61], v[114:117], v[162:165], v[58:61]
	v_mfma_f32_16x16x32_bf16 v[46:49], v[86:89], v[184:187], v[46:49]
	v_mfma_f32_16x16x32_bf16 v[42:45], v[114:117], v[184:187], v[42:45]
	v_mfma_f32_16x16x32_bf16 v[30:33], v[86:89], v[192:195], v[30:33]
	v_mfma_f32_16x16x32_bf16 v[26:29], v[114:117], v[192:195], v[26:29]
	v_mfma_f32_16x16x32_bf16 v[14:17], v[86:89], v[200:203], v[14:17]
	v_mfma_f32_16x16x32_bf16 v[10:13], v[114:117], v[200:203], v[10:13]
	v_mfma_f32_16x16x32_bf16 v[62:65], v[90:93], v[166:169], v[62:65]
	v_mfma_f32_16x16x32_bf16 v[58:61], v[118:121], v[166:169], v[58:61]
	v_mfma_f32_16x16x32_bf16 v[46:49], v[90:93], v[188:191], v[46:49]
	v_mfma_f32_16x16x32_bf16 v[42:45], v[118:121], v[188:191], v[42:45]
	v_mfma_f32_16x16x32_bf16 v[30:33], v[90:93], v[196:199], v[30:33]
	v_mfma_f32_16x16x32_bf16 v[26:29], v[118:121], v[196:199], v[26:29]
	v_mfma_f32_16x16x32_bf16 v[14:17], v[90:93], v[204:207], v[14:17]
	v_mfma_f32_16x16x32_bf16 v[10:13], v[118:121], v[204:207], v[10:13]
	s_setprio 0
	s_setprio 1
	v_mfma_f32_16x16x32_bf16 v[54:57], v[146:149], v[162:165], v[54:57]
	v_mfma_f32_16x16x32_bf16 v[50:53], v[154:157], v[162:165], v[50:53]
	v_mfma_f32_16x16x32_bf16 v[38:41], v[146:149], v[184:187], v[38:41]
	v_mfma_f32_16x16x32_bf16 v[34:37], v[154:157], v[184:187], v[34:37]
	v_mfma_f32_16x16x32_bf16 v[22:25], v[146:149], v[192:195], v[22:25]
	v_mfma_f32_16x16x32_bf16 v[18:21], v[154:157], v[192:195], v[18:21]
	v_mfma_f32_16x16x32_bf16 v[6:9], v[146:149], v[200:203], v[6:9]
	v_mfma_f32_16x16x32_bf16 v[2:5], v[154:157], v[200:203], v[2:5]
	v_mfma_f32_16x16x32_bf16 v[54:57], v[150:153], v[166:169], v[54:57]
	v_mfma_f32_16x16x32_bf16 v[50:53], v[158:161], v[166:169], v[50:53]
	v_mfma_f32_16x16x32_bf16 v[38:41], v[150:153], v[188:191], v[38:41]
	v_mfma_f32_16x16x32_bf16 v[34:37], v[158:161], v[188:191], v[34:37]
	v_mfma_f32_16x16x32_bf16 v[22:25], v[150:153], v[196:199], v[22:25]
	v_mfma_f32_16x16x32_bf16 v[18:21], v[158:161], v[196:199], v[18:21]
	v_mfma_f32_16x16x32_bf16 v[6:9], v[150:153], v[204:207], v[6:9]
	v_mfma_f32_16x16x32_bf16 v[2:5], v[158:161], v[204:207], v[2:5]
	s_barrier
	s_setprio 0
	s_add_i32 s64, 0, 0x18000
	s_add_i32 s65, 0, 0x1c000
	v_add_u32_e32 v118, s64, v219
	v_add_u32_e32 v158, s65, v219
	ds_read_b128 v[86:89], v118
	ds_read_b128 v[90:93], v118 offset:1024
	ds_read_b128 v[114:117], v118 offset:2048
	ds_read_b128 v[118:121], v118 offset:3072
	ds_read_b128 v[146:149], v158
	ds_read_b128 v[150:153], v158 offset:1024
	ds_read_b128 v[154:157], v158 offset:2048
	ds_read_b128 v[158:161], v158 offset:3072
	s_add_u32 s12, s12, 0x20000
	s_addc_u32 s13, s13, 0
	s_mov_b32 m0, s51
	v_lshl_add_u64 v[216:217], s[12:13], 0, v[170:171]
	ds_read_b128 v[162:165], v222 offset:32768
	ds_read_b128 v[166:169], v222 offset:33792
	ds_read_b128 v[184:187], v222 offset:34816
	ds_read_b128 v[188:191], v222 offset:35840
	ds_read_b128 v[192:195], v222 offset:36864
	ds_read_b128 v[196:199], v222 offset:37888
	ds_read_b128 v[200:203], v222 offset:38912
	ds_read_b128 v[204:207], v222 offset:39936
	global_load_lds_dwordx4 v[216:217], off
	v_lshl_add_u64 v[216:217], s[12:13], 0, v[174:175]
	s_mov_b32 m0, s52
	s_nop 0
	global_load_lds_dwordx4 v[216:217], off
	s_waitcnt vmcnt(8)
	s_waitcnt lgkmcnt(0)
	s_setprio 1
	s_barrier
	v_mfma_f32_16x16x32_bf16 v[142:145], v[86:89], v[162:165], v[142:145]
	v_mfma_f32_16x16x32_bf16 v[138:141], v[114:117], v[162:165], v[138:141]
	v_mfma_f32_16x16x32_bf16 v[126:129], v[86:89], v[184:187], v[126:129]
	v_mfma_f32_16x16x32_bf16 v[122:125], v[114:117], v[184:187], v[122:125]
	v_mfma_f32_16x16x32_bf16 v[102:105], v[86:89], v[192:195], v[102:105]
	v_mfma_f32_16x16x32_bf16 v[98:101], v[114:117], v[192:195], v[98:101]
	v_mfma_f32_16x16x32_bf16 v[78:81], v[86:89], v[200:203], v[78:81]
	v_mfma_f32_16x16x32_bf16 v[74:77], v[114:117], v[200:203], v[74:77]
	v_mfma_f32_16x16x32_bf16 v[142:145], v[90:93], v[166:169], v[142:145]
	v_mfma_f32_16x16x32_bf16 v[138:141], v[118:121], v[166:169], v[138:141]
	v_mfma_f32_16x16x32_bf16 v[126:129], v[90:93], v[188:191], v[126:129]
	v_mfma_f32_16x16x32_bf16 v[122:125], v[118:121], v[188:191], v[122:125]
	v_mfma_f32_16x16x32_bf16 v[102:105], v[90:93], v[196:199], v[102:105]
	v_mfma_f32_16x16x32_bf16 v[98:101], v[118:121], v[196:199], v[98:101]
	v_mfma_f32_16x16x32_bf16 v[78:81], v[90:93], v[204:207], v[78:81]
	v_mfma_f32_16x16x32_bf16 v[74:77], v[118:121], v[204:207], v[74:77]
	s_setprio 0
	s_setprio 1
	v_mfma_f32_16x16x32_bf16 v[134:137], v[146:149], v[162:165], v[134:137]
	v_mfma_f32_16x16x32_bf16 v[130:133], v[154:157], v[162:165], v[130:133]
	v_mfma_f32_16x16x32_bf16 v[110:113], v[146:149], v[184:187], v[110:113]
	v_mfma_f32_16x16x32_bf16 v[106:109], v[154:157], v[184:187], v[106:109]
	v_mfma_f32_16x16x32_bf16 v[94:97], v[146:149], v[192:195], v[94:97]
	v_mfma_f32_16x16x32_bf16 v[82:85], v[154:157], v[192:195], v[82:85]
	v_mfma_f32_16x16x32_bf16 v[70:73], v[146:149], v[200:203], v[70:73]
	v_mfma_f32_16x16x32_bf16 v[66:69], v[154:157], v[200:203], v[66:69]
	v_mfma_f32_16x16x32_bf16 v[134:137], v[150:153], v[166:169], v[134:137]
	v_mfma_f32_16x16x32_bf16 v[130:133], v[158:161], v[166:169], v[130:133]
	v_mfma_f32_16x16x32_bf16 v[110:113], v[150:153], v[188:191], v[110:113]
	v_mfma_f32_16x16x32_bf16 v[106:109], v[158:161], v[188:191], v[106:109]
	v_mfma_f32_16x16x32_bf16 v[94:97], v[150:153], v[196:199], v[94:97]
	v_mfma_f32_16x16x32_bf16 v[82:85], v[158:161], v[196:199], v[82:85]
	v_mfma_f32_16x16x32_bf16 v[70:73], v[150:153], v[204:207], v[70:73]
	v_mfma_f32_16x16x32_bf16 v[66:69], v[158:161], v[204:207], v[66:69]
	s_barrier
	s_setprio 0
	s_add_i32 s12, s64, s49
	v_lshl_add_u64 v[208:209], v[208:209], 0, s[30:31]
	s_mov_b32 m0, s12
	ds_read_b128 v[162:165], v222 offset:49152
	ds_read_b128 v[166:169], v222 offset:50176
	ds_read_b128 v[184:187], v222 offset:51200
	ds_read_b128 v[188:191], v222 offset:52224
	ds_read_b128 v[192:195], v222 offset:53248
	ds_read_b128 v[196:199], v222 offset:54272
	ds_read_b128 v[200:203], v222 offset:55296
	ds_read_b128 v[204:207], v222 offset:56320
	global_load_lds_dwordx4 v[208:209], off
	s_add_i32 m0, s12, 0x2000
	s_add_u32 s10, s10, 0x20080
	v_lshl_add_u64 v[208:209], v[210:211], 0, s[30:31]
	s_addc_u32 s11, s11, 0
	s_add_i32 s12, s65, s49
	global_load_lds_dwordx4 v[208:209], off
	v_lshl_add_u64 v[208:209], s[10:11], 0, v[172:173]
	s_mov_b32 m0, s12
	s_nop 0
	global_load_lds_dwordx4 v[208:209], off
	v_lshl_add_u64 v[208:209], s[10:11], 0, v[176:177]
	s_add_i32 m0, s12, 0x2000
	s_nop 0
	global_load_lds_dwordx4 v[208:209], off
	v_lshl_add_u64 v[208:209], v[212:213], 0, s[30:31]
	s_mov_b32 m0, s56
	s_nop 0
	global_load_lds_dwordx4 v[208:209], off
	v_lshl_add_u64 v[208:209], v[214:215], 0, s[30:31]
	s_mov_b32 m0, s57
	s_nop 0
	global_load_lds_dwordx4 v[208:209], off
	s_waitcnt vmcnt(8)
	s_waitcnt lgkmcnt(0)
	s_setprio 1
	s_barrier
	v_mfma_f32_16x16x32_bf16 v[62:65], v[86:89], v[162:165], v[62:65]
	v_mfma_f32_16x16x32_bf16 v[58:61], v[114:117], v[162:165], v[58:61]
	v_mfma_f32_16x16x32_bf16 v[46:49], v[86:89], v[184:187], v[46:49]
	v_mfma_f32_16x16x32_bf16 v[42:45], v[114:117], v[184:187], v[42:45]
	v_mfma_f32_16x16x32_bf16 v[30:33], v[86:89], v[192:195], v[30:33]
	v_mfma_f32_16x16x32_bf16 v[26:29], v[114:117], v[192:195], v[26:29]
	v_mfma_f32_16x16x32_bf16 v[14:17], v[86:89], v[200:203], v[14:17]
	v_mfma_f32_16x16x32_bf16 v[10:13], v[114:117], v[200:203], v[10:13]
	v_mfma_f32_16x16x32_bf16 v[62:65], v[90:93], v[166:169], v[62:65]
	v_mfma_f32_16x16x32_bf16 v[58:61], v[118:121], v[166:169], v[58:61]
	v_mfma_f32_16x16x32_bf16 v[46:49], v[90:93], v[188:191], v[46:49]
	v_mfma_f32_16x16x32_bf16 v[42:45], v[118:121], v[188:191], v[42:45]
	v_mfma_f32_16x16x32_bf16 v[30:33], v[90:93], v[196:199], v[30:33]
	v_mfma_f32_16x16x32_bf16 v[26:29], v[118:121], v[196:199], v[26:29]
	v_mfma_f32_16x16x32_bf16 v[14:17], v[90:93], v[204:207], v[14:17]
	v_mfma_f32_16x16x32_bf16 v[10:13], v[118:121], v[204:207], v[10:13]
	s_setprio 0
	s_setprio 1
	v_mfma_f32_16x16x32_bf16 v[54:57], v[146:149], v[162:165], v[54:57]
	v_mfma_f32_16x16x32_bf16 v[50:53], v[154:157], v[162:165], v[50:53]
	v_mfma_f32_16x16x32_bf16 v[38:41], v[146:149], v[184:187], v[38:41]
	v_mfma_f32_16x16x32_bf16 v[34:37], v[154:157], v[184:187], v[34:37]
	v_mfma_f32_16x16x32_bf16 v[22:25], v[146:149], v[192:195], v[22:25]
	v_mfma_f32_16x16x32_bf16 v[18:21], v[154:157], v[192:195], v[18:21]
	v_mfma_f32_16x16x32_bf16 v[6:9], v[146:149], v[200:203], v[6:9]
	v_mfma_f32_16x16x32_bf16 v[2:5], v[154:157], v[200:203], v[2:5]
	v_mfma_f32_16x16x32_bf16 v[54:57], v[150:153], v[166:169], v[54:57]
	v_mfma_f32_16x16x32_bf16 v[50:53], v[158:161], v[166:169], v[50:53]
	v_mfma_f32_16x16x32_bf16 v[38:41], v[150:153], v[188:191], v[38:41]
	v_mfma_f32_16x16x32_bf16 v[34:37], v[158:161], v[188:191], v[34:37]
	v_mfma_f32_16x16x32_bf16 v[22:25], v[150:153], v[196:199], v[22:25]
	v_mfma_f32_16x16x32_bf16 v[18:21], v[158:161], v[196:199], v[18:21]
	v_mfma_f32_16x16x32_bf16 v[6:9], v[150:153], v[204:207], v[6:9]
	v_mfma_f32_16x16x32_bf16 v[2:5], v[158:161], v[204:207], v[2:5]
	s_barrier
	s_setprio 0
	s_add_i32 s63, s63, 2
	s_add_u32 s39, s39, 0x100
	s_addc_u32 s41, s41, 0
	s_add_u32 s8, s8, 0x100
	s_addc_u32 s9, s9, 0
	s_cmp_gt_u32 s63, 5
	s_cbranch_scc0 .LBB0_1681
	s_and_b64 vcc, exec, s[36:37]
	s_cbranch_vccz .LBB0_1684
	s_barrier

.LBB0_1706:
	s_lshl_b32 s10, s10, 5
	s_add_i32 s25, 0, 0x18000
	s_lshl_b32 s9, s11, 6
	s_and_b32 s10, s10, 0x60
	s_lshl_b32 s24, s11, 13
	s_add_i32 s11, s25, s22
	s_mov_b64 s[18:19], 0x80
	s_lshl_b32 s23, s10, 7
	v_lshl_add_u64 v[32:33], v[18:19], 0, s[18:19]
	s_mov_b32 m0, s11
	s_add_i32 s13, s11, 0x2000
	s_add_i32 s12, s20, 0x8000
	s_add_i32 s14, s20, 0xa000
	s_waitcnt vmcnt(2)
	s_barrier
	global_load_lds_dwordx4 v[32:33], off
	v_lshl_add_u64 v[38:39], v[20:21], 0, s[18:19]
	s_mov_b32 m0, s13
	s_add_u32 s4, s4, 0x20080
	global_load_lds_dwordx4 v[38:39], off
	v_lshl_add_u64 v[30:31], v[12:13], 0, s[18:19]
	s_mov_b32 m0, s12
	s_addc_u32 s5, s5, 0
	s_add_i32 s26, 0, 0x1c000
	global_load_lds_dwordx4 v[30:31], off
	v_lshl_add_u64 v[40:41], v[14:15], 0, s[18:19]
	s_mov_b32 m0, s14
	s_add_i32 s18, s26, s22
	global_load_lds_dwordx4 v[40:41], off
	v_lshl_add_u64 v[240:241], s[4:5], 0, v[22:23]
	s_mov_b32 m0, s18
	s_add_i32 s19, s18, 0x2000
	global_load_lds_dwordx4 v[240:241], off
	v_lshl_add_u64 v[242:243], s[4:5], 0, v[24:25]
	s_mov_b32 m0, s19
	v_bfe_u32 v1, v26, 4, 2
	global_load_lds_dwordx4 v[242:243], off
	v_and_b32_e32 v130, 15, v26
	v_lshlrev_b32_e32 v22, 4, v1
	v_lshlrev_b32_e32 v23, 2, v26
	v_lshl_or_b32 v22, v130, 6, v22
	v_and_b32_e32 v23, 32, v23
	v_bitop3_b32 v24, v22, s23, v23 bitop3:0xde
	v_bitop3_b32 v22, v22, s24, v23 bitop3:0xde
	s_add_i32 s23, 0, 0x10000
	s_add_i32 s24, 0, 0x14000
	v_add_u32_e32 v42, s23, v24
	v_add_u32_e32 v58, s24, v24
	s_waitcnt vmcnt(6)
	s_barrier
	v_add_u32_e32 v131, 0, v22
	v_add_u32_e32 v204, s25, v24
	v_add_u32_e32 v220, s26, v24
	ds_read_b128 v[22:25], v42
	ds_read_b128 v[26:29], v42 offset:1024
	ds_read_b128 v[34:37], v42 offset:2048
	ds_read_b128 v[42:45], v42 offset:3072
	ds_read_b128 v[46:49], v58
	ds_read_b128 v[50:53], v58 offset:1024
	ds_read_b128 v[54:57], v58 offset:2048
	ds_read_b128 v[58:61], v58 offset:3072
	s_add_u32 s6, s6, 0x20080
	s_addc_u32 s7, s7, 0
	s_add_i32 s23, s23, s22
	s_add_i32 s22, s24, s22
	s_mov_b32 s4, 0x8000
	s_mov_b32 s5, 0xc000
	s_add_i32 m0, s20, 0xc000
	s_add_i32 s25, s20, 0xe000
	s_add_i32 s26, s23, 0x2000
	s_add_i32 s24, s22, 0x2000
	s_cmpk_gt_u32 s17, 0xff
	v_lshl_add_u64 v[6:7], s[6:7], 0, v[6:7]
	ds_read_b128 v[62:65], v131
	ds_read_b128 v[66:69], v131 offset:1024
	ds_read_b128 v[70:73], v131 offset:2048
	ds_read_b128 v[74:77], v131 offset:3072
	ds_read_b128 v[78:81], v131 offset:4096
	ds_read_b128 v[82:85], v131 offset:5120
	ds_read_b128 v[86:89], v131 offset:6144
	ds_read_b128 v[90:93], v131 offset:7168
	global_load_lds_dwordx4 v[6:7], off
	v_lshl_add_u64 v[6:7], s[6:7], 0, v[8:9]
	s_mov_b32 m0, s25
	s_nop 0
	global_load_lds_dwordx4 v[6:7], off
	s_waitcnt vmcnt(8)
	s_waitcnt lgkmcnt(0)
	s_setprio 1
	s_barrier
	v_mfma_f32_16x16x32_bf16 v[6:9], v[22:25], v[62:65], 0
	v_mfma_f32_16x16x32_bf16 v[94:97], v[34:37], v[62:65], 0
	v_mfma_f32_16x16x32_bf16 v[98:101], v[22:25], v[70:73], 0
	v_mfma_f32_16x16x32_bf16 v[102:105], v[34:37], v[70:73], 0
	v_mfma_f32_16x16x32_bf16 v[106:109], v[22:25], v[78:81], 0
	v_mfma_f32_16x16x32_bf16 v[110:113], v[34:37], v[78:81], 0
	v_mfma_f32_16x16x32_bf16 v[114:117], v[22:25], v[86:89], 0
	v_mfma_f32_16x16x32_bf16 v[118:121], v[34:37], v[86:89], 0
	v_mfma_f32_16x16x32_bf16 v[6:9], v[26:29], v[66:69], v[6:9]
	v_mfma_f32_16x16x32_bf16 v[94:97], v[42:45], v[66:69], v[94:97]
	v_mfma_f32_16x16x32_bf16 v[98:101], v[26:29], v[74:77], v[98:101]
	v_mfma_f32_16x16x32_bf16 v[102:105], v[42:45], v[74:77], v[102:105]
	v_mfma_f32_16x16x32_bf16 v[106:109], v[26:29], v[82:85], v[106:109]
	v_mfma_f32_16x16x32_bf16 v[110:113], v[42:45], v[82:85], v[110:113]
	v_mfma_f32_16x16x32_bf16 v[114:117], v[26:29], v[90:93], v[114:117]
	v_mfma_f32_16x16x32_bf16 v[118:121], v[42:45], v[90:93], v[118:121]
	s_setprio 0
	s_setprio 1
	v_mfma_f32_16x16x32_bf16 v[122:125], v[46:49], v[62:65], 0
	v_mfma_f32_16x16x32_bf16 v[62:65], v[54:57], v[62:65], 0
	v_mfma_f32_16x16x32_bf16 v[122:125], v[50:53], v[66:69], v[122:125]
	v_mfma_f32_16x16x32_bf16 v[62:65], v[58:61], v[66:69], v[62:65]
	v_mfma_f32_16x16x32_bf16 v[66:69], v[46:49], v[70:73], 0
	v_mfma_f32_16x16x32_bf16 v[70:73], v[54:57], v[70:73], 0
	v_mfma_f32_16x16x32_bf16 v[66:69], v[50:53], v[74:77], v[66:69]
	v_mfma_f32_16x16x32_bf16 v[70:73], v[58:61], v[74:77], v[70:73]
	v_mfma_f32_16x16x32_bf16 v[74:77], v[46:49], v[78:81], 0
	v_mfma_f32_16x16x32_bf16 v[78:81], v[54:57], v[78:81], 0
	v_mfma_f32_16x16x32_bf16 v[74:77], v[50:53], v[82:85], v[74:77]
	v_mfma_f32_16x16x32_bf16 v[78:81], v[58:61], v[82:85], v[78:81]
	v_mfma_f32_16x16x32_bf16 v[82:85], v[46:49], v[86:89], 0
	v_mfma_f32_16x16x32_bf16 v[86:89], v[54:57], v[86:89], 0
	v_mfma_f32_16x16x32_bf16 v[82:85], v[50:53], v[90:93], v[82:85]
	v_mfma_f32_16x16x32_bf16 v[86:89], v[58:61], v[90:93], v[86:89]
	s_barrier
	s_setprio 0
	s_mov_b32 m0, s23
	ds_read_b128 v[90:93], v131 offset:16384
	ds_read_b128 v[126:129], v131 offset:17408
	ds_read_b128 v[132:135], v131 offset:18432
	ds_read_b128 v[136:139], v131 offset:19456
	ds_read_b128 v[140:143], v131 offset:20480
	ds_read_b128 v[144:147], v131 offset:21504
	ds_read_b128 v[148:151], v131 offset:22528
	ds_read_b128 v[152:155], v131 offset:23552
	global_load_lds_dwordx4 v[18:19], off
	s_mov_b32 m0, s26
	s_nop 0
	global_load_lds_dwordx4 v[20:21], off
	s_mov_b32 m0, s22
	s_nop 0
	global_load_lds_dwordx4 v[16:17], off
	s_mov_b32 m0, s24
	s_nop 0
	global_load_lds_dwordx4 v[10:11], off
	s_mov_b32 m0, s20
	s_nop 0
	global_load_lds_dwordx4 v[12:13], off
	s_mov_b32 m0, s21
	s_nop 0
	global_load_lds_dwordx4 v[14:15], off
	s_waitcnt vmcnt(8)
	s_waitcnt lgkmcnt(0)
	s_setprio 1
	s_barrier
	v_mfma_f32_16x16x32_bf16 v[10:13], v[22:25], v[90:93], 0
	v_mfma_f32_16x16x32_bf16 v[156:159], v[26:29], v[126:129], v[10:13]
	v_mfma_f32_16x16x32_bf16 v[10:13], v[34:37], v[90:93], 0
	v_mfma_f32_16x16x32_bf16 v[160:163], v[42:45], v[126:129], v[10:13]
	v_mfma_f32_16x16x32_bf16 v[10:13], v[22:25], v[132:135], 0
	v_mfma_f32_16x16x32_bf16 v[164:167], v[26:29], v[136:139], v[10:13]
	v_mfma_f32_16x16x32_bf16 v[10:13], v[34:37], v[132:135], 0
	v_mfma_f32_16x16x32_bf16 v[168:171], v[42:45], v[136:139], v[10:13]
	v_mfma_f32_16x16x32_bf16 v[10:13], v[22:25], v[140:143], 0
	v_mfma_f32_16x16x32_bf16 v[172:175], v[26:29], v[144:147], v[10:13]
	v_mfma_f32_16x16x32_bf16 v[10:13], v[34:37], v[140:143], 0
	v_mfma_f32_16x16x32_bf16 v[176:179], v[42:45], v[144:147], v[10:13]
	v_mfma_f32_16x16x32_bf16 v[10:13], v[22:25], v[148:151], 0
	v_mfma_f32_16x16x32_bf16 v[180:183], v[26:29], v[152:155], v[10:13]
	v_mfma_f32_16x16x32_bf16 v[10:13], v[34:37], v[148:151], 0
	v_mfma_f32_16x16x32_bf16 v[184:187], v[42:45], v[152:155], v[10:13]
	s_setprio 0
	s_setprio 1
	v_mfma_f32_16x16x32_bf16 v[10:13], v[46:49], v[90:93], 0
	v_mfma_f32_16x16x32_bf16 v[188:191], v[50:53], v[126:129], v[10:13]
	v_mfma_f32_16x16x32_bf16 v[10:13], v[54:57], v[90:93], 0
	v_mfma_f32_16x16x32_bf16 v[126:129], v[58:61], v[126:129], v[10:13]
	v_mfma_f32_16x16x32_bf16 v[10:13], v[46:49], v[132:135], 0
	v_mfma_f32_16x16x32_bf16 v[192:195], v[50:53], v[136:139], v[10:13]
	v_mfma_f32_16x16x32_bf16 v[10:13], v[54:57], v[132:135], 0
	v_mfma_f32_16x16x32_bf16 v[132:135], v[58:61], v[136:139], v[10:13]
	v_mfma_f32_16x16x32_bf16 v[10:13], v[46:49], v[140:143], 0
	v_mfma_f32_16x16x32_bf16 v[136:139], v[50:53], v[144:147], v[10:13]
	v_mfma_f32_16x16x32_bf16 v[10:13], v[54:57], v[140:143], 0
	v_mfma_f32_16x16x32_bf16 v[140:143], v[58:61], v[144:147], v[10:13]
	v_mfma_f32_16x16x32_bf16 v[10:13], v[46:49], v[148:151], 0
	v_mfma_f32_16x16x32_bf16 v[144:147], v[50:53], v[152:155], v[10:13]
	v_mfma_f32_16x16x32_bf16 v[10:13], v[54:57], v[148:151], 0
	v_mfma_f32_16x16x32_bf16 v[148:151], v[58:61], v[152:155], v[10:13]
	s_barrier
	s_setprio 0
	ds_read_b128 v[152:155], v204
	ds_read_b128 v[196:199], v204 offset:1024
	ds_read_b128 v[200:203], v204 offset:2048
	ds_read_b128 v[204:207], v204 offset:3072
	ds_read_b128 v[208:211], v220
	ds_read_b128 v[212:215], v220 offset:1024
	ds_read_b128 v[216:219], v220 offset:2048
	ds_read_b128 v[220:223], v220 offset:3072
	s_mov_b32 m0, s15
	ds_read_b128 v[26:29], v131 offset:32768
	ds_read_b128 v[34:37], v131 offset:33792
	ds_read_b128 v[50:53], v131 offset:34816
	ds_read_b128 v[54:57], v131 offset:35840
	ds_read_b128 v[58:61], v131 offset:36864
	ds_read_b128 v[224:227], v131 offset:37888
	ds_read_b128 v[228:231], v131 offset:38912
	ds_read_b128 v[232:235], v131 offset:39936
	global_load_lds_dwordx4 v[2:3], off
	s_mov_b32 m0, s16
	s_nop 0
	global_load_lds_dwordx4 v[4:5], off
	s_waitcnt vmcnt(8)
	s_waitcnt lgkmcnt(0)
	s_setprio 1
	s_barrier
	v_mfma_f32_16x16x32_bf16 v[2:5], v[152:155], v[26:29], v[6:9]
	v_mfma_f32_16x16x32_bf16 v[42:45], v[196:199], v[34:37], v[2:5]
	v_mfma_f32_16x16x32_bf16 v[2:5], v[200:203], v[26:29], v[94:97]
	v_mfma_f32_16x16x32_bf16 v[46:49], v[204:207], v[34:37], v[2:5]
	v_mfma_f32_16x16x32_bf16 v[2:5], v[152:155], v[50:53], v[98:101]
	v_mfma_f32_16x16x32_bf16 v[18:21], v[196:199], v[54:57], v[2:5]
	v_mfma_f32_16x16x32_bf16 v[2:5], v[200:203], v[50:53], v[102:105]
	v_mfma_f32_16x16x32_bf16 v[22:25], v[204:207], v[54:57], v[2:5]
	v_mfma_f32_16x16x32_bf16 v[2:5], v[152:155], v[58:61], v[106:109]
	v_mfma_f32_16x16x32_bf16 v[10:13], v[196:199], v[224:227], v[2:5]
	v_mfma_f32_16x16x32_bf16 v[2:5], v[200:203], v[58:61], v[110:113]
	v_mfma_f32_16x16x32_bf16 v[14:17], v[204:207], v[224:227], v[2:5]
	v_mfma_f32_16x16x32_bf16 v[2:5], v[152:155], v[228:231], v[114:117]
	v_mfma_f32_16x16x32_bf16 v[6:9], v[200:203], v[228:231], v[118:121]
	v_mfma_f32_16x16x32_bf16 v[2:5], v[196:199], v[232:235], v[2:5]
	v_mfma_f32_16x16x32_bf16 v[6:9], v[204:207], v[232:235], v[6:9]
	s_setprio 0
	s_setprio 1
	v_mfma_f32_16x16x32_bf16 v[90:93], v[208:211], v[26:29], v[122:125]
	v_mfma_f32_16x16x32_bf16 v[26:29], v[216:219], v[26:29], v[62:65]
	v_mfma_f32_16x16x32_bf16 v[94:97], v[220:223], v[34:37], v[26:29]
	v_mfma_f32_16x16x32_bf16 v[26:29], v[208:211], v[50:53], v[66:69]
	v_mfma_f32_16x16x32_bf16 v[66:69], v[212:215], v[54:57], v[26:29]
	v_mfma_f32_16x16x32_bf16 v[26:29], v[216:219], v[50:53], v[70:73]
	v_mfma_f32_16x16x32_bf16 v[70:73], v[220:223], v[54:57], v[26:29]
	v_mfma_f32_16x16x32_bf16 v[26:29], v[208:211], v[58:61], v[74:77]
	v_mfma_f32_16x16x32_bf16 v[50:53], v[212:215], v[224:227], v[26:29]
	v_mfma_f32_16x16x32_bf16 v[26:29], v[216:219], v[58:61], v[78:81]
	v_mfma_f32_16x16x32_bf16 v[90:93], v[212:215], v[34:37], v[90:93]
	v_mfma_f32_16x16x32_bf16 v[54:57], v[220:223], v[224:227], v[26:29]
	v_mfma_f32_16x16x32_bf16 v[26:29], v[208:211], v[228:231], v[82:85]
	v_mfma_f32_16x16x32_bf16 v[34:37], v[216:219], v[228:231], v[86:89]
	v_mfma_f32_16x16x32_bf16 v[26:29], v[212:215], v[232:235], v[26:29]
	v_mfma_f32_16x16x32_bf16 v[34:37], v[220:223], v[232:235], v[34:37]
	s_barrier
	s_setprio 0
	s_mov_b32 m0, s11
	ds_read_b128 v[82:85], v131 offset:49152
	ds_read_b128 v[86:89], v131 offset:50176
	ds_read_b128 v[106:109], v131 offset:51200
	ds_read_b128 v[110:113], v131 offset:52224
	ds_read_b128 v[224:227], v131 offset:53248
	ds_read_b128 v[228:231], v131 offset:54272
	ds_read_b128 v[232:235], v131 offset:55296
	ds_read_b128 v[236:239], v131 offset:56320
	global_load_lds_dwordx4 v[32:33], off
	s_mov_b32 m0, s13
	s_nop 0
	global_load_lds_dwordx4 v[38:39], off
	s_mov_b32 m0, s18
	s_nop 0
	global_load_lds_dwordx4 v[240:241], off
	s_mov_b32 m0, s19
	s_nop 0
	global_load_lds_dwordx4 v[242:243], off
	s_mov_b32 m0, s12
	s_nop 0
	global_load_lds_dwordx4 v[30:31], off
	s_mov_b32 m0, s14
	s_nop 0
	global_load_lds_dwordx4 v[40:41], off
	s_waitcnt vmcnt(8)
	s_waitcnt lgkmcnt(0)
	s_setprio 1
	s_barrier
	v_mfma_f32_16x16x32_bf16 v[30:33], v[152:155], v[82:85], v[156:159]
	v_mfma_f32_16x16x32_bf16 v[98:101], v[196:199], v[86:89], v[30:33]
	v_mfma_f32_16x16x32_bf16 v[30:33], v[200:203], v[82:85], v[160:163]
	v_mfma_f32_16x16x32_bf16 v[102:105], v[204:207], v[86:89], v[30:33]
	v_mfma_f32_16x16x32_bf16 v[30:33], v[152:155], v[106:109], v[164:167]
	v_mfma_f32_16x16x32_bf16 v[74:77], v[196:199], v[110:113], v[30:33]
	v_mfma_f32_16x16x32_bf16 v[30:33], v[200:203], v[106:109], v[168:171]
	v_mfma_f32_16x16x32_bf16 v[78:81], v[204:207], v[110:113], v[30:33]
	v_mfma_f32_16x16x32_bf16 v[30:33], v[152:155], v[224:227], v[172:175]
	v_mfma_f32_16x16x32_bf16 v[58:61], v[196:199], v[228:231], v[30:33]
	v_mfma_f32_16x16x32_bf16 v[30:33], v[200:203], v[224:227], v[176:179]
	v_mfma_f32_16x16x32_bf16 v[62:65], v[204:207], v[228:231], v[30:33]
	v_mfma_f32_16x16x32_bf16 v[30:33], v[152:155], v[232:235], v[180:183]
	v_mfma_f32_16x16x32_bf16 v[38:41], v[200:203], v[232:235], v[184:187]
	v_mfma_f32_16x16x32_bf16 v[30:33], v[196:199], v[236:239], v[30:33]
	v_mfma_f32_16x16x32_bf16 v[38:41], v[204:207], v[236:239], v[38:41]
	s_setprio 0
	s_setprio 1
	v_mfma_f32_16x16x32_bf16 v[114:117], v[208:211], v[82:85], v[188:191]
	v_mfma_f32_16x16x32_bf16 v[82:85], v[216:219], v[82:85], v[126:129]
	v_mfma_f32_16x16x32_bf16 v[126:129], v[220:223], v[86:89], v[82:85]
	v_mfma_f32_16x16x32_bf16 v[82:85], v[208:211], v[106:109], v[192:195]
	v_mfma_f32_16x16x32_bf16 v[122:125], v[212:215], v[86:89], v[114:117]
	v_mfma_f32_16x16x32_bf16 v[114:117], v[212:215], v[110:113], v[82:85]
	v_mfma_f32_16x16x32_bf16 v[82:85], v[216:219], v[106:109], v[132:135]
	v_mfma_f32_16x16x32_bf16 v[118:121], v[220:223], v[110:113], v[82:85]
	v_mfma_f32_16x16x32_bf16 v[82:85], v[208:211], v[224:227], v[136:139]
	v_mfma_f32_16x16x32_bf16 v[106:109], v[212:215], v[228:231], v[82:85]
	v_mfma_f32_16x16x32_bf16 v[82:85], v[216:219], v[224:227], v[140:143]
	v_mfma_f32_16x16x32_bf16 v[110:113], v[220:223], v[228:231], v[82:85]
	v_mfma_f32_16x16x32_bf16 v[82:85], v[208:211], v[232:235], v[144:147]
	v_mfma_f32_16x16x32_bf16 v[86:89], v[216:219], v[232:235], v[148:151]
	v_mfma_f32_16x16x32_bf16 v[82:85], v[212:215], v[236:239], v[82:85]
	v_mfma_f32_16x16x32_bf16 v[86:89], v[220:223], v[236:239], v[86:89]
	s_barrier
	s_setprio 0
	s_cbranch_scc1 .LBB0_1708
	s_barrier

.LBB0_1840:
	ds_read_b128 v[146:149], v152
	ds_read_b128 v[156:159], v152 offset:1024
	ds_read_b128 v[160:163], v152 offset:2048
	ds_read_b128 v[164:167], v152 offset:3072
	ds_read_b128 v[168:171], v153
	ds_read_b128 v[172:175], v153 offset:1024
	ds_read_b128 v[176:179], v153 offset:2048
	ds_read_b128 v[180:183], v153 offset:3072
	s_add_u32 s28, s26, 0xfff80080
	s_addc_u32 s29, s27, -1
	s_cmp_eq_u32 s54, 28
	s_cselect_b32 s31, s19, s29
	s_cselect_b32 s30, s50, s28
	s_cselect_b32 s29, s17, s53
	s_cselect_b32 s28, s51, s52
	v_lshl_add_u64 v[216:217], s[26:27], 0, v[140:141]
	s_add_i32 m0, s25, 0xc000
	ds_read_b128 v[184:187], v154
	ds_read_b128 v[188:191], v154 offset:1024
	ds_read_b128 v[192:195], v154 offset:2048
	ds_read_b128 v[196:199], v154 offset:3072
	ds_read_b128 v[200:203], v154 offset:4096
	ds_read_b128 v[204:207], v154 offset:5120
	ds_read_b128 v[208:211], v154 offset:6144
	ds_read_b128 v[212:215], v154 offset:7168
	global_load_lds_dwordx4 v[216:217], off
	v_lshl_add_u64 v[216:217], s[26:27], 0, v[138:139]
	s_add_i32 m0, s25, 0xe000
	s_nop 0
	global_load_lds_dwordx4 v[216:217], off
	s_waitcnt vmcnt(8)
	s_waitcnt lgkmcnt(0)
	s_setprio 1
	s_barrier
	v_mfma_f32_16x16x32_bf16 v[122:125], v[146:149], v[184:187], v[122:125]
	v_mfma_f32_16x16x32_bf16 v[118:121], v[160:163], v[184:187], v[118:121]
	v_mfma_f32_16x16x32_bf16 v[106:109], v[146:149], v[192:195], v[106:109]
	v_mfma_f32_16x16x32_bf16 v[102:105], v[160:163], v[192:195], v[102:105]
	v_mfma_f32_16x16x32_bf16 v[90:93], v[146:149], v[200:203], v[90:93]
	v_mfma_f32_16x16x32_bf16 v[86:89], v[160:163], v[200:203], v[86:89]
	v_mfma_f32_16x16x32_bf16 v[74:77], v[146:149], v[208:211], v[74:77]
	v_mfma_f32_16x16x32_bf16 v[70:73], v[160:163], v[208:211], v[70:73]
	v_mfma_f32_16x16x32_bf16 v[122:125], v[156:159], v[188:191], v[122:125]
	v_mfma_f32_16x16x32_bf16 v[118:121], v[164:167], v[188:191], v[118:121]
	v_mfma_f32_16x16x32_bf16 v[106:109], v[156:159], v[196:199], v[106:109]
	v_mfma_f32_16x16x32_bf16 v[102:105], v[164:167], v[196:199], v[102:105]
	v_mfma_f32_16x16x32_bf16 v[90:93], v[156:159], v[204:207], v[90:93]
	v_mfma_f32_16x16x32_bf16 v[86:89], v[164:167], v[204:207], v[86:89]
	v_mfma_f32_16x16x32_bf16 v[74:77], v[156:159], v[212:215], v[74:77]
	v_mfma_f32_16x16x32_bf16 v[70:73], v[164:167], v[212:215], v[70:73]
	s_setprio 0
	s_setprio 1
	v_mfma_f32_16x16x32_bf16 v[126:129], v[168:171], v[184:187], v[126:129]
	v_mfma_f32_16x16x32_bf16 v[114:117], v[176:179], v[184:187], v[114:117]
	v_mfma_f32_16x16x32_bf16 v[110:113], v[168:171], v[192:195], v[110:113]
	v_mfma_f32_16x16x32_bf16 v[98:101], v[176:179], v[192:195], v[98:101]
	v_mfma_f32_16x16x32_bf16 v[94:97], v[168:171], v[200:203], v[94:97]
	v_mfma_f32_16x16x32_bf16 v[82:85], v[176:179], v[200:203], v[82:85]
	v_mfma_f32_16x16x32_bf16 v[78:81], v[168:171], v[208:211], v[78:81]
	v_mfma_f32_16x16x32_bf16 v[66:69], v[176:179], v[208:211], v[66:69]
	v_mfma_f32_16x16x32_bf16 v[126:129], v[172:175], v[188:191], v[126:129]
	v_mfma_f32_16x16x32_bf16 v[114:117], v[180:183], v[188:191], v[114:117]
	v_mfma_f32_16x16x32_bf16 v[110:113], v[172:175], v[196:199], v[110:113]
	v_mfma_f32_16x16x32_bf16 v[98:101], v[180:183], v[196:199], v[98:101]
	v_mfma_f32_16x16x32_bf16 v[94:97], v[172:175], v[204:207], v[94:97]
	v_mfma_f32_16x16x32_bf16 v[82:85], v[180:183], v[204:207], v[82:85]
	v_mfma_f32_16x16x32_bf16 v[78:81], v[172:175], v[212:215], v[78:81]
	v_mfma_f32_16x16x32_bf16 v[66:69], v[180:183], v[212:215], v[66:69]
	s_barrier
	s_setprio 0
	s_add_i32 s55, s46, s34
	v_lshl_add_u64 v[216:217], s[28:29], 0, v[134:135]
	s_mov_b32 m0, s55
	ds_read_b128 v[184:187], v154 offset:16384
	ds_read_b128 v[188:191], v154 offset:17408
	ds_read_b128 v[192:195], v154 offset:18432
	ds_read_b128 v[196:199], v154 offset:19456
	ds_read_b128 v[200:203], v154 offset:20480
	ds_read_b128 v[204:207], v154 offset:21504
	ds_read_b128 v[208:211], v154 offset:22528
	ds_read_b128 v[212:215], v154 offset:23552
	global_load_lds_dwordx4 v[216:217], off
	s_add_i32 m0, s55, 0x2000
	s_add_u32 s56, s28, 0x80000
	v_lshl_add_u64 v[218:219], s[28:29], 0, v[130:131]
	s_addc_u32 s57, s29, 0
	s_add_i32 s55, s47, s34
	global_load_lds_dwordx4 v[218:219], off
	v_lshl_add_u64 v[220:221], s[56:57], 0, v[134:135]
	s_mov_b32 m0, s55
	v_lshl_add_u64 v[222:223], s[30:31], 0, v[132:133]
	global_load_lds_dwordx4 v[220:221], off
	v_lshl_add_u64 v[220:221], s[56:57], 0, v[130:131]
	s_add_i32 m0, s55, 0x2000
	s_nop 0
	global_load_lds_dwordx4 v[220:221], off
	v_lshl_add_u64 v[220:221], s[30:31], 0, v[136:137]
	s_mov_b32 m0, s25
	s_nop 0
	global_load_lds_dwordx4 v[220:221], off
	s_mov_b32 m0, s37
	s_nop 0
	global_load_lds_dwordx4 v[222:223], off
	s_waitcnt vmcnt(8)
	s_waitcnt lgkmcnt(0)
	s_setprio 1
	s_barrier
	v_mfma_f32_16x16x32_bf16 v[58:61], v[146:149], v[184:187], v[58:61]
	v_mfma_f32_16x16x32_bf16 v[54:57], v[160:163], v[184:187], v[54:57]
	v_mfma_f32_16x16x32_bf16 v[42:45], v[146:149], v[192:195], v[42:45]
	v_mfma_f32_16x16x32_bf16 v[38:41], v[160:163], v[192:195], v[38:41]
	v_mfma_f32_16x16x32_bf16 v[26:29], v[146:149], v[200:203], v[26:29]
	v_mfma_f32_16x16x32_bf16 v[22:25], v[160:163], v[200:203], v[22:25]
	v_mfma_f32_16x16x32_bf16 v[10:13], v[146:149], v[208:211], v[10:13]
	v_mfma_f32_16x16x32_bf16 v[6:9], v[160:163], v[208:211], v[6:9]
	v_mfma_f32_16x16x32_bf16 v[58:61], v[156:159], v[188:191], v[58:61]
	v_mfma_f32_16x16x32_bf16 v[54:57], v[164:167], v[188:191], v[54:57]
	v_mfma_f32_16x16x32_bf16 v[42:45], v[156:159], v[196:199], v[42:45]
	v_mfma_f32_16x16x32_bf16 v[38:41], v[164:167], v[196:199], v[38:41]
	v_mfma_f32_16x16x32_bf16 v[26:29], v[156:159], v[204:207], v[26:29]
	v_mfma_f32_16x16x32_bf16 v[22:25], v[164:167], v[204:207], v[22:25]
	v_mfma_f32_16x16x32_bf16 v[10:13], v[156:159], v[212:215], v[10:13]
	v_mfma_f32_16x16x32_bf16 v[6:9], v[164:167], v[212:215], v[6:9]
	s_setprio 0
	s_setprio 1
	v_mfma_f32_16x16x32_bf16 v[62:65], v[168:171], v[184:187], v[62:65]
	v_mfma_f32_16x16x32_bf16 v[50:53], v[176:179], v[184:187], v[50:53]
	v_mfma_f32_16x16x32_bf16 v[46:49], v[168:171], v[192:195], v[46:49]
	v_mfma_f32_16x16x32_bf16 v[34:37], v[176:179], v[192:195], v[34:37]
	v_mfma_f32_16x16x32_bf16 v[30:33], v[168:171], v[200:203], v[30:33]
	v_mfma_f32_16x16x32_bf16 v[18:21], v[176:179], v[200:203], v[18:21]
	v_mfma_f32_16x16x32_bf16 v[14:17], v[168:171], v[208:211], v[14:17]
	v_mfma_f32_16x16x32_bf16 v[2:5], v[176:179], v[208:211], v[2:5]
	v_mfma_f32_16x16x32_bf16 v[62:65], v[172:175], v[188:191], v[62:65]
	v_mfma_f32_16x16x32_bf16 v[50:53], v[180:183], v[188:191], v[50:53]
	v_mfma_f32_16x16x32_bf16 v[46:49], v[172:175], v[196:199], v[46:49]
	v_mfma_f32_16x16x32_bf16 v[34:37], v[180:183], v[196:199], v[34:37]
	v_mfma_f32_16x16x32_bf16 v[30:33], v[172:175], v[204:207], v[30:33]
	v_mfma_f32_16x16x32_bf16 v[18:21], v[180:183], v[204:207], v[18:21]
	v_mfma_f32_16x16x32_bf16 v[14:17], v[172:175], v[212:215], v[14:17]
	v_mfma_f32_16x16x32_bf16 v[2:5], v[180:183], v[212:215], v[2:5]
	s_barrier
	s_setprio 0
	s_add_i32 s55, 0, 0x18000
	v_add_u32_e32 v155, s55, v151
	s_add_i32 s56, 0, 0x1c000
	ds_read_b128 v[146:149], v155
	ds_read_b128 v[156:159], v155 offset:1024
	ds_read_b128 v[160:163], v155 offset:2048
	ds_read_b128 v[164:167], v155 offset:3072
	v_add_u32_e32 v155, s56, v151
	ds_read_b128 v[168:171], v155
	ds_read_b128 v[172:175], v155 offset:1024
	ds_read_b128 v[176:179], v155 offset:2048
	ds_read_b128 v[180:183], v155 offset:3072
	s_add_u32 s30, s30, 0x80000
	s_addc_u32 s31, s31, 0
	s_mov_b32 m0, s38
	v_lshl_add_u64 v[224:225], s[30:31], 0, v[136:137]
	ds_read_b128 v[184:187], v154 offset:32768
	ds_read_b128 v[188:191], v154 offset:33792
	ds_read_b128 v[192:195], v154 offset:34816
	ds_read_b128 v[196:199], v154 offset:35840
	ds_read_b128 v[200:203], v154 offset:36864
	ds_read_b128 v[204:207], v154 offset:37888
	ds_read_b128 v[208:211], v154 offset:38912
	ds_read_b128 v[212:215], v154 offset:39936
	global_load_lds_dwordx4 v[224:225], off
	v_lshl_add_u64 v[224:225], s[30:31], 0, v[132:133]
	s_mov_b32 m0, s39
	s_nop 0
	global_load_lds_dwordx4 v[224:225], off
	s_waitcnt vmcnt(8)
	s_waitcnt lgkmcnt(0)
	s_setprio 1
	s_barrier
	v_mfma_f32_16x16x32_bf16 v[122:125], v[146:149], v[184:187], v[122:125]
	v_mfma_f32_16x16x32_bf16 v[118:121], v[160:163], v[184:187], v[118:121]
	v_mfma_f32_16x16x32_bf16 v[106:109], v[146:149], v[192:195], v[106:109]
	v_mfma_f32_16x16x32_bf16 v[102:105], v[160:163], v[192:195], v[102:105]
	v_mfma_f32_16x16x32_bf16 v[90:93], v[146:149], v[200:203], v[90:93]
	v_mfma_f32_16x16x32_bf16 v[86:89], v[160:163], v[200:203], v[86:89]
	v_mfma_f32_16x16x32_bf16 v[74:77], v[146:149], v[208:211], v[74:77]
	v_mfma_f32_16x16x32_bf16 v[70:73], v[160:163], v[208:211], v[70:73]
	v_mfma_f32_16x16x32_bf16 v[122:125], v[156:159], v[188:191], v[122:125]
	v_mfma_f32_16x16x32_bf16 v[118:121], v[164:167], v[188:191], v[118:121]
	v_mfma_f32_16x16x32_bf16 v[106:109], v[156:159], v[196:199], v[106:109]
	v_mfma_f32_16x16x32_bf16 v[102:105], v[164:167], v[196:199], v[102:105]
	v_mfma_f32_16x16x32_bf16 v[90:93], v[156:159], v[204:207], v[90:93]
	v_mfma_f32_16x16x32_bf16 v[86:89], v[164:167], v[204:207], v[86:89]
	v_mfma_f32_16x16x32_bf16 v[74:77], v[156:159], v[212:215], v[74:77]
	v_mfma_f32_16x16x32_bf16 v[70:73], v[164:167], v[212:215], v[70:73]
	s_setprio 0
	s_setprio 1
	v_mfma_f32_16x16x32_bf16 v[126:129], v[168:171], v[184:187], v[126:129]
	v_mfma_f32_16x16x32_bf16 v[114:117], v[176:179], v[184:187], v[114:117]
	v_mfma_f32_16x16x32_bf16 v[110:113], v[168:171], v[192:195], v[110:113]
	v_mfma_f32_16x16x32_bf16 v[98:101], v[176:179], v[192:195], v[98:101]
	v_mfma_f32_16x16x32_bf16 v[94:97], v[168:171], v[200:203], v[94:97]
	v_mfma_f32_16x16x32_bf16 v[82:85], v[176:179], v[200:203], v[82:85]
	v_mfma_f32_16x16x32_bf16 v[78:81], v[168:171], v[208:211], v[78:81]
	v_mfma_f32_16x16x32_bf16 v[66:69], v[176:179], v[208:211], v[66:69]
	v_mfma_f32_16x16x32_bf16 v[126:129], v[172:175], v[188:191], v[126:129]
	v_mfma_f32_16x16x32_bf16 v[114:117], v[180:183], v[188:191], v[114:117]
	v_mfma_f32_16x16x32_bf16 v[110:113], v[172:175], v[196:199], v[110:113]
	v_mfma_f32_16x16x32_bf16 v[98:101], v[180:183], v[196:199], v[98:101]
	v_mfma_f32_16x16x32_bf16 v[94:97], v[172:175], v[204:207], v[94:97]
	v_mfma_f32_16x16x32_bf16 v[82:85], v[180:183], v[204:207], v[82:85]
	v_mfma_f32_16x16x32_bf16 v[78:81], v[172:175], v[212:215], v[78:81]
	v_mfma_f32_16x16x32_bf16 v[66:69], v[180:183], v[212:215], v[66:69]
	s_barrier
	s_setprio 0
	s_add_i32 s30, s55, s34
	v_lshl_add_u64 v[216:217], v[216:217], 0, s[12:13]
	s_mov_b32 m0, s30
	ds_read_b128 v[184:187], v154 offset:49152
	ds_read_b128 v[188:191], v154 offset:50176
	ds_read_b128 v[192:195], v154 offset:51200
	ds_read_b128 v[196:199], v154 offset:52224
	ds_read_b128 v[200:203], v154 offset:53248
	ds_read_b128 v[204:207], v154 offset:54272
	ds_read_b128 v[208:211], v154 offset:55296
	ds_read_b128 v[212:215], v154 offset:56320
	global_load_lds_dwordx4 v[216:217], off
	s_add_i32 m0, s30, 0x2000
	s_add_u32 s28, s28, 0x80080
	v_lshl_add_u64 v[216:217], v[218:219], 0, s[12:13]
	s_addc_u32 s29, s29, 0
	s_add_i32 s30, s56, s34
	global_load_lds_dwordx4 v[216:217], off
	v_lshl_add_u64 v[216:217], s[28:29], 0, v[134:135]
	s_mov_b32 m0, s30
	s_nop 0
	global_load_lds_dwordx4 v[216:217], off
	v_lshl_add_u64 v[216:217], s[28:29], 0, v[130:131]
	s_add_i32 m0, s30, 0x2000
	s_nop 0
	global_load_lds_dwordx4 v[216:217], off
	v_lshl_add_u64 v[216:217], v[220:221], 0, s[12:13]
	s_mov_b32 m0, s42
	s_nop 0
	global_load_lds_dwordx4 v[216:217], off
	v_lshl_add_u64 v[216:217], v[222:223], 0, s[12:13]
	s_mov_b32 m0, s43
	s_nop 0
	global_load_lds_dwordx4 v[216:217], off
	s_waitcnt vmcnt(8)
	s_waitcnt lgkmcnt(0)
	s_setprio 1
	s_barrier
	v_mfma_f32_16x16x32_bf16 v[58:61], v[146:149], v[184:187], v[58:61]
	v_mfma_f32_16x16x32_bf16 v[54:57], v[160:163], v[184:187], v[54:57]
	v_mfma_f32_16x16x32_bf16 v[42:45], v[146:149], v[192:195], v[42:45]
	v_mfma_f32_16x16x32_bf16 v[38:41], v[160:163], v[192:195], v[38:41]
	v_mfma_f32_16x16x32_bf16 v[26:29], v[146:149], v[200:203], v[26:29]
	v_mfma_f32_16x16x32_bf16 v[22:25], v[160:163], v[200:203], v[22:25]
	v_mfma_f32_16x16x32_bf16 v[10:13], v[146:149], v[208:211], v[10:13]
	v_mfma_f32_16x16x32_bf16 v[6:9], v[160:163], v[208:211], v[6:9]
	v_mfma_f32_16x16x32_bf16 v[58:61], v[156:159], v[188:191], v[58:61]
	v_mfma_f32_16x16x32_bf16 v[54:57], v[164:167], v[188:191], v[54:57]
	v_mfma_f32_16x16x32_bf16 v[42:45], v[156:159], v[196:199], v[42:45]
	v_mfma_f32_16x16x32_bf16 v[38:41], v[164:167], v[196:199], v[38:41]
	v_mfma_f32_16x16x32_bf16 v[26:29], v[156:159], v[204:207], v[26:29]
	v_mfma_f32_16x16x32_bf16 v[22:25], v[164:167], v[204:207], v[22:25]
	v_mfma_f32_16x16x32_bf16 v[10:13], v[156:159], v[212:215], v[10:13]
	v_mfma_f32_16x16x32_bf16 v[6:9], v[164:167], v[212:215], v[6:9]
	s_setprio 0
	s_setprio 1
	v_mfma_f32_16x16x32_bf16 v[62:65], v[168:171], v[184:187], v[62:65]
	v_mfma_f32_16x16x32_bf16 v[50:53], v[176:179], v[184:187], v[50:53]
	v_mfma_f32_16x16x32_bf16 v[46:49], v[168:171], v[192:195], v[46:49]
	v_mfma_f32_16x16x32_bf16 v[34:37], v[176:179], v[192:195], v[34:37]
	v_mfma_f32_16x16x32_bf16 v[30:33], v[168:171], v[200:203], v[30:33]
	v_mfma_f32_16x16x32_bf16 v[18:21], v[176:179], v[200:203], v[18:21]
	v_mfma_f32_16x16x32_bf16 v[14:17], v[168:171], v[208:211], v[14:17]
	v_mfma_f32_16x16x32_bf16 v[2:5], v[176:179], v[208:211], v[2:5]
	v_mfma_f32_16x16x32_bf16 v[62:65], v[172:175], v[188:191], v[62:65]
	v_mfma_f32_16x16x32_bf16 v[50:53], v[180:183], v[188:191], v[50:53]
	v_mfma_f32_16x16x32_bf16 v[46:49], v[172:175], v[196:199], v[46:49]
	v_mfma_f32_16x16x32_bf16 v[34:37], v[180:183], v[196:199], v[34:37]
	v_mfma_f32_16x16x32_bf16 v[30:33], v[172:175], v[204:207], v[30:33]
	v_mfma_f32_16x16x32_bf16 v[18:21], v[180:183], v[204:207], v[18:21]
	v_mfma_f32_16x16x32_bf16 v[14:17], v[172:175], v[212:215], v[14:17]
	v_mfma_f32_16x16x32_bf16 v[2:5], v[180:183], v[212:215], v[2:5]
	s_barrier
	s_setprio 0
	s_add_i32 s54, s54, 2
	s_add_u32 s52, s52, 0x100
	s_addc_u32 s53, s53, 0
	s_add_u32 s26, s26, 0x100
	s_addc_u32 s27, s27, 0
	s_cmp_gt_u32 s54, 29
	s_cbranch_scc0 .LBB0_1840
	s_and_b64 vcc, exec, s[14:15]
	s_cbranch_vccz .LBB0_1843
	s_barrier

.LBB0_1919:
	ds_read_b128 v[82:85], v220
	ds_read_b128 v[86:89], v220 offset:1024
	ds_read_b128 v[106:109], v220 offset:2048
	ds_read_b128 v[110:113], v220 offset:3072
	ds_read_b128 v[146:149], v221
	ds_read_b128 v[150:153], v221 offset:1024
	ds_read_b128 v[154:157], v221 offset:2048
	ds_read_b128 v[158:161], v221 offset:3072
	s_add_u32 s6, s8, 0x100
	s_addc_u32 s7, s9, 0
	s_cmpk_eq_i32 s61, 0x54
	s_cselect_b32 s13, s39, s7
	s_cselect_b32 s12, s38, s6
	s_cselect_b32 s11, s41, s18
	s_cselect_b32 s10, s40, s15
	v_lshl_add_u64 v[208:209], s[8:9], 0, v[180:181]
	s_add_i32 m0, s44, 0xc000
	ds_read_b128 v[162:165], v222
	ds_read_b128 v[166:169], v222 offset:1024
	ds_read_b128 v[184:187], v222 offset:2048
	ds_read_b128 v[188:191], v222 offset:3072
	ds_read_b128 v[192:195], v222 offset:4096
	ds_read_b128 v[196:199], v222 offset:5120
	ds_read_b128 v[200:203], v222 offset:6144
	ds_read_b128 v[204:207], v222 offset:7168
	global_load_lds_dwordx4 v[208:209], off
	v_lshl_add_u64 v[208:209], s[8:9], 0, v[178:179]
	s_add_i32 m0, s44, 0xe000
	s_nop 0
	global_load_lds_dwordx4 v[208:209], off
	s_waitcnt vmcnt(8)
	s_waitcnt lgkmcnt(0)
	s_setprio 1
	s_barrier
	v_mfma_f32_16x16x32_bf16 v[142:145], v[82:85], v[162:165], v[142:145]
	v_mfma_f32_16x16x32_bf16 v[138:141], v[106:109], v[162:165], v[138:141]
	v_mfma_f32_16x16x32_bf16 v[126:129], v[82:85], v[184:187], v[126:129]
	v_mfma_f32_16x16x32_bf16 v[122:125], v[106:109], v[184:187], v[122:125]
	v_mfma_f32_16x16x32_bf16 v[102:105], v[82:85], v[192:195], v[102:105]
	v_mfma_f32_16x16x32_bf16 v[98:101], v[106:109], v[192:195], v[98:101]
	v_mfma_f32_16x16x32_bf16 v[78:81], v[82:85], v[200:203], v[78:81]
	v_mfma_f32_16x16x32_bf16 v[74:77], v[106:109], v[200:203], v[74:77]
	v_mfma_f32_16x16x32_bf16 v[142:145], v[86:89], v[166:169], v[142:145]
	v_mfma_f32_16x16x32_bf16 v[138:141], v[110:113], v[166:169], v[138:141]
	v_mfma_f32_16x16x32_bf16 v[126:129], v[86:89], v[188:191], v[126:129]
	v_mfma_f32_16x16x32_bf16 v[122:125], v[110:113], v[188:191], v[122:125]
	v_mfma_f32_16x16x32_bf16 v[102:105], v[86:89], v[196:199], v[102:105]
	v_mfma_f32_16x16x32_bf16 v[98:101], v[110:113], v[196:199], v[98:101]
	v_mfma_f32_16x16x32_bf16 v[78:81], v[86:89], v[204:207], v[78:81]
	v_mfma_f32_16x16x32_bf16 v[74:77], v[110:113], v[204:207], v[74:77]
	s_setprio 0
	s_setprio 1
	v_mfma_f32_16x16x32_bf16 v[134:137], v[146:149], v[162:165], v[134:137]
	v_mfma_f32_16x16x32_bf16 v[130:133], v[154:157], v[162:165], v[130:133]
	v_mfma_f32_16x16x32_bf16 v[118:121], v[146:149], v[184:187], v[118:121]
	v_mfma_f32_16x16x32_bf16 v[114:117], v[154:157], v[184:187], v[114:117]
	v_mfma_f32_16x16x32_bf16 v[94:97], v[146:149], v[192:195], v[94:97]
	v_mfma_f32_16x16x32_bf16 v[90:93], v[154:157], v[192:195], v[90:93]
	v_mfma_f32_16x16x32_bf16 v[70:73], v[146:149], v[200:203], v[70:73]
	v_mfma_f32_16x16x32_bf16 v[66:69], v[154:157], v[200:203], v[66:69]
	v_mfma_f32_16x16x32_bf16 v[134:137], v[150:153], v[166:169], v[134:137]
	v_mfma_f32_16x16x32_bf16 v[130:133], v[158:161], v[166:169], v[130:133]
	v_mfma_f32_16x16x32_bf16 v[118:121], v[150:153], v[188:191], v[118:121]
	v_mfma_f32_16x16x32_bf16 v[114:117], v[158:161], v[188:191], v[114:117]
	v_mfma_f32_16x16x32_bf16 v[94:97], v[150:153], v[196:199], v[94:97]
	v_mfma_f32_16x16x32_bf16 v[90:93], v[158:161], v[196:199], v[90:93]
	v_mfma_f32_16x16x32_bf16 v[70:73], v[150:153], v[204:207], v[70:73]
	v_mfma_f32_16x16x32_bf16 v[66:69], v[158:161], v[204:207], v[66:69]
	s_barrier
	s_setprio 0
	s_add_i32 s8, s55, s43
	v_lshl_add_u64 v[208:209], s[10:11], 0, v[172:173]
	s_mov_b32 m0, s8
	ds_read_b128 v[162:165], v222 offset:16384
	ds_read_b128 v[166:169], v222 offset:17408
	ds_read_b128 v[184:187], v222 offset:18432
	ds_read_b128 v[188:191], v222 offset:19456
	ds_read_b128 v[192:195], v222 offset:20480
	ds_read_b128 v[196:199], v222 offset:21504
	ds_read_b128 v[200:203], v222 offset:22528
	ds_read_b128 v[204:207], v222 offset:23552
	global_load_lds_dwordx4 v[208:209], off
	s_add_i32 m0, s8, 0x2000
	s_add_u32 s8, s10, 0x160000
	v_lshl_add_u64 v[210:211], s[10:11], 0, v[176:177]
	s_addc_u32 s9, s11, 0
	s_add_i32 s62, s56, s43
	global_load_lds_dwordx4 v[210:211], off
	v_lshl_add_u64 v[212:213], s[8:9], 0, v[172:173]
	s_mov_b32 m0, s62
	v_lshl_add_u64 v[214:215], s[12:13], 0, v[174:175]
	global_load_lds_dwordx4 v[212:213], off
	v_lshl_add_u64 v[212:213], s[8:9], 0, v[176:177]
	s_add_i32 m0, s62, 0x2000
	s_nop 0
	global_load_lds_dwordx4 v[212:213], off
	v_lshl_add_u64 v[212:213], s[12:13], 0, v[170:171]
	s_mov_b32 m0, s44
	s_nop 0
	global_load_lds_dwordx4 v[212:213], off
	s_mov_b32 m0, s45
	s_nop 0
	global_load_lds_dwordx4 v[214:215], off
	s_waitcnt vmcnt(8)
	s_waitcnt lgkmcnt(0)
	s_setprio 1
	s_barrier
	v_mfma_f32_16x16x32_bf16 v[62:65], v[82:85], v[162:165], v[62:65]
	v_mfma_f32_16x16x32_bf16 v[58:61], v[106:109], v[162:165], v[58:61]
	v_mfma_f32_16x16x32_bf16 v[46:49], v[82:85], v[184:187], v[46:49]
	v_mfma_f32_16x16x32_bf16 v[42:45], v[106:109], v[184:187], v[42:45]
	v_mfma_f32_16x16x32_bf16 v[30:33], v[82:85], v[192:195], v[30:33]
	v_mfma_f32_16x16x32_bf16 v[26:29], v[106:109], v[192:195], v[26:29]
	v_mfma_f32_16x16x32_bf16 v[14:17], v[82:85], v[200:203], v[14:17]
	v_mfma_f32_16x16x32_bf16 v[10:13], v[106:109], v[200:203], v[10:13]
	v_mfma_f32_16x16x32_bf16 v[62:65], v[86:89], v[166:169], v[62:65]
	v_mfma_f32_16x16x32_bf16 v[58:61], v[110:113], v[166:169], v[58:61]
	v_mfma_f32_16x16x32_bf16 v[46:49], v[86:89], v[188:191], v[46:49]
	v_mfma_f32_16x16x32_bf16 v[42:45], v[110:113], v[188:191], v[42:45]
	v_mfma_f32_16x16x32_bf16 v[30:33], v[86:89], v[196:199], v[30:33]
	v_mfma_f32_16x16x32_bf16 v[26:29], v[110:113], v[196:199], v[26:29]
	v_mfma_f32_16x16x32_bf16 v[14:17], v[86:89], v[204:207], v[14:17]
	v_mfma_f32_16x16x32_bf16 v[10:13], v[110:113], v[204:207], v[10:13]
	s_setprio 0
	s_setprio 1
	v_mfma_f32_16x16x32_bf16 v[54:57], v[146:149], v[162:165], v[54:57]
	v_mfma_f32_16x16x32_bf16 v[50:53], v[154:157], v[162:165], v[50:53]
	v_mfma_f32_16x16x32_bf16 v[38:41], v[146:149], v[184:187], v[38:41]
	v_mfma_f32_16x16x32_bf16 v[34:37], v[154:157], v[184:187], v[34:37]
	v_mfma_f32_16x16x32_bf16 v[22:25], v[146:149], v[192:195], v[22:25]
	v_mfma_f32_16x16x32_bf16 v[18:21], v[154:157], v[192:195], v[18:21]
	v_mfma_f32_16x16x32_bf16 v[6:9], v[146:149], v[200:203], v[6:9]
	v_mfma_f32_16x16x32_bf16 v[2:5], v[154:157], v[200:203], v[2:5]
	v_mfma_f32_16x16x32_bf16 v[54:57], v[150:153], v[166:169], v[54:57]
	v_mfma_f32_16x16x32_bf16 v[50:53], v[158:161], v[166:169], v[50:53]
	v_mfma_f32_16x16x32_bf16 v[38:41], v[150:153], v[188:191], v[38:41]
	v_mfma_f32_16x16x32_bf16 v[34:37], v[158:161], v[188:191], v[34:37]
	v_mfma_f32_16x16x32_bf16 v[22:25], v[150:153], v[196:199], v[22:25]
	v_mfma_f32_16x16x32_bf16 v[18:21], v[158:161], v[196:199], v[18:21]
	v_mfma_f32_16x16x32_bf16 v[6:9], v[150:153], v[204:207], v[6:9]
	v_mfma_f32_16x16x32_bf16 v[2:5], v[158:161], v[204:207], v[2:5]
	s_barrier
	s_setprio 0
	s_add_i32 s62, 0, 0x18000
	s_add_i32 s63, 0, 0x1c000
	v_add_u32_e32 v110, s62, v219
	v_add_u32_e32 v158, s63, v219
	ds_read_b128 v[82:85], v110
	ds_read_b128 v[86:89], v110 offset:1024
	ds_read_b128 v[106:109], v110 offset:2048
	ds_read_b128 v[110:113], v110 offset:3072
	ds_read_b128 v[146:149], v158
	ds_read_b128 v[150:153], v158 offset:1024
	ds_read_b128 v[154:157], v158 offset:2048
	ds_read_b128 v[158:161], v158 offset:3072
	s_add_u32 s8, s12, 0x160000
	s_addc_u32 s9, s13, 0
	s_mov_b32 m0, s46
	v_lshl_add_u64 v[216:217], s[8:9], 0, v[170:171]
	ds_read_b128 v[162:165], v222 offset:32768
	ds_read_b128 v[166:169], v222 offset:33792
	ds_read_b128 v[184:187], v222 offset:34816
	ds_read_b128 v[188:191], v222 offset:35840
	ds_read_b128 v[192:195], v222 offset:36864
	ds_read_b128 v[196:199], v222 offset:37888
	ds_read_b128 v[200:203], v222 offset:38912
	ds_read_b128 v[204:207], v222 offset:39936
	global_load_lds_dwordx4 v[216:217], off
	v_lshl_add_u64 v[216:217], s[8:9], 0, v[174:175]
	s_mov_b32 m0, s47
	s_nop 0
	global_load_lds_dwordx4 v[216:217], off
	s_waitcnt vmcnt(8)
	s_waitcnt lgkmcnt(0)
	s_setprio 1
	s_barrier
	v_mfma_f32_16x16x32_bf16 v[142:145], v[82:85], v[162:165], v[142:145]
	v_mfma_f32_16x16x32_bf16 v[138:141], v[106:109], v[162:165], v[138:141]
	v_mfma_f32_16x16x32_bf16 v[126:129], v[82:85], v[184:187], v[126:129]
	v_mfma_f32_16x16x32_bf16 v[122:125], v[106:109], v[184:187], v[122:125]
	v_mfma_f32_16x16x32_bf16 v[102:105], v[82:85], v[192:195], v[102:105]
	v_mfma_f32_16x16x32_bf16 v[98:101], v[106:109], v[192:195], v[98:101]
	v_mfma_f32_16x16x32_bf16 v[78:81], v[82:85], v[200:203], v[78:81]
	v_mfma_f32_16x16x32_bf16 v[74:77], v[106:109], v[200:203], v[74:77]
	v_mfma_f32_16x16x32_bf16 v[142:145], v[86:89], v[166:169], v[142:145]
	v_mfma_f32_16x16x32_bf16 v[138:141], v[110:113], v[166:169], v[138:141]
	v_mfma_f32_16x16x32_bf16 v[126:129], v[86:89], v[188:191], v[126:129]
	v_mfma_f32_16x16x32_bf16 v[122:125], v[110:113], v[188:191], v[122:125]
	v_mfma_f32_16x16x32_bf16 v[102:105], v[86:89], v[196:199], v[102:105]
	v_mfma_f32_16x16x32_bf16 v[98:101], v[110:113], v[196:199], v[98:101]
	v_mfma_f32_16x16x32_bf16 v[78:81], v[86:89], v[204:207], v[78:81]
	v_mfma_f32_16x16x32_bf16 v[74:77], v[110:113], v[204:207], v[74:77]
	s_setprio 0
	s_setprio 1
	v_mfma_f32_16x16x32_bf16 v[134:137], v[146:149], v[162:165], v[134:137]
	v_mfma_f32_16x16x32_bf16 v[130:133], v[154:157], v[162:165], v[130:133]
	v_mfma_f32_16x16x32_bf16 v[118:121], v[146:149], v[184:187], v[118:121]
	v_mfma_f32_16x16x32_bf16 v[114:117], v[154:157], v[184:187], v[114:117]
	v_mfma_f32_16x16x32_bf16 v[94:97], v[146:149], v[192:195], v[94:97]
	v_mfma_f32_16x16x32_bf16 v[90:93], v[154:157], v[192:195], v[90:93]
	v_mfma_f32_16x16x32_bf16 v[70:73], v[146:149], v[200:203], v[70:73]
	v_mfma_f32_16x16x32_bf16 v[66:69], v[154:157], v[200:203], v[66:69]
	v_mfma_f32_16x16x32_bf16 v[134:137], v[150:153], v[166:169], v[134:137]
	v_mfma_f32_16x16x32_bf16 v[130:133], v[158:161], v[166:169], v[130:133]
	v_mfma_f32_16x16x32_bf16 v[118:121], v[150:153], v[188:191], v[118:121]
	v_mfma_f32_16x16x32_bf16 v[114:117], v[158:161], v[188:191], v[114:117]
	v_mfma_f32_16x16x32_bf16 v[94:97], v[150:153], v[196:199], v[94:97]
	v_mfma_f32_16x16x32_bf16 v[90:93], v[158:161], v[196:199], v[90:93]
	v_mfma_f32_16x16x32_bf16 v[70:73], v[150:153], v[204:207], v[70:73]
	v_mfma_f32_16x16x32_bf16 v[66:69], v[158:161], v[204:207], v[66:69]
	s_barrier
	s_setprio 0
	s_add_i32 s8, s62, s43
	v_lshl_add_u64 v[208:209], v[208:209], 0, s[30:31]
	s_mov_b32 m0, s8
	ds_read_b128 v[162:165], v222 offset:49152
	ds_read_b128 v[166:169], v222 offset:50176
	ds_read_b128 v[184:187], v222 offset:51200
	ds_read_b128 v[188:191], v222 offset:52224
	ds_read_b128 v[192:195], v222 offset:53248
	ds_read_b128 v[196:199], v222 offset:54272
	ds_read_b128 v[200:203], v222 offset:55296
	ds_read_b128 v[204:207], v222 offset:56320
	global_load_lds_dwordx4 v[208:209], off
	s_add_i32 m0, s8, 0x2000
	s_add_u32 s8, s10, 0x160080
	v_lshl_add_u64 v[208:209], v[210:211], 0, s[30:31]
	s_addc_u32 s9, s11, 0
	s_add_i32 s10, s63, s43
	global_load_lds_dwordx4 v[208:209], off
	v_lshl_add_u64 v[208:209], s[8:9], 0, v[172:173]
	s_mov_b32 m0, s10
	s_nop 0
	global_load_lds_dwordx4 v[208:209], off
	v_lshl_add_u64 v[208:209], s[8:9], 0, v[176:177]
	s_add_i32 m0, s10, 0x2000
	s_nop 0
	global_load_lds_dwordx4 v[208:209], off
	v_lshl_add_u64 v[208:209], v[212:213], 0, s[30:31]
	s_mov_b32 m0, s51
	s_nop 0
	global_load_lds_dwordx4 v[208:209], off
	v_lshl_add_u64 v[208:209], v[214:215], 0, s[30:31]
	s_mov_b32 m0, s52
	s_nop 0
	global_load_lds_dwordx4 v[208:209], off
	s_waitcnt vmcnt(8)
	s_waitcnt lgkmcnt(0)
	s_setprio 1
	s_barrier
	v_mfma_f32_16x16x32_bf16 v[62:65], v[82:85], v[162:165], v[62:65]
	v_mfma_f32_16x16x32_bf16 v[58:61], v[106:109], v[162:165], v[58:61]
	v_mfma_f32_16x16x32_bf16 v[46:49], v[82:85], v[184:187], v[46:49]
	v_mfma_f32_16x16x32_bf16 v[42:45], v[106:109], v[184:187], v[42:45]
	v_mfma_f32_16x16x32_bf16 v[30:33], v[82:85], v[192:195], v[30:33]
	v_mfma_f32_16x16x32_bf16 v[26:29], v[106:109], v[192:195], v[26:29]
	v_mfma_f32_16x16x32_bf16 v[14:17], v[82:85], v[200:203], v[14:17]
	v_mfma_f32_16x16x32_bf16 v[10:13], v[106:109], v[200:203], v[10:13]
	v_mfma_f32_16x16x32_bf16 v[62:65], v[86:89], v[166:169], v[62:65]
	v_mfma_f32_16x16x32_bf16 v[58:61], v[110:113], v[166:169], v[58:61]
	v_mfma_f32_16x16x32_bf16 v[46:49], v[86:89], v[188:191], v[46:49]
	v_mfma_f32_16x16x32_bf16 v[42:45], v[110:113], v[188:191], v[42:45]
	v_mfma_f32_16x16x32_bf16 v[30:33], v[86:89], v[196:199], v[30:33]
	v_mfma_f32_16x16x32_bf16 v[26:29], v[110:113], v[196:199], v[26:29]
	v_mfma_f32_16x16x32_bf16 v[14:17], v[86:89], v[204:207], v[14:17]
	v_mfma_f32_16x16x32_bf16 v[10:13], v[110:113], v[204:207], v[10:13]
	s_setprio 0
	s_setprio 1
	v_mfma_f32_16x16x32_bf16 v[54:57], v[146:149], v[162:165], v[54:57]
	v_mfma_f32_16x16x32_bf16 v[50:53], v[154:157], v[162:165], v[50:53]
	v_mfma_f32_16x16x32_bf16 v[38:41], v[146:149], v[184:187], v[38:41]
	v_mfma_f32_16x16x32_bf16 v[34:37], v[154:157], v[184:187], v[34:37]
	v_mfma_f32_16x16x32_bf16 v[22:25], v[146:149], v[192:195], v[22:25]
	v_mfma_f32_16x16x32_bf16 v[18:21], v[154:157], v[192:195], v[18:21]
	v_mfma_f32_16x16x32_bf16 v[6:9], v[146:149], v[200:203], v[6:9]
	v_mfma_f32_16x16x32_bf16 v[2:5], v[154:157], v[200:203], v[2:5]
	v_mfma_f32_16x16x32_bf16 v[54:57], v[150:153], v[166:169], v[54:57]
	v_mfma_f32_16x16x32_bf16 v[50:53], v[158:161], v[166:169], v[50:53]
	v_mfma_f32_16x16x32_bf16 v[38:41], v[150:153], v[188:191], v[38:41]
	v_mfma_f32_16x16x32_bf16 v[34:37], v[158:161], v[188:191], v[34:37]
	v_mfma_f32_16x16x32_bf16 v[22:25], v[150:153], v[196:199], v[22:25]
	v_mfma_f32_16x16x32_bf16 v[18:21], v[158:161], v[196:199], v[18:21]
	v_mfma_f32_16x16x32_bf16 v[6:9], v[150:153], v[204:207], v[6:9]
	v_mfma_f32_16x16x32_bf16 v[2:5], v[158:161], v[204:207], v[2:5]
	s_barrier
	s_setprio 0
	s_add_i32 s61, s61, 2
	s_add_u32 s15, s15, 0x100
	s_addc_u32 s18, s18, 0
	s_cmpk_gt_u32 s61, 0x55
	s_mov_b64 s[8:9], s[6:7]
	s_cbranch_scc0 .LBB0_1919
	s_and_b64 vcc, exec, s[36:37]
	s_cbranch_vccz .LBB0_1922
	s_barrier

.LBB0_1945:
	ds_read_b128 v[148:151], v143
	ds_read_b128 v[152:155], v143 offset:1024
	ds_read_b128 v[156:159], v143 offset:2048
	ds_read_b128 v[160:163], v143 offset:3072
	ds_read_b128 v[164:167], v144
	ds_read_b128 v[168:171], v144 offset:1024
	ds_read_b128 v[172:175], v144 offset:2048
	ds_read_b128 v[176:179], v144 offset:3072
	s_add_u32 s10, s8, 0x100
	s_addc_u32 s11, s9, 0
	s_cmp_lg_u32 s27, 18
	s_cselect_b32 s12, s10, 0
	s_cselect_b32 s13, s11, 0
	s_add_u32 s14, s4, s12
	s_addc_u32 s15, s5, s13
	s_add_u32 s12, s2, s12
	s_addc_u32 s13, s3, s13
	s_mov_b32 m0, s28
	v_lshl_add_u64 v[212:213], v[140:141], 0, s[8:9]
	ds_read_b128 v[180:183], v145
	ds_read_b128 v[184:187], v145 offset:1024
	ds_read_b128 v[188:191], v145 offset:2048
	ds_read_b128 v[192:195], v145 offset:3072
	ds_read_b128 v[196:199], v145 offset:4096
	ds_read_b128 v[200:203], v145 offset:5120
	ds_read_b128 v[204:207], v145 offset:6144
	ds_read_b128 v[208:211], v145 offset:7168
	global_load_lds_dwordx4 v[212:213], off
	v_lshl_add_u64 v[212:213], v[138:139], 0, s[8:9]
	s_mov_b32 m0, s29
	s_nop 0
	global_load_lds_dwordx4 v[212:213], off
	s_waitcnt vmcnt(8)
	s_waitcnt lgkmcnt(0)
	s_setprio 1
	s_barrier
	v_mfma_f32_16x16x32_bf16 v[126:129], v[148:151], v[180:183], v[126:129]
	v_mfma_f32_16x16x32_bf16 v[122:125], v[156:159], v[180:183], v[122:125]
	v_mfma_f32_16x16x32_bf16 v[118:121], v[148:151], v[188:191], v[118:121]
	v_mfma_f32_16x16x32_bf16 v[114:117], v[156:159], v[188:191], v[114:117]
	v_mfma_f32_16x16x32_bf16 v[106:109], v[148:151], v[196:199], v[106:109]
	v_mfma_f32_16x16x32_bf16 v[98:101], v[156:159], v[196:199], v[98:101]
	v_mfma_f32_16x16x32_bf16 v[90:93], v[148:151], v[204:207], v[90:93]
	v_mfma_f32_16x16x32_bf16 v[82:85], v[156:159], v[204:207], v[82:85]
	v_mfma_f32_16x16x32_bf16 v[126:129], v[152:155], v[184:187], v[126:129]
	v_mfma_f32_16x16x32_bf16 v[122:125], v[160:163], v[184:187], v[122:125]
	v_mfma_f32_16x16x32_bf16 v[118:121], v[152:155], v[192:195], v[118:121]
	v_mfma_f32_16x16x32_bf16 v[114:117], v[160:163], v[192:195], v[114:117]
	v_mfma_f32_16x16x32_bf16 v[106:109], v[152:155], v[200:203], v[106:109]
	v_mfma_f32_16x16x32_bf16 v[98:101], v[160:163], v[200:203], v[98:101]
	v_mfma_f32_16x16x32_bf16 v[90:93], v[152:155], v[208:211], v[90:93]
	v_mfma_f32_16x16x32_bf16 v[82:85], v[160:163], v[208:211], v[82:85]
	s_setprio 0
	s_setprio 1
	v_mfma_f32_16x16x32_bf16 v[110:113], v[164:167], v[180:183], v[110:113]
	v_mfma_f32_16x16x32_bf16 v[102:105], v[172:175], v[180:183], v[102:105]
	v_mfma_f32_16x16x32_bf16 v[94:97], v[164:167], v[188:191], v[94:97]
	v_mfma_f32_16x16x32_bf16 v[86:89], v[172:175], v[188:191], v[86:89]
	v_mfma_f32_16x16x32_bf16 v[78:81], v[164:167], v[196:199], v[78:81]
	v_mfma_f32_16x16x32_bf16 v[74:77], v[172:175], v[196:199], v[74:77]
	v_mfma_f32_16x16x32_bf16 v[70:73], v[164:167], v[204:207], v[70:73]
	v_mfma_f32_16x16x32_bf16 v[66:69], v[172:175], v[204:207], v[66:69]
	v_mfma_f32_16x16x32_bf16 v[110:113], v[168:171], v[184:187], v[110:113]
	v_mfma_f32_16x16x32_bf16 v[102:105], v[176:179], v[184:187], v[102:105]
	v_mfma_f32_16x16x32_bf16 v[94:97], v[168:171], v[192:195], v[94:97]
	v_mfma_f32_16x16x32_bf16 v[86:89], v[176:179], v[192:195], v[86:89]
	v_mfma_f32_16x16x32_bf16 v[78:81], v[168:171], v[200:203], v[78:81]
	v_mfma_f32_16x16x32_bf16 v[74:77], v[176:179], v[200:203], v[74:77]
	v_mfma_f32_16x16x32_bf16 v[70:73], v[168:171], v[208:211], v[70:73]
	v_mfma_f32_16x16x32_bf16 v[66:69], v[176:179], v[208:211], v[66:69]
	s_barrier
	s_setprio 0
	s_mov_b32 m0, s30
	v_lshl_add_u64 v[212:213], s[12:13], 0, v[132:133]
	s_add_u32 s8, s12, 0x160000
	ds_read_b128 v[180:183], v145 offset:16384
	ds_read_b128 v[184:187], v145 offset:17408
	ds_read_b128 v[188:191], v145 offset:18432
	ds_read_b128 v[192:195], v145 offset:19456
	ds_read_b128 v[196:199], v145 offset:20480
	ds_read_b128 v[200:203], v145 offset:21504
	ds_read_b128 v[204:207], v145 offset:22528
	ds_read_b128 v[208:211], v145 offset:23552
	global_load_lds_dwordx4 v[212:213], off
	v_lshl_add_u64 v[214:215], s[12:13], 0, v[136:137]
	s_mov_b32 m0, s31
	s_addc_u32 s9, s13, 0
	global_load_lds_dwordx4 v[214:215], off
	v_lshl_add_u64 v[216:217], s[8:9], 0, v[132:133]
	s_mov_b32 m0, s33
	v_lshl_add_u64 v[218:219], s[14:15], 0, v[134:135]
	global_load_lds_dwordx4 v[216:217], off
	v_lshl_add_u64 v[216:217], s[8:9], 0, v[136:137]
	s_mov_b32 m0, s34
	s_nop 0
	global_load_lds_dwordx4 v[216:217], off
	v_lshl_add_u64 v[216:217], s[14:15], 0, v[130:131]
	s_mov_b32 m0, s19
	s_nop 0
	global_load_lds_dwordx4 v[216:217], off
	s_mov_b32 m0, s20
	s_nop 0
	global_load_lds_dwordx4 v[218:219], off
	s_waitcnt vmcnt(8)
	s_waitcnt lgkmcnt(0)
	s_setprio 1
	s_barrier
	v_mfma_f32_16x16x32_bf16 v[62:65], v[148:151], v[180:183], v[62:65]
	v_mfma_f32_16x16x32_bf16 v[58:61], v[156:159], v[180:183], v[58:61]
	v_mfma_f32_16x16x32_bf16 v[54:57], v[148:151], v[188:191], v[54:57]
	v_mfma_f32_16x16x32_bf16 v[50:53], v[156:159], v[188:191], v[50:53]
	v_mfma_f32_16x16x32_bf16 v[42:45], v[148:151], v[196:199], v[42:45]
	v_mfma_f32_16x16x32_bf16 v[34:37], v[156:159], v[196:199], v[34:37]
	v_mfma_f32_16x16x32_bf16 v[26:29], v[148:151], v[204:207], v[26:29]
	v_mfma_f32_16x16x32_bf16 v[18:21], v[156:159], v[204:207], v[18:21]
	v_mfma_f32_16x16x32_bf16 v[62:65], v[152:155], v[184:187], v[62:65]
	v_mfma_f32_16x16x32_bf16 v[58:61], v[160:163], v[184:187], v[58:61]
	v_mfma_f32_16x16x32_bf16 v[54:57], v[152:155], v[192:195], v[54:57]
	v_mfma_f32_16x16x32_bf16 v[50:53], v[160:163], v[192:195], v[50:53]
	v_mfma_f32_16x16x32_bf16 v[42:45], v[152:155], v[200:203], v[42:45]
	v_mfma_f32_16x16x32_bf16 v[34:37], v[160:163], v[200:203], v[34:37]
	v_mfma_f32_16x16x32_bf16 v[26:29], v[152:155], v[208:211], v[26:29]
	v_mfma_f32_16x16x32_bf16 v[18:21], v[160:163], v[208:211], v[18:21]
	s_setprio 0
	s_setprio 1
	v_mfma_f32_16x16x32_bf16 v[46:49], v[164:167], v[180:183], v[46:49]
	v_mfma_f32_16x16x32_bf16 v[38:41], v[172:175], v[180:183], v[38:41]
	v_mfma_f32_16x16x32_bf16 v[30:33], v[164:167], v[188:191], v[30:33]
	v_mfma_f32_16x16x32_bf16 v[22:25], v[172:175], v[188:191], v[22:25]
	v_mfma_f32_16x16x32_bf16 v[14:17], v[164:167], v[196:199], v[14:17]
	v_mfma_f32_16x16x32_bf16 v[10:13], v[172:175], v[196:199], v[10:13]
	v_mfma_f32_16x16x32_bf16 v[6:9], v[164:167], v[204:207], v[6:9]
	v_mfma_f32_16x16x32_bf16 v[2:5], v[172:175], v[204:207], v[2:5]
	v_mfma_f32_16x16x32_bf16 v[46:49], v[168:171], v[184:187], v[46:49]
	v_mfma_f32_16x16x32_bf16 v[38:41], v[176:179], v[184:187], v[38:41]
	v_mfma_f32_16x16x32_bf16 v[30:33], v[168:171], v[192:195], v[30:33]
	v_mfma_f32_16x16x32_bf16 v[22:25], v[176:179], v[192:195], v[22:25]
	v_mfma_f32_16x16x32_bf16 v[14:17], v[168:171], v[200:203], v[14:17]
	v_mfma_f32_16x16x32_bf16 v[10:13], v[176:179], v[200:203], v[10:13]
	v_mfma_f32_16x16x32_bf16 v[6:9], v[168:171], v[208:211], v[6:9]
	v_mfma_f32_16x16x32_bf16 v[2:5], v[176:179], v[208:211], v[2:5]
	s_barrier
	s_setprio 0
	ds_read_b128 v[148:151], v146
	ds_read_b128 v[152:155], v146 offset:1024
	ds_read_b128 v[156:159], v146 offset:2048
	ds_read_b128 v[160:163], v146 offset:3072
	ds_read_b128 v[164:167], v147
	ds_read_b128 v[168:171], v147 offset:1024
	ds_read_b128 v[172:175], v147 offset:2048
	ds_read_b128 v[176:179], v147 offset:3072
	s_add_u32 s8, s14, 0x160000
	s_addc_u32 s9, s15, 0
	s_mov_b32 m0, s21
	v_lshl_add_u64 v[220:221], s[8:9], 0, v[130:131]
	ds_read_b128 v[180:183], v145 offset:32768
	ds_read_b128 v[184:187], v145 offset:33792
	ds_read_b128 v[188:191], v145 offset:34816
	ds_read_b128 v[192:195], v145 offset:35840
	ds_read_b128 v[196:199], v145 offset:36864
	ds_read_b128 v[200:203], v145 offset:37888
	ds_read_b128 v[204:207], v145 offset:38912
	ds_read_b128 v[208:211], v145 offset:39936
	global_load_lds_dwordx4 v[220:221], off
	v_lshl_add_u64 v[220:221], s[8:9], 0, v[134:135]
	s_mov_b32 m0, s23
	s_nop 0
	global_load_lds_dwordx4 v[220:221], off
	s_waitcnt vmcnt(8)
	s_waitcnt lgkmcnt(0)
	s_setprio 1
	s_barrier
	v_mfma_f32_16x16x32_bf16 v[126:129], v[148:151], v[180:183], v[126:129]
	v_mfma_f32_16x16x32_bf16 v[122:125], v[156:159], v[180:183], v[122:125]
	v_mfma_f32_16x16x32_bf16 v[118:121], v[148:151], v[188:191], v[118:121]
	v_mfma_f32_16x16x32_bf16 v[114:117], v[156:159], v[188:191], v[114:117]
	v_mfma_f32_16x16x32_bf16 v[106:109], v[148:151], v[196:199], v[106:109]
	v_mfma_f32_16x16x32_bf16 v[98:101], v[156:159], v[196:199], v[98:101]
	v_mfma_f32_16x16x32_bf16 v[90:93], v[148:151], v[204:207], v[90:93]
	v_mfma_f32_16x16x32_bf16 v[82:85], v[156:159], v[204:207], v[82:85]
	v_mfma_f32_16x16x32_bf16 v[126:129], v[152:155], v[184:187], v[126:129]
	v_mfma_f32_16x16x32_bf16 v[122:125], v[160:163], v[184:187], v[122:125]
	v_mfma_f32_16x16x32_bf16 v[118:121], v[152:155], v[192:195], v[118:121]
	v_mfma_f32_16x16x32_bf16 v[114:117], v[160:163], v[192:195], v[114:117]
	v_mfma_f32_16x16x32_bf16 v[106:109], v[152:155], v[200:203], v[106:109]
	v_mfma_f32_16x16x32_bf16 v[98:101], v[160:163], v[200:203], v[98:101]
	v_mfma_f32_16x16x32_bf16 v[90:93], v[152:155], v[208:211], v[90:93]
	v_mfma_f32_16x16x32_bf16 v[82:85], v[160:163], v[208:211], v[82:85]
	s_setprio 0
	s_setprio 1
	v_mfma_f32_16x16x32_bf16 v[110:113], v[164:167], v[180:183], v[110:113]
	v_mfma_f32_16x16x32_bf16 v[102:105], v[172:175], v[180:183], v[102:105]
	v_mfma_f32_16x16x32_bf16 v[94:97], v[164:167], v[188:191], v[94:97]
	v_mfma_f32_16x16x32_bf16 v[86:89], v[172:175], v[188:191], v[86:89]
	v_mfma_f32_16x16x32_bf16 v[78:81], v[164:167], v[196:199], v[78:81]
	v_mfma_f32_16x16x32_bf16 v[74:77], v[172:175], v[196:199], v[74:77]
	v_mfma_f32_16x16x32_bf16 v[70:73], v[164:167], v[204:207], v[70:73]
	v_mfma_f32_16x16x32_bf16 v[66:69], v[172:175], v[204:207], v[66:69]
	v_mfma_f32_16x16x32_bf16 v[110:113], v[168:171], v[184:187], v[110:113]
	v_mfma_f32_16x16x32_bf16 v[102:105], v[176:179], v[184:187], v[102:105]
	v_mfma_f32_16x16x32_bf16 v[94:97], v[168:171], v[192:195], v[94:97]
	v_mfma_f32_16x16x32_bf16 v[86:89], v[176:179], v[192:195], v[86:89]
	v_mfma_f32_16x16x32_bf16 v[78:81], v[168:171], v[200:203], v[78:81]
	v_mfma_f32_16x16x32_bf16 v[74:77], v[176:179], v[200:203], v[74:77]
	v_mfma_f32_16x16x32_bf16 v[70:73], v[168:171], v[208:211], v[70:73]
	v_mfma_f32_16x16x32_bf16 v[66:69], v[176:179], v[208:211], v[66:69]
	s_barrier
	s_setprio 0
	s_mov_b32 m0, s35
	v_lshl_add_u64 v[212:213], v[212:213], 0, s[6:7]
	s_add_u32 s8, s12, 0x160080
	ds_read_b128 v[180:183], v145 offset:49152
	ds_read_b128 v[184:187], v145 offset:50176
	ds_read_b128 v[188:191], v145 offset:51200
	ds_read_b128 v[192:195], v145 offset:52224
	ds_read_b128 v[196:199], v145 offset:53248
	ds_read_b128 v[200:203], v145 offset:54272
	ds_read_b128 v[204:207], v145 offset:55296
	ds_read_b128 v[208:211], v145 offset:56320
	global_load_lds_dwordx4 v[212:213], off
	v_lshl_add_u64 v[212:213], v[214:215], 0, s[6:7]
	s_mov_b32 m0, s36
	s_addc_u32 s9, s13, 0
	global_load_lds_dwordx4 v[212:213], off
	v_lshl_add_u64 v[212:213], s[8:9], 0, v[132:133]
	s_mov_b32 m0, s37
	s_nop 0
	global_load_lds_dwordx4 v[212:213], off
	v_lshl_add_u64 v[212:213], s[8:9], 0, v[136:137]
	s_mov_b32 m0, s38
	s_nop 0
	global_load_lds_dwordx4 v[212:213], off
	v_lshl_add_u64 v[212:213], v[216:217], 0, s[6:7]
	s_mov_b32 m0, s25
	s_nop 0
	global_load_lds_dwordx4 v[212:213], off
	v_lshl_add_u64 v[212:213], v[218:219], 0, s[6:7]
	s_mov_b32 m0, s26
	s_nop 0
	global_load_lds_dwordx4 v[212:213], off
	s_waitcnt vmcnt(8)
	s_waitcnt lgkmcnt(0)
	s_setprio 1
	s_barrier
	v_mfma_f32_16x16x32_bf16 v[62:65], v[148:151], v[180:183], v[62:65]
	v_mfma_f32_16x16x32_bf16 v[58:61], v[156:159], v[180:183], v[58:61]
	v_mfma_f32_16x16x32_bf16 v[54:57], v[148:151], v[188:191], v[54:57]
	v_mfma_f32_16x16x32_bf16 v[50:53], v[156:159], v[188:191], v[50:53]
	v_mfma_f32_16x16x32_bf16 v[42:45], v[148:151], v[196:199], v[42:45]
	v_mfma_f32_16x16x32_bf16 v[34:37], v[156:159], v[196:199], v[34:37]
	v_mfma_f32_16x16x32_bf16 v[26:29], v[148:151], v[204:207], v[26:29]
	v_mfma_f32_16x16x32_bf16 v[18:21], v[156:159], v[204:207], v[18:21]
	v_mfma_f32_16x16x32_bf16 v[62:65], v[152:155], v[184:187], v[62:65]
	v_mfma_f32_16x16x32_bf16 v[58:61], v[160:163], v[184:187], v[58:61]
	v_mfma_f32_16x16x32_bf16 v[54:57], v[152:155], v[192:195], v[54:57]
	v_mfma_f32_16x16x32_bf16 v[50:53], v[160:163], v[192:195], v[50:53]
	v_mfma_f32_16x16x32_bf16 v[42:45], v[152:155], v[200:203], v[42:45]
	v_mfma_f32_16x16x32_bf16 v[34:37], v[160:163], v[200:203], v[34:37]
	v_mfma_f32_16x16x32_bf16 v[26:29], v[152:155], v[208:211], v[26:29]
	v_mfma_f32_16x16x32_bf16 v[18:21], v[160:163], v[208:211], v[18:21]
	s_setprio 0
	s_setprio 1
	v_mfma_f32_16x16x32_bf16 v[46:49], v[164:167], v[180:183], v[46:49]
	v_mfma_f32_16x16x32_bf16 v[38:41], v[172:175], v[180:183], v[38:41]
	v_mfma_f32_16x16x32_bf16 v[30:33], v[164:167], v[188:191], v[30:33]
	v_mfma_f32_16x16x32_bf16 v[22:25], v[172:175], v[188:191], v[22:25]
	v_mfma_f32_16x16x32_bf16 v[14:17], v[164:167], v[196:199], v[14:17]
	v_mfma_f32_16x16x32_bf16 v[10:13], v[172:175], v[196:199], v[10:13]
	v_mfma_f32_16x16x32_bf16 v[6:9], v[164:167], v[204:207], v[6:9]
	v_mfma_f32_16x16x32_bf16 v[2:5], v[172:175], v[204:207], v[2:5]
	v_mfma_f32_16x16x32_bf16 v[46:49], v[168:171], v[184:187], v[46:49]
	v_mfma_f32_16x16x32_bf16 v[38:41], v[176:179], v[184:187], v[38:41]
	v_mfma_f32_16x16x32_bf16 v[30:33], v[168:171], v[192:195], v[30:33]
	v_mfma_f32_16x16x32_bf16 v[22:25], v[176:179], v[192:195], v[22:25]
	v_mfma_f32_16x16x32_bf16 v[14:17], v[168:171], v[200:203], v[14:17]
	v_mfma_f32_16x16x32_bf16 v[10:13], v[176:179], v[200:203], v[10:13]
	v_mfma_f32_16x16x32_bf16 v[6:9], v[168:171], v[208:211], v[6:9]
	v_mfma_f32_16x16x32_bf16 v[2:5], v[176:179], v[208:211], v[2:5]
	s_barrier
	s_setprio 0
	s_add_i32 s27, s27, 2
	s_cmp_gt_u32 s27, 19
	s_mov_b64 s[8:9], s[10:11]
	s_cbranch_scc0 .LBB0_1945
	s_cmpk_lt_u32 s18, 0x100
	s_cbranch_scc0 .LBB0_1948
	s_barrier
